# v017
# speedup vs baseline: 1.0580x; 1.0100x over previous
; #define FOR_R _Pragma("unroll") for (int r = 0; r < 4; ++r)
; #define FOR_AI _Pragma("unroll") for (int ai = 0; ai < 2; ++ai)
; #define FOR_BJ _Pragma("unroll") for (int bj = 0; bj < 2; ++bj)
; #define FOR_M4 _Pragma("unroll") for (int m = 0; m < 4; ++m)
; #define FOR_NN _Pragma("unroll") for (int n = 0; n < 2; ++n)
; __device__ void job_merged_g(const P& p, int g, int job, const HALF* GTbuf, HALF* sm) {
;     ...
;     FOR_AI FOR_BJ {
;       FOR_M4 FOR_NN {
;         const int row0 = ai * 128 + wr * 64 + m * 16 + fq * 4, col = bj * 128 + wc * 32 + n * 16 + fr;
;         FOR_R {
;           HALF* sp = sm + (row0 + r) * SST2 + col;
;           *sp = (HALF)(acc[ai][bj][m][n][r] * (float)(*sp));
;         }
;       }
;       __builtin_amdgcn_sched_barrier(0);
;     }
.LBB0_145:
	s_or_b64 exec, exec, s[12:13]
	s_waitcnt lgkmcnt(0)
	s_barrier
	ds_read_u16 v186, v131
	ds_read_u16 v187, v131 offset:32
	ds_read_u16 v188, v131 offset:528
	ds_read_u16 v189, v131 offset:560
	ds_read_u16 v190, v131 offset:1056
	ds_read_u16 v191, v131 offset:1088
	ds_read_u16 v192, v131 offset:1584
	ds_read_u16 v193, v131 offset:1616
	s_waitcnt lgkmcnt(7)
	v_fma_mixlo_f16 v124, v124, v186, 0 op_sel_hi:[0,1,0]
	ds_write_b16 v131, v124
	s_waitcnt lgkmcnt(7)
	v_fma_mixlo_f16 v120, v120, v187, 0 op_sel_hi:[0,1,0]
	ds_write_b16 v131, v120 offset:32
	s_waitcnt lgkmcnt(7)
	v_fma_mixlo_f16 v124, v125, v188, 0 op_sel_hi:[0,1,0]
	ds_write_b16 v131, v124 offset:528
	s_waitcnt lgkmcnt(7)
	v_fma_mixlo_f16 v120, v121, v189, 0 op_sel_hi:[0,1,0]
	ds_write_b16 v131, v120 offset:560
	s_waitcnt lgkmcnt(7)
	v_fma_mixlo_f16 v124, v126, v190, 0 op_sel_hi:[0,1,0]
	ds_write_b16 v131, v124 offset:1056
	s_waitcnt lgkmcnt(7)
	v_fma_mixlo_f16 v120, v122, v191, 0 op_sel_hi:[0,1,0]
	ds_write_b16 v131, v120 offset:1088
	s_waitcnt lgkmcnt(7)
	v_fma_mixlo_f16 v124, v127, v192, 0 op_sel_hi:[0,1,0]
	ds_write_b16 v131, v124 offset:1584
	s_waitcnt lgkmcnt(7)
	v_fma_mixlo_f16 v120, v123, v193, 0 op_sel_hi:[0,1,0]
	ds_write_b16 v131, v120 offset:1616
	ds_read_u16 v186, v131 offset:8448
	ds_read_u16 v187, v131 offset:8976
	ds_read_u16 v188, v131 offset:9504
	ds_read_u16 v189, v131 offset:10032
	ds_read_u16 v190, v131 offset:8480
	ds_read_u16 v191, v131 offset:9008
	ds_read_u16 v192, v131 offset:9536
	ds_read_u16 v193, v131 offset:10064
	s_waitcnt lgkmcnt(7)
	v_fma_mixlo_f16 v116, v116, v186, 0 op_sel_hi:[0,1,0]
	ds_write_b16 v131, v116 offset:8448
	s_waitcnt lgkmcnt(7)
	v_fma_mixlo_f16 v116, v117, v187, 0 op_sel_hi:[0,1,0]
	ds_write_b16 v131, v116 offset:8976
	s_waitcnt lgkmcnt(7)
	v_fma_mixlo_f16 v116, v118, v188, 0 op_sel_hi:[0,1,0]
	ds_write_b16 v131, v116 offset:9504
	s_waitcnt lgkmcnt(7)
	v_fma_mixlo_f16 v116, v119, v189, 0 op_sel_hi:[0,1,0]
	ds_write_b16 v131, v116 offset:10032
	s_waitcnt lgkmcnt(7)
	v_fma_mixlo_f16 v112, v112, v190, 0 op_sel_hi:[0,1,0]
	ds_write_b16 v131, v112 offset:8480
	s_waitcnt lgkmcnt(7)
	v_fma_mixlo_f16 v112, v113, v191, 0 op_sel_hi:[0,1,0]
	ds_write_b16 v131, v112 offset:9008
	s_waitcnt lgkmcnt(7)
	v_fma_mixlo_f16 v112, v114, v192, 0 op_sel_hi:[0,1,0]
	ds_write_b16 v131, v112 offset:9536
	s_waitcnt lgkmcnt(7)
	v_fma_mixlo_f16 v112, v115, v193, 0 op_sel_hi:[0,1,0]
	ds_write_b16 v131, v112 offset:10064
	ds_read_u16 v186, v131 offset:16896
	ds_read_u16 v187, v131 offset:17424
	ds_read_u16 v188, v131 offset:17952
	ds_read_u16 v189, v131 offset:18480
	ds_read_u16 v190, v131 offset:16928
	ds_read_u16 v191, v131 offset:17456
	ds_read_u16 v192, v131 offset:17984
	ds_read_u16 v193, v131 offset:18512
	s_waitcnt lgkmcnt(7)
	v_fma_mixlo_f16 v108, v108, v186, 0 op_sel_hi:[0,1,0]
	ds_write_b16 v131, v108 offset:16896
	s_waitcnt lgkmcnt(7)
	v_fma_mixlo_f16 v108, v109, v187, 0 op_sel_hi:[0,1,0]
	ds_write_b16 v131, v108 offset:17424
	s_waitcnt lgkmcnt(7)
	v_fma_mixlo_f16 v108, v110, v188, 0 op_sel_hi:[0,1,0]
	ds_write_b16 v131, v108 offset:17952
	s_waitcnt lgkmcnt(7)
	v_fma_mixlo_f16 v108, v111, v189, 0 op_sel_hi:[0,1,0]
	ds_write_b16 v131, v108 offset:18480
	s_waitcnt lgkmcnt(7)
	v_fma_mixlo_f16 v104, v104, v190, 0 op_sel_hi:[0,1,0]
	ds_write_b16 v131, v104 offset:16928
	s_waitcnt lgkmcnt(7)
	v_fma_mixlo_f16 v104, v105, v191, 0 op_sel_hi:[0,1,0]
	ds_write_b16 v131, v104 offset:17456
	s_waitcnt lgkmcnt(7)
	v_fma_mixlo_f16 v104, v106, v192, 0 op_sel_hi:[0,1,0]
	ds_write_b16 v131, v104 offset:17984
	s_waitcnt lgkmcnt(7)
	v_fma_mixlo_f16 v104, v107, v193, 0 op_sel_hi:[0,1,0]
	ds_write_b16 v131, v104 offset:18512
	ds_read_u16 v186, v131 offset:25344
	ds_read_u16 v187, v131 offset:25872
	ds_read_u16 v188, v131 offset:26400
	ds_read_u16 v189, v131 offset:26928
	ds_read_u16 v190, v131 offset:25376
	ds_read_u16 v191, v131 offset:25904
	ds_read_u16 v192, v131 offset:26432
	ds_read_u16 v193, v131 offset:26960
	s_waitcnt lgkmcnt(7)
	v_fma_mixlo_f16 v100, v100, v186, 0 op_sel_hi:[0,1,0]
	ds_write_b16 v131, v100 offset:25344
	s_waitcnt lgkmcnt(7)
	v_fma_mixlo_f16 v100, v101, v187, 0 op_sel_hi:[0,1,0]
	ds_write_b16 v131, v100 offset:25872
	s_waitcnt lgkmcnt(7)
	v_fma_mixlo_f16 v100, v102, v188, 0 op_sel_hi:[0,1,0]
	ds_write_b16 v131, v100 offset:26400
	s_waitcnt lgkmcnt(7)
	v_fma_mixlo_f16 v100, v103, v189, 0 op_sel_hi:[0,1,0]
	ds_write_b16 v131, v100 offset:26928
	s_waitcnt lgkmcnt(7)
	v_fma_mixlo_f16 v96, v96, v190, 0 op_sel_hi:[0,1,0]
	ds_write_b16 v131, v96 offset:25376
	s_waitcnt lgkmcnt(7)
	v_fma_mixlo_f16 v96, v97, v191, 0 op_sel_hi:[0,1,0]
	ds_write_b16 v131, v96 offset:25904
	s_waitcnt lgkmcnt(7)
	v_fma_mixlo_f16 v96, v98, v192, 0 op_sel_hi:[0,1,0]
	ds_write_b16 v131, v96 offset:26432
	s_waitcnt lgkmcnt(7)
	v_fma_mixlo_f16 v96, v99, v193, 0 op_sel_hi:[0,1,0]
	ds_write_b16 v131, v96 offset:26960
	ds_read_u16 v186, v131 offset:256
	ds_read_u16 v187, v131 offset:288
	ds_read_u16 v188, v131 offset:784
	ds_read_u16 v189, v131 offset:816
	ds_read_u16 v190, v131 offset:1312
	ds_read_u16 v191, v131 offset:1344
	ds_read_u16 v192, v131 offset:1840
	ds_read_u16 v193, v131 offset:1872
	s_waitcnt lgkmcnt(7)
	v_fma_mixlo_f16 v92, v92, v186, 0 op_sel_hi:[0,1,0]
	ds_write_b16 v131, v92 offset:256
	s_waitcnt lgkmcnt(7)
	v_fma_mixlo_f16 v88, v88, v187, 0 op_sel_hi:[0,1,0]
	ds_write_b16 v131, v88 offset:288
	s_waitcnt lgkmcnt(7)
	v_fma_mixlo_f16 v92, v93, v188, 0 op_sel_hi:[0,1,0]
	ds_write_b16 v131, v92 offset:784
	s_waitcnt lgkmcnt(7)
	v_fma_mixlo_f16 v88, v89, v189, 0 op_sel_hi:[0,1,0]
	ds_write_b16 v131, v88 offset:816
	s_waitcnt lgkmcnt(7)
; #define FOR_R _Pragma("unroll") for (int r = 0; r < 4; ++r)
; #define FOR_AI _Pragma("unroll") for (int ai = 0; ai < 2; ++ai)
; #define FOR_BJ _Pragma("unroll") for (int bj = 0; bj < 2; ++bj)
; #define FOR_M4 _Pragma("unroll") for (int m = 0; m < 4; ++m)
; #define FOR_NN _Pragma("unroll") for (int n = 0; n < 2; ++n)
; __device__ void job_merged_g(const P& p, int g, int job, const HALF* GTbuf, HALF* sm) {
;     ...
;     FOR_AI FOR_BJ {
;       FOR_M4 FOR_NN {
;         const int row0 = ai * 128 + wr * 64 + m * 16 + fq * 4, col = bj * 128 + wc * 32 + n * 16 + fr;
;         FOR_R {
;           HALF* sp = sm + (row0 + r) * SST2 + col;
;           *sp = (HALF)(acc[ai][bj][m][n][r] * (float)(*sp));
;         }
;       }
;       __builtin_amdgcn_sched_barrier(0);
;     }
	v_fma_mixlo_f16 v92, v94, v190, 0 op_sel_hi:[0,1,0]
	ds_write_b16 v131, v92 offset:1312
	s_waitcnt lgkmcnt(7)
	v_fma_mixlo_f16 v88, v90, v191, 0 op_sel_hi:[0,1,0]
	ds_write_b16 v131, v88 offset:1344
	s_waitcnt lgkmcnt(7)
	v_fma_mixlo_f16 v92, v95, v192, 0 op_sel_hi:[0,1,0]
	ds_write_b16 v131, v92 offset:1840
	s_waitcnt lgkmcnt(7)
	v_fma_mixlo_f16 v88, v91, v193, 0 op_sel_hi:[0,1,0]
	ds_write_b16 v131, v88 offset:1872
	ds_read_u16 v186, v131 offset:8704
	ds_read_u16 v187, v131 offset:9232
	ds_read_u16 v188, v131 offset:9760
	ds_read_u16 v189, v131 offset:10288
	ds_read_u16 v190, v131 offset:8736
	ds_read_u16 v191, v131 offset:9264
	ds_read_u16 v192, v131 offset:9792
	ds_read_u16 v193, v131 offset:10320
	s_waitcnt lgkmcnt(7)
	v_fma_mixlo_f16 v84, v84, v186, 0 op_sel_hi:[0,1,0]
	ds_write_b16 v131, v84 offset:8704
	s_waitcnt lgkmcnt(7)
	v_fma_mixlo_f16 v84, v85, v187, 0 op_sel_hi:[0,1,0]
	ds_write_b16 v131, v84 offset:9232
	s_waitcnt lgkmcnt(7)
	v_fma_mixlo_f16 v84, v86, v188, 0 op_sel_hi:[0,1,0]
	ds_write_b16 v131, v84 offset:9760
	s_waitcnt lgkmcnt(7)
	v_fma_mixlo_f16 v84, v87, v189, 0 op_sel_hi:[0,1,0]
	ds_write_b16 v131, v84 offset:10288
	s_waitcnt lgkmcnt(7)
	v_fma_mixlo_f16 v80, v80, v190, 0 op_sel_hi:[0,1,0]
	ds_write_b16 v131, v80 offset:8736
	s_waitcnt lgkmcnt(7)
	v_fma_mixlo_f16 v80, v81, v191, 0 op_sel_hi:[0,1,0]
	ds_write_b16 v131, v80 offset:9264
	s_waitcnt lgkmcnt(7)
	v_fma_mixlo_f16 v80, v82, v192, 0 op_sel_hi:[0,1,0]
	ds_write_b16 v131, v80 offset:9792
	s_waitcnt lgkmcnt(7)
	v_fma_mixlo_f16 v80, v83, v193, 0 op_sel_hi:[0,1,0]
	ds_write_b16 v131, v80 offset:10320
	ds_read_u16 v186, v131 offset:17152
	ds_read_u16 v187, v131 offset:17680
	ds_read_u16 v188, v131 offset:18208
	ds_read_u16 v189, v131 offset:18736
	ds_read_u16 v190, v131 offset:17184
	ds_read_u16 v191, v131 offset:17712
	ds_read_u16 v192, v131 offset:18240
	ds_read_u16 v193, v131 offset:18768
	s_waitcnt lgkmcnt(7)
	v_fma_mixlo_f16 v76, v76, v186, 0 op_sel_hi:[0,1,0]
	ds_write_b16 v131, v76 offset:17152
	s_waitcnt lgkmcnt(7)
	v_fma_mixlo_f16 v76, v77, v187, 0 op_sel_hi:[0,1,0]
	ds_write_b16 v131, v76 offset:17680
	s_waitcnt lgkmcnt(7)
	v_fma_mixlo_f16 v76, v78, v188, 0 op_sel_hi:[0,1,0]
	ds_write_b16 v131, v76 offset:18208
	s_waitcnt lgkmcnt(7)
	v_fma_mixlo_f16 v76, v79, v189, 0 op_sel_hi:[0,1,0]
	ds_write_b16 v131, v76 offset:18736
	s_waitcnt lgkmcnt(7)
	v_fma_mixlo_f16 v72, v72, v190, 0 op_sel_hi:[0,1,0]
	ds_write_b16 v131, v72 offset:17184
	s_waitcnt lgkmcnt(7)
	v_fma_mixlo_f16 v72, v73, v191, 0 op_sel_hi:[0,1,0]
	ds_write_b16 v131, v72 offset:17712
	s_waitcnt lgkmcnt(7)
	v_fma_mixlo_f16 v72, v74, v192, 0 op_sel_hi:[0,1,0]
	ds_write_b16 v131, v72 offset:18240
	s_waitcnt lgkmcnt(7)
	v_fma_mixlo_f16 v72, v75, v193, 0 op_sel_hi:[0,1,0]
	ds_write_b16 v131, v72 offset:18768
	ds_read_u16 v186, v131 offset:25600
	ds_read_u16 v187, v131 offset:26128
	ds_read_u16 v188, v131 offset:26656
	ds_read_u16 v189, v131 offset:27184
	ds_read_u16 v190, v131 offset:25632
	ds_read_u16 v191, v131 offset:26160
	ds_read_u16 v192, v131 offset:26688
	ds_read_u16 v193, v131 offset:27216
	s_waitcnt lgkmcnt(7)
	v_fma_mixlo_f16 v68, v68, v186, 0 op_sel_hi:[0,1,0]
	ds_write_b16 v131, v68 offset:25600
	s_waitcnt lgkmcnt(7)
	v_fma_mixlo_f16 v68, v69, v187, 0 op_sel_hi:[0,1,0]
	ds_write_b16 v131, v68 offset:26128
	s_waitcnt lgkmcnt(7)
	v_fma_mixlo_f16 v68, v70, v188, 0 op_sel_hi:[0,1,0]
	ds_write_b16 v131, v68 offset:26656
	s_waitcnt lgkmcnt(7)
	v_fma_mixlo_f16 v68, v71, v189, 0 op_sel_hi:[0,1,0]
	ds_write_b16 v131, v68 offset:27184
	s_waitcnt lgkmcnt(7)
	v_fma_mixlo_f16 v64, v64, v190, 0 op_sel_hi:[0,1,0]
	ds_write_b16 v131, v64 offset:25632
	s_waitcnt lgkmcnt(7)
	v_fma_mixlo_f16 v64, v65, v191, 0 op_sel_hi:[0,1,0]
	ds_write_b16 v131, v64 offset:26160
	s_waitcnt lgkmcnt(7)
	v_fma_mixlo_f16 v64, v66, v192, 0 op_sel_hi:[0,1,0]
	ds_write_b16 v131, v64 offset:26688
	s_waitcnt lgkmcnt(7)
	v_fma_mixlo_f16 v64, v67, v193, 0 op_sel_hi:[0,1,0]
	ds_write_b16 v131, v64 offset:27216
	ds_read_u16 v186, v132
	ds_read_u16 v187, v132 offset:32
	ds_read_u16 v188, v132 offset:528
	ds_read_u16 v189, v132 offset:560
	ds_read_u16 v190, v132 offset:1056
	ds_read_u16 v191, v132 offset:1088
	ds_read_u16 v192, v132 offset:1584
	ds_read_u16 v193, v132 offset:1616
	s_waitcnt lgkmcnt(7)
	v_fma_mixlo_f16 v60, v60, v186, 0 op_sel_hi:[0,1,0]
	ds_write_b16 v132, v60
	s_waitcnt lgkmcnt(7)
	v_fma_mixlo_f16 v56, v56, v187, 0 op_sel_hi:[0,1,0]
	ds_write_b16 v132, v56 offset:32
	s_waitcnt lgkmcnt(7)
	v_fma_mixlo_f16 v60, v61, v188, 0 op_sel_hi:[0,1,0]
	ds_write_b16 v132, v60 offset:528
	s_waitcnt lgkmcnt(7)
	v_fma_mixlo_f16 v56, v57, v189, 0 op_sel_hi:[0,1,0]
	ds_write_b16 v132, v56 offset:560
	s_waitcnt lgkmcnt(7)
	v_fma_mixlo_f16 v60, v62, v190, 0 op_sel_hi:[0,1,0]
	ds_write_b16 v132, v60 offset:1056
	s_waitcnt lgkmcnt(7)
	v_fma_mixlo_f16 v56, v58, v191, 0 op_sel_hi:[0,1,0]
	ds_write_b16 v132, v56 offset:1088
	s_waitcnt lgkmcnt(7)
	v_fma_mixlo_f16 v60, v63, v192, 0 op_sel_hi:[0,1,0]
	ds_write_b16 v132, v60 offset:1584
	s_waitcnt lgkmcnt(7)
	v_fma_mixlo_f16 v56, v59, v193, 0 op_sel_hi:[0,1,0]
	ds_write_b16 v132, v56 offset:1616
	ds_read_u16 v186, v132 offset:8448
	ds_read_u16 v187, v132 offset:8976
	ds_read_u16 v188, v132 offset:9504
	ds_read_u16 v189, v132 offset:10032
	ds_read_u16 v190, v132 offset:8480
	ds_read_u16 v191, v132 offset:9008
	ds_read_u16 v192, v132 offset:9536
	ds_read_u16 v193, v132 offset:10064
	s_waitcnt lgkmcnt(7)
	v_fma_mixlo_f16 v52, v52, v186, 0 op_sel_hi:[0,1,0]
	ds_write_b16 v132, v52 offset:8448
	s_waitcnt lgkmcnt(7)
	v_fma_mixlo_f16 v52, v53, v187, 0 op_sel_hi:[0,1,0]
	ds_write_b16 v132, v52 offset:8976
	s_waitcnt lgkmcnt(7)
; #define FOR_R _Pragma("unroll") for (int r = 0; r < 4; ++r)
; #define FOR_AI _Pragma("unroll") for (int ai = 0; ai < 2; ++ai)
; #define FOR_BJ _Pragma("unroll") for (int bj = 0; bj < 2; ++bj)
; #define FOR_M4 _Pragma("unroll") for (int m = 0; m < 4; ++m)
; #define FOR_NN _Pragma("unroll") for (int n = 0; n < 2; ++n)
; __device__ void job_merged_g(const P& p, int g, int job, const HALF* GTbuf, HALF* sm) {
;     ...
;     FOR_AI FOR_BJ {
;       FOR_M4 FOR_NN {
;         const int row0 = ai * 128 + wr * 64 + m * 16 + fq * 4, col = bj * 128 + wc * 32 + n * 16 + fr;
;         FOR_R {
;           HALF* sp = sm + (row0 + r) * SST2 + col;
;           *sp = (HALF)(acc[ai][bj][m][n][r] * (float)(*sp));
;         }
;       }
;       __builtin_amdgcn_sched_barrier(0);
;     }
	v_fma_mixlo_f16 v52, v54, v188, 0 op_sel_hi:[0,1,0]
	ds_write_b16 v132, v52 offset:9504
	s_waitcnt lgkmcnt(7)
	v_fma_mixlo_f16 v52, v55, v189, 0 op_sel_hi:[0,1,0]
	ds_write_b16 v132, v52 offset:10032
	s_waitcnt lgkmcnt(7)
	v_fma_mixlo_f16 v48, v48, v190, 0 op_sel_hi:[0,1,0]
	ds_write_b16 v132, v48 offset:8480
	s_waitcnt lgkmcnt(7)
	v_fma_mixlo_f16 v48, v49, v191, 0 op_sel_hi:[0,1,0]
	ds_write_b16 v132, v48 offset:9008
	s_waitcnt lgkmcnt(7)
	v_fma_mixlo_f16 v48, v50, v192, 0 op_sel_hi:[0,1,0]
	ds_write_b16 v132, v48 offset:9536
	s_waitcnt lgkmcnt(7)
	v_fma_mixlo_f16 v48, v51, v193, 0 op_sel_hi:[0,1,0]
	ds_write_b16 v132, v48 offset:10064
	ds_read_u16 v186, v132 offset:16896
	ds_read_u16 v187, v132 offset:17424
	ds_read_u16 v188, v132 offset:17952
	ds_read_u16 v189, v132 offset:18480
	ds_read_u16 v190, v132 offset:16928
	ds_read_u16 v191, v132 offset:17456
	ds_read_u16 v192, v132 offset:17984
	ds_read_u16 v193, v132 offset:18512
	s_waitcnt lgkmcnt(7)
	v_fma_mixlo_f16 v44, v44, v186, 0 op_sel_hi:[0,1,0]
	ds_write_b16 v132, v44 offset:16896
	s_waitcnt lgkmcnt(7)
	v_fma_mixlo_f16 v44, v45, v187, 0 op_sel_hi:[0,1,0]
	ds_write_b16 v132, v44 offset:17424
	s_waitcnt lgkmcnt(7)
	v_fma_mixlo_f16 v44, v46, v188, 0 op_sel_hi:[0,1,0]
	ds_write_b16 v132, v44 offset:17952
	s_waitcnt lgkmcnt(7)
	v_fma_mixlo_f16 v44, v47, v189, 0 op_sel_hi:[0,1,0]
	ds_write_b16 v132, v44 offset:18480
	s_waitcnt lgkmcnt(7)
	v_fma_mixlo_f16 v40, v40, v190, 0 op_sel_hi:[0,1,0]
	ds_write_b16 v132, v40 offset:16928
	s_waitcnt lgkmcnt(7)
	v_fma_mixlo_f16 v40, v41, v191, 0 op_sel_hi:[0,1,0]
	ds_write_b16 v132, v40 offset:17456
	s_waitcnt lgkmcnt(7)
	v_fma_mixlo_f16 v40, v42, v192, 0 op_sel_hi:[0,1,0]
	ds_write_b16 v132, v40 offset:17984
	s_waitcnt lgkmcnt(7)
	v_fma_mixlo_f16 v40, v43, v193, 0 op_sel_hi:[0,1,0]
	ds_write_b16 v132, v40 offset:18512
	ds_read_u16 v186, v132 offset:25344
	ds_read_u16 v187, v132 offset:25872
	ds_read_u16 v188, v132 offset:26400
	ds_read_u16 v189, v132 offset:26928
	ds_read_u16 v190, v132 offset:25376
	ds_read_u16 v191, v132 offset:25904
	ds_read_u16 v192, v132 offset:26432
	ds_read_u16 v193, v132 offset:26960
	s_waitcnt lgkmcnt(7)
	v_fma_mixlo_f16 v36, v36, v186, 0 op_sel_hi:[0,1,0]
	ds_write_b16 v132, v36 offset:25344
	s_waitcnt lgkmcnt(7)
	v_fma_mixlo_f16 v36, v37, v187, 0 op_sel_hi:[0,1,0]
	ds_write_b16 v132, v36 offset:25872
	s_waitcnt lgkmcnt(7)
	v_fma_mixlo_f16 v36, v38, v188, 0 op_sel_hi:[0,1,0]
	ds_write_b16 v132, v36 offset:26400
	s_waitcnt lgkmcnt(7)
	v_fma_mixlo_f16 v36, v39, v189, 0 op_sel_hi:[0,1,0]
	ds_write_b16 v132, v36 offset:26928
	s_waitcnt lgkmcnt(7)
	v_fma_mixlo_f16 v32, v32, v190, 0 op_sel_hi:[0,1,0]
	ds_write_b16 v132, v32 offset:25376
	s_waitcnt lgkmcnt(7)
	v_fma_mixlo_f16 v32, v33, v191, 0 op_sel_hi:[0,1,0]
	ds_write_b16 v132, v32 offset:25904
	s_waitcnt lgkmcnt(7)
	v_fma_mixlo_f16 v32, v34, v192, 0 op_sel_hi:[0,1,0]
	ds_write_b16 v132, v32 offset:26432
	s_waitcnt lgkmcnt(7)
	v_fma_mixlo_f16 v32, v35, v193, 0 op_sel_hi:[0,1,0]
	ds_write_b16 v132, v32 offset:26960
	ds_read_u16 v186, v132 offset:256
	ds_read_u16 v187, v132 offset:288
	ds_read_u16 v188, v132 offset:784
	ds_read_u16 v189, v132 offset:816
	ds_read_u16 v190, v132 offset:1312
	ds_read_u16 v191, v132 offset:1344
	ds_read_u16 v192, v132 offset:1840
	ds_read_u16 v193, v132 offset:1872
	s_waitcnt lgkmcnt(7)
	v_fma_mixlo_f16 v28, v28, v186, 0 op_sel_hi:[0,1,0]
	ds_write_b16 v132, v28 offset:256
	s_waitcnt lgkmcnt(7)
	v_fma_mixlo_f16 v24, v24, v187, 0 op_sel_hi:[0,1,0]
	ds_write_b16 v132, v24 offset:288
	s_waitcnt lgkmcnt(7)
	v_fma_mixlo_f16 v28, v29, v188, 0 op_sel_hi:[0,1,0]
	ds_write_b16 v132, v28 offset:784
	s_waitcnt lgkmcnt(7)
	v_fma_mixlo_f16 v24, v25, v189, 0 op_sel_hi:[0,1,0]
	ds_write_b16 v132, v24 offset:816
	s_waitcnt lgkmcnt(7)
	v_fma_mixlo_f16 v28, v30, v190, 0 op_sel_hi:[0,1,0]
	ds_write_b16 v132, v28 offset:1312
	s_waitcnt lgkmcnt(7)
	v_fma_mixlo_f16 v24, v26, v191, 0 op_sel_hi:[0,1,0]
	ds_write_b16 v132, v24 offset:1344
	s_waitcnt lgkmcnt(7)
	v_fma_mixlo_f16 v28, v31, v192, 0 op_sel_hi:[0,1,0]
	ds_write_b16 v132, v28 offset:1840
	s_waitcnt lgkmcnt(7)
	v_fma_mixlo_f16 v24, v27, v193, 0 op_sel_hi:[0,1,0]
	ds_write_b16 v132, v24 offset:1872
	ds_read_u16 v186, v132 offset:8704
	ds_read_u16 v187, v132 offset:9232
	ds_read_u16 v188, v132 offset:9760
	ds_read_u16 v189, v132 offset:10288
	ds_read_u16 v190, v132 offset:8736
	ds_read_u16 v191, v132 offset:9264
	ds_read_u16 v192, v132 offset:9792
	ds_read_u16 v193, v132 offset:10320
	s_waitcnt lgkmcnt(7)
	v_fma_mixlo_f16 v20, v20, v186, 0 op_sel_hi:[0,1,0]
	ds_write_b16 v132, v20 offset:8704
	s_waitcnt lgkmcnt(7)
	v_fma_mixlo_f16 v20, v21, v187, 0 op_sel_hi:[0,1,0]
	ds_write_b16 v132, v20 offset:9232
	s_waitcnt lgkmcnt(7)
	v_fma_mixlo_f16 v20, v22, v188, 0 op_sel_hi:[0,1,0]
	ds_write_b16 v132, v20 offset:9760
	s_waitcnt lgkmcnt(7)
	v_fma_mixlo_f16 v20, v23, v189, 0 op_sel_hi:[0,1,0]
	ds_write_b16 v132, v20 offset:10288
	s_waitcnt lgkmcnt(7)
	v_fma_mixlo_f16 v16, v16, v190, 0 op_sel_hi:[0,1,0]
	ds_write_b16 v132, v16 offset:8736
	s_waitcnt lgkmcnt(7)
	v_fma_mixlo_f16 v16, v17, v191, 0 op_sel_hi:[0,1,0]
	ds_write_b16 v132, v16 offset:9264
	s_waitcnt lgkmcnt(7)
	v_fma_mixlo_f16 v16, v18, v192, 0 op_sel_hi:[0,1,0]
	ds_write_b16 v132, v16 offset:9792
	s_waitcnt lgkmcnt(7)
	v_fma_mixlo_f16 v16, v19, v193, 0 op_sel_hi:[0,1,0]
	ds_write_b16 v132, v16 offset:10320
	ds_read_u16 v186, v132 offset:17152
	ds_read_u16 v187, v132 offset:17680
	ds_read_u16 v188, v132 offset:18208
	ds_read_u16 v189, v132 offset:18736
	ds_read_u16 v190, v132 offset:17184
	ds_read_u16 v191, v132 offset:17712
	ds_read_u16 v192, v132 offset:18240
	ds_read_u16 v193, v132 offset:18768
	s_waitcnt lgkmcnt(7)
; #define FOR_R _Pragma("unroll") for (int r = 0; r < 4; ++r)
; #define FOR_AI _Pragma("unroll") for (int ai = 0; ai < 2; ++ai)
; #define FOR_BJ _Pragma("unroll") for (int bj = 0; bj < 2; ++bj)
; #define FOR_M4 _Pragma("unroll") for (int m = 0; m < 4; ++m)
; #define FOR_NN _Pragma("unroll") for (int n = 0; n < 2; ++n)
; __device__ void job_merged_g(const P& p, int g, int job, const HALF* GTbuf, HALF* sm) {
;     ...
;     FOR_AI FOR_BJ {
;       FOR_M4 FOR_NN {
;         const int row0 = ai * 128 + wr * 64 + m * 16 + fq * 4, col = bj * 128 + wc * 32 + n * 16 + fr;
;         FOR_R {
;           HALF* sp = sm + (row0 + r) * SST2 + col;
;           *sp = (HALF)(acc[ai][bj][m][n][r] * (float)(*sp));
;         }
;       }
;       __builtin_amdgcn_sched_barrier(0);
;     }
;     __syncthreads();
	v_fma_mixlo_f16 v12, v12, v186, 0 op_sel_hi:[0,1,0]
	ds_write_b16 v132, v12 offset:17152
	s_waitcnt lgkmcnt(7)
	v_fma_mixlo_f16 v12, v13, v187, 0 op_sel_hi:[0,1,0]
	ds_write_b16 v132, v12 offset:17680
	s_waitcnt lgkmcnt(7)
	v_fma_mixlo_f16 v12, v14, v188, 0 op_sel_hi:[0,1,0]
	ds_write_b16 v132, v12 offset:18208
	s_waitcnt lgkmcnt(7)
	v_fma_mixlo_f16 v12, v15, v189, 0 op_sel_hi:[0,1,0]
	ds_write_b16 v132, v12 offset:18736
	s_waitcnt lgkmcnt(7)
	v_fma_mixlo_f16 v8, v8, v190, 0 op_sel_hi:[0,1,0]
	ds_write_b16 v132, v8 offset:17184
	s_waitcnt lgkmcnt(7)
	v_fma_mixlo_f16 v8, v9, v191, 0 op_sel_hi:[0,1,0]
	ds_write_b16 v132, v8 offset:17712
	s_waitcnt lgkmcnt(7)
	v_fma_mixlo_f16 v8, v10, v192, 0 op_sel_hi:[0,1,0]
	ds_write_b16 v132, v8 offset:18240
	s_waitcnt lgkmcnt(7)
	v_fma_mixlo_f16 v8, v11, v193, 0 op_sel_hi:[0,1,0]
	ds_write_b16 v132, v8 offset:18768
	ds_read_u16 v186, v132 offset:25600
	ds_read_u16 v187, v132 offset:26128
	ds_read_u16 v188, v132 offset:26656
	ds_read_u16 v189, v132 offset:27184
	ds_read_u16 v190, v132 offset:25632
	ds_read_u16 v191, v132 offset:26160
	ds_read_u16 v192, v132 offset:26688
	ds_read_u16 v193, v132 offset:27216
	s_waitcnt lgkmcnt(7)
	v_fma_mixlo_f16 v4, v4, v186, 0 op_sel_hi:[0,1,0]
	ds_write_b16 v132, v4 offset:25600
	s_waitcnt lgkmcnt(7)
	v_fma_mixlo_f16 v4, v5, v187, 0 op_sel_hi:[0,1,0]
	ds_write_b16 v132, v4 offset:26128
	s_waitcnt lgkmcnt(7)
	v_fma_mixlo_f16 v4, v6, v188, 0 op_sel_hi:[0,1,0]
	ds_write_b16 v132, v4 offset:26656
	s_waitcnt lgkmcnt(7)
	v_fma_mixlo_f16 v4, v7, v189, 0 op_sel_hi:[0,1,0]
	ds_write_b16 v132, v4 offset:27184
	s_waitcnt lgkmcnt(7)
	v_fma_mixlo_f16 v0, v0, v190, 0 op_sel_hi:[0,1,0]
	ds_write_b16 v132, v0 offset:25632
	s_waitcnt lgkmcnt(7)
	v_fma_mixlo_f16 v0, v1, v191, 0 op_sel_hi:[0,1,0]
	ds_write_b16 v132, v0 offset:26160
	s_waitcnt lgkmcnt(7)
	v_fma_mixlo_f16 v0, v2, v192, 0 op_sel_hi:[0,1,0]
	ds_write_b16 v132, v0 offset:26688
	s_waitcnt lgkmcnt(7)
	v_fma_mixlo_f16 v0, v3, v193, 0 op_sel_hi:[0,1,0]
	ds_write_b16 v132, v0 offset:27216
	s_waitcnt lgkmcnt(0)
	s_barrier
	s_and_saveexec_b64 s[12:13], s[4:5]
	s_cbranch_execz .LBB0_148
; __device__ void job_merged_g(const P& p, int g, int job, const HALF* GTbuf, HALF* sm) {
;     ...
;     for (int id0 = t5_; id0 < 256 * 32; id0 += 4 * 512) {
;       h8 prev[4];
;       if (fam > 0) {
; #pragma unroll
;         for (int k = 0; k < 4; ++k) {
;           const int id = id0 + 512 * k;
;           prev[k] = *(const h8*)(MR + (size_t)(id >> 5) * 1024 + (id & 31) * 8);
;         }
;       }
; #pragma unroll
;       for (int k = 0; k < 4; ++k) {
;         const int id = id0 + 512 * k;
;         const int row = id >> 5, ch = id & 31;
;         h8 v = *(const h8*)(sm + row * SST2 + ch * 8);
;         if (fam > 0) {
; #pragma unroll
;           for (int e = 0; e < 8; ++e) v[e] = (HALF)((float)v[e] + (float)prev[k][e]);
;         }
;         *(h8*)(MR + (size_t)row * 1024 + ch * 8) = v;
;       }
;     }
	v_ashrrev_i32_e32 v64, 5, v130
	v_lshlrev_b32_e32 v65, 4, v130
	v_and_b32_e32 v65, 0x1f0, v65
	v_lshl_add_u32 v152, v64, 11, v65
	v_lshl_add_u64 v[66:67], s[6:7], 0, v[152:153]
	v_mov_b32_e32 v68, v66
	v_mov_b32_e32 v69, v67
	v_mul_u32_u24_e32 v70, 0x210, v64
	v_add_u32_e32 v70, v70, v65
	v_add_u32_e32 v71, 0x10800, v70
	s_mov_b64 s[14:15], 0x8000
	global_load_dwordx4 v[0:3], v[66:67], off
	v_lshl_add_u64 v[66:67], v[66:67], 0, s[14:15]
	global_load_dwordx4 v[4:7], v[66:67], off
	v_lshl_add_u64 v[66:67], v[66:67], 0, s[14:15]
	global_load_dwordx4 v[8:11], v[66:67], off
	v_lshl_add_u64 v[66:67], v[66:67], 0, s[14:15]
	global_load_dwordx4 v[12:15], v[66:67], off
	v_lshl_add_u64 v[66:67], v[66:67], 0, s[14:15]
	global_load_dwordx4 v[16:19], v[66:67], off
	v_lshl_add_u64 v[66:67], v[66:67], 0, s[14:15]
	global_load_dwordx4 v[20:23], v[66:67], off
	v_lshl_add_u64 v[66:67], v[66:67], 0, s[14:15]
	global_load_dwordx4 v[24:27], v[66:67], off
	v_lshl_add_u64 v[66:67], v[66:67], 0, s[14:15]
	global_load_dwordx4 v[28:31], v[66:67], off
	v_lshl_add_u64 v[66:67], v[66:67], 0, s[14:15]
	global_load_dwordx4 v[32:35], v[66:67], off
	v_lshl_add_u64 v[66:67], v[66:67], 0, s[14:15]
	global_load_dwordx4 v[36:39], v[66:67], off
	v_lshl_add_u64 v[66:67], v[66:67], 0, s[14:15]
	global_load_dwordx4 v[40:43], v[66:67], off
	v_lshl_add_u64 v[66:67], v[66:67], 0, s[14:15]
	global_load_dwordx4 v[44:47], v[66:67], off
	v_lshl_add_u64 v[66:67], v[66:67], 0, s[14:15]
	global_load_dwordx4 v[48:51], v[66:67], off
	v_lshl_add_u64 v[66:67], v[66:67], 0, s[14:15]
	global_load_dwordx4 v[52:55], v[66:67], off
	v_lshl_add_u64 v[66:67], v[66:67], 0, s[14:15]
	global_load_dwordx4 v[56:59], v[66:67], off
	v_lshl_add_u64 v[66:67], v[66:67], 0, s[14:15]
	global_load_dwordx4 v[60:63], v[66:67], off
	ds_read_b128 v[72:75], v70
	ds_read_b128 v[76:79], v70 offset:8448
	ds_read_b128 v[80:83], v70 offset:16896
	ds_read_b128 v[84:87], v70 offset:25344
	s_waitcnt vmcnt(15) lgkmcnt(3)
	v_pk_add_f16 v3, v3, v75
	v_pk_add_f16 v2, v2, v74
	v_pk_add_f16 v1, v1, v73
	v_pk_add_f16 v0, v0, v72
	global_store_dwordx4 v[68:69], v[0:3], off
	v_lshl_add_u64 v[68:69], v[68:69], 0, s[14:15]
	s_waitcnt vmcnt(15) lgkmcnt(2)
	v_pk_add_f16 v7, v7, v79
	v_pk_add_f16 v6, v6, v78
	v_pk_add_f16 v5, v5, v77
	v_pk_add_f16 v4, v4, v76
	global_store_dwordx4 v[68:69], v[4:7], off
	v_lshl_add_u64 v[68:69], v[68:69], 0, s[14:15]
	s_waitcnt vmcnt(15) lgkmcnt(1)
	v_pk_add_f16 v11, v11, v83
	v_pk_add_f16 v10, v10, v82
	v_pk_add_f16 v9, v9, v81
	v_pk_add_f16 v8, v8, v80
	global_store_dwordx4 v[68:69], v[8:11], off
	v_lshl_add_u64 v[68:69], v[68:69], 0, s[14:15]
	s_waitcnt vmcnt(15) lgkmcnt(0)
	v_pk_add_f16 v15, v15, v87
	v_pk_add_f16 v14, v14, v86
	v_pk_add_f16 v13, v13, v85
	v_pk_add_f16 v12, v12, v84
	global_store_dwordx4 v[68:69], v[12:15], off
	v_lshl_add_u64 v[68:69], v[68:69], 0, s[14:15]
	ds_read_b128 v[72:75], v70 offset:33792
	ds_read_b128 v[76:79], v70 offset:42240
	ds_read_b128 v[80:83], v70 offset:50688
	ds_read_b128 v[84:87], v70 offset:59136
	s_waitcnt vmcnt(15) lgkmcnt(3)
	v_pk_add_f16 v19, v19, v75
	v_pk_add_f16 v18, v18, v74
	v_pk_add_f16 v17, v17, v73
	v_pk_add_f16 v16, v16, v72
	global_store_dwordx4 v[68:69], v[16:19], off
	v_lshl_add_u64 v[68:69], v[68:69], 0, s[14:15]
	s_waitcnt vmcnt(15) lgkmcnt(2)
	v_pk_add_f16 v23, v23, v79
	v_pk_add_f16 v22, v22, v78
	v_pk_add_f16 v21, v21, v77
	v_pk_add_f16 v20, v20, v76
	global_store_dwordx4 v[68:69], v[20:23], off
	v_lshl_add_u64 v[68:69], v[68:69], 0, s[14:15]
	s_waitcnt vmcnt(15) lgkmcnt(1)
	v_pk_add_f16 v27, v27, v83
	v_pk_add_f16 v26, v26, v82
	v_pk_add_f16 v25, v25, v81
	v_pk_add_f16 v24, v24, v80
	global_store_dwordx4 v[68:69], v[24:27], off
	v_lshl_add_u64 v[68:69], v[68:69], 0, s[14:15]
	s_waitcnt vmcnt(15) lgkmcnt(0)
	v_pk_add_f16 v31, v31, v87
	v_pk_add_f16 v30, v30, v86
	v_pk_add_f16 v29, v29, v85
	v_pk_add_f16 v28, v28, v84
	global_store_dwordx4 v[68:69], v[28:31], off
	v_lshl_add_u64 v[68:69], v[68:69], 0, s[14:15]
	ds_read_b128 v[72:75], v71
	ds_read_b128 v[76:79], v71 offset:8448
	ds_read_b128 v[80:83], v71 offset:16896
	ds_read_b128 v[84:87], v71 offset:25344
	s_waitcnt vmcnt(15) lgkmcnt(3)
	v_pk_add_f16 v35, v35, v75
	v_pk_add_f16 v34, v34, v74
	v_pk_add_f16 v33, v33, v73
	v_pk_add_f16 v32, v32, v72
	global_store_dwordx4 v[68:69], v[32:35], off
	v_lshl_add_u64 v[68:69], v[68:69], 0, s[14:15]
	s_waitcnt vmcnt(15) lgkmcnt(2)
	v_pk_add_f16 v39, v39, v79
	v_pk_add_f16 v38, v38, v78
	v_pk_add_f16 v37, v37, v77
	v_pk_add_f16 v36, v36, v76
	global_store_dwordx4 v[68:69], v[36:39], off
	v_lshl_add_u64 v[68:69], v[68:69], 0, s[14:15]
	s_waitcnt vmcnt(15) lgkmcnt(1)
	v_pk_add_f16 v43, v43, v83
	v_pk_add_f16 v42, v42, v82
	v_pk_add_f16 v41, v41, v81
	v_pk_add_f16 v40, v40, v80
	global_store_dwordx4 v[68:69], v[40:43], off
	v_lshl_add_u64 v[68:69], v[68:69], 0, s[14:15]
	s_waitcnt vmcnt(15) lgkmcnt(0)
	v_pk_add_f16 v47, v47, v87
	v_pk_add_f16 v46, v46, v86
	v_pk_add_f16 v45, v45, v85
	v_pk_add_f16 v44, v44, v84
	global_store_dwordx4 v[68:69], v[44:47], off
	v_lshl_add_u64 v[68:69], v[68:69], 0, s[14:15]
	ds_read_b128 v[72:75], v71 offset:33792
	ds_read_b128 v[76:79], v71 offset:42240
	ds_read_b128 v[80:83], v71 offset:50688
	ds_read_b128 v[84:87], v71 offset:59136
	s_waitcnt vmcnt(15) lgkmcnt(3)
	v_pk_add_f16 v51, v51, v75
	v_pk_add_f16 v50, v50, v74
	v_pk_add_f16 v49, v49, v73
	v_pk_add_f16 v48, v48, v72
	global_store_dwordx4 v[68:69], v[48:51], off
	v_lshl_add_u64 v[68:69], v[68:69], 0, s[14:15]
	s_waitcnt vmcnt(15) lgkmcnt(2)
	v_pk_add_f16 v55, v55, v79
	v_pk_add_f16 v54, v54, v78
	v_pk_add_f16 v53, v53, v77
	v_pk_add_f16 v52, v52, v76
	global_store_dwordx4 v[68:69], v[52:55], off
	v_lshl_add_u64 v[68:69], v[68:69], 0, s[14:15]
	s_waitcnt vmcnt(15) lgkmcnt(1)
	v_pk_add_f16 v59, v59, v83
	v_pk_add_f16 v58, v58, v82
	v_pk_add_f16 v57, v57, v81
	v_pk_add_f16 v56, v56, v80
	global_store_dwordx4 v[68:69], v[56:59], off
	v_lshl_add_u64 v[68:69], v[68:69], 0, s[14:15]
	s_waitcnt vmcnt(15) lgkmcnt(0)
	v_pk_add_f16 v63, v63, v87
	v_pk_add_f16 v62, v62, v86
	v_pk_add_f16 v61, v61, v85
	v_pk_add_f16 v60, v60, v84
	global_store_dwordx4 v[68:69], v[60:63], off

; #define FOR_R _Pragma("unroll") for (int r = 0; r < 4; ++r)
; #define FOR_AI _Pragma("unroll") for (int ai = 0; ai < 2; ++ai)
; #define FOR_BJ _Pragma("unroll") for (int bj = 0; bj < 2; ++bj)
; #define FOR_M4 _Pragma("unroll") for (int m = 0; m < 4; ++m)
; #define FOR_NN _Pragma("unroll") for (int n = 0; n < 2; ++n)
; __device__ void job_merged_g(const P& p, int g, int job, const HALF* GTbuf, HALF* sm) {
;     ...
;     FOR_AI FOR_BJ {
;       FOR_M4 FOR_NN {
;         const int row0 = ai * 128 + wr * 64 + m * 16 + fq * 4, col = bj * 128 + wc * 32 + n * 16 + fr;
;         FOR_R {
;           HALF* sp = sm + (row0 + r) * SST2 + col;
;           *sp = (HALF)(acc[ai][bj][m][n][r] * (float)(*sp));
;         }
;       }
;       __builtin_amdgcn_sched_barrier(0);
;     }
.LBB0_157:
	s_or_b64 exec, exec, s[0:1]
	s_waitcnt lgkmcnt(0)
	s_barrier
	ds_read_u16 v186, v131
	ds_read_u16 v187, v131 offset:32
	ds_read_u16 v188, v131 offset:528
	ds_read_u16 v189, v131 offset:560
	ds_read_u16 v190, v131 offset:1056
	ds_read_u16 v191, v131 offset:1088
	ds_read_u16 v192, v131 offset:1584
	ds_read_u16 v193, v131 offset:1616
	s_waitcnt lgkmcnt(7)
	v_fma_mixlo_f16 v124, v124, v186, 0 op_sel_hi:[0,1,0]
	ds_write_b16 v131, v124
	s_waitcnt lgkmcnt(7)
	v_fma_mixlo_f16 v120, v120, v187, 0 op_sel_hi:[0,1,0]
	ds_write_b16 v131, v120 offset:32
	s_waitcnt lgkmcnt(7)
	v_fma_mixlo_f16 v124, v125, v188, 0 op_sel_hi:[0,1,0]
	ds_write_b16 v131, v124 offset:528
	s_waitcnt lgkmcnt(7)
	v_fma_mixlo_f16 v120, v121, v189, 0 op_sel_hi:[0,1,0]
	ds_write_b16 v131, v120 offset:560
	s_waitcnt lgkmcnt(7)
	v_fma_mixlo_f16 v124, v126, v190, 0 op_sel_hi:[0,1,0]
	ds_write_b16 v131, v124 offset:1056
	s_waitcnt lgkmcnt(7)
	v_fma_mixlo_f16 v120, v122, v191, 0 op_sel_hi:[0,1,0]
	ds_write_b16 v131, v120 offset:1088
	s_waitcnt lgkmcnt(7)
	v_fma_mixlo_f16 v124, v127, v192, 0 op_sel_hi:[0,1,0]
	ds_write_b16 v131, v124 offset:1584
	s_waitcnt lgkmcnt(7)
	v_fma_mixlo_f16 v120, v123, v193, 0 op_sel_hi:[0,1,0]
	ds_write_b16 v131, v120 offset:1616
	ds_read_u16 v186, v131 offset:8448
	ds_read_u16 v187, v131 offset:8976
	ds_read_u16 v188, v131 offset:9504
	ds_read_u16 v189, v131 offset:10032
	ds_read_u16 v190, v131 offset:8480
	ds_read_u16 v191, v131 offset:9008
	ds_read_u16 v192, v131 offset:9536
	ds_read_u16 v193, v131 offset:10064
	s_waitcnt lgkmcnt(7)
	v_fma_mixlo_f16 v116, v116, v186, 0 op_sel_hi:[0,1,0]
	ds_write_b16 v131, v116 offset:8448
	s_waitcnt lgkmcnt(7)
	v_fma_mixlo_f16 v116, v117, v187, 0 op_sel_hi:[0,1,0]
	ds_write_b16 v131, v116 offset:8976
	s_waitcnt lgkmcnt(7)
	v_fma_mixlo_f16 v116, v118, v188, 0 op_sel_hi:[0,1,0]
	ds_write_b16 v131, v116 offset:9504
	s_waitcnt lgkmcnt(7)
	v_fma_mixlo_f16 v116, v119, v189, 0 op_sel_hi:[0,1,0]
	ds_write_b16 v131, v116 offset:10032
	s_waitcnt lgkmcnt(7)
	v_fma_mixlo_f16 v112, v112, v190, 0 op_sel_hi:[0,1,0]
	ds_write_b16 v131, v112 offset:8480
	s_waitcnt lgkmcnt(7)
	v_fma_mixlo_f16 v112, v113, v191, 0 op_sel_hi:[0,1,0]
	ds_write_b16 v131, v112 offset:9008
	s_waitcnt lgkmcnt(7)
	v_fma_mixlo_f16 v112, v114, v192, 0 op_sel_hi:[0,1,0]
	ds_write_b16 v131, v112 offset:9536
	s_waitcnt lgkmcnt(7)
	v_fma_mixlo_f16 v112, v115, v193, 0 op_sel_hi:[0,1,0]
	ds_write_b16 v131, v112 offset:10064
	ds_read_u16 v186, v131 offset:16896
	ds_read_u16 v187, v131 offset:17424
	ds_read_u16 v188, v131 offset:17952
	ds_read_u16 v189, v131 offset:18480
	ds_read_u16 v190, v131 offset:16928
	ds_read_u16 v191, v131 offset:17456
	ds_read_u16 v192, v131 offset:17984
	ds_read_u16 v193, v131 offset:18512
	s_waitcnt lgkmcnt(7)
	v_fma_mixlo_f16 v108, v108, v186, 0 op_sel_hi:[0,1,0]
	ds_write_b16 v131, v108 offset:16896
	s_waitcnt lgkmcnt(7)
	v_fma_mixlo_f16 v108, v109, v187, 0 op_sel_hi:[0,1,0]
	ds_write_b16 v131, v108 offset:17424
	s_waitcnt lgkmcnt(7)
	v_fma_mixlo_f16 v108, v110, v188, 0 op_sel_hi:[0,1,0]
	ds_write_b16 v131, v108 offset:17952
	s_waitcnt lgkmcnt(7)
	v_fma_mixlo_f16 v108, v111, v189, 0 op_sel_hi:[0,1,0]
	ds_write_b16 v131, v108 offset:18480
	s_waitcnt lgkmcnt(7)
	v_fma_mixlo_f16 v104, v104, v190, 0 op_sel_hi:[0,1,0]
	ds_write_b16 v131, v104 offset:16928
	s_waitcnt lgkmcnt(7)
	v_fma_mixlo_f16 v104, v105, v191, 0 op_sel_hi:[0,1,0]
	ds_write_b16 v131, v104 offset:17456
	s_waitcnt lgkmcnt(7)
	v_fma_mixlo_f16 v104, v106, v192, 0 op_sel_hi:[0,1,0]
	ds_write_b16 v131, v104 offset:17984
	s_waitcnt lgkmcnt(7)
	v_fma_mixlo_f16 v104, v107, v193, 0 op_sel_hi:[0,1,0]
	ds_write_b16 v131, v104 offset:18512
	ds_read_u16 v186, v131 offset:25344
	ds_read_u16 v187, v131 offset:25872
	ds_read_u16 v188, v131 offset:26400
	ds_read_u16 v189, v131 offset:26928
	ds_read_u16 v190, v131 offset:25376
	ds_read_u16 v191, v131 offset:25904
	ds_read_u16 v192, v131 offset:26432
	ds_read_u16 v193, v131 offset:26960
	s_waitcnt lgkmcnt(7)
	v_fma_mixlo_f16 v100, v100, v186, 0 op_sel_hi:[0,1,0]
	ds_write_b16 v131, v100 offset:25344
	s_waitcnt lgkmcnt(7)
	v_fma_mixlo_f16 v100, v101, v187, 0 op_sel_hi:[0,1,0]
	ds_write_b16 v131, v100 offset:25872
	s_waitcnt lgkmcnt(7)
	v_fma_mixlo_f16 v100, v102, v188, 0 op_sel_hi:[0,1,0]
	ds_write_b16 v131, v100 offset:26400
	s_waitcnt lgkmcnt(7)
	v_fma_mixlo_f16 v100, v103, v189, 0 op_sel_hi:[0,1,0]
	ds_write_b16 v131, v100 offset:26928
	s_waitcnt lgkmcnt(7)
	v_fma_mixlo_f16 v96, v96, v190, 0 op_sel_hi:[0,1,0]
	ds_write_b16 v131, v96 offset:25376
	s_waitcnt lgkmcnt(7)
	v_fma_mixlo_f16 v96, v97, v191, 0 op_sel_hi:[0,1,0]
	ds_write_b16 v131, v96 offset:25904
	s_waitcnt lgkmcnt(7)
	v_fma_mixlo_f16 v96, v98, v192, 0 op_sel_hi:[0,1,0]
	ds_write_b16 v131, v96 offset:26432
	s_waitcnt lgkmcnt(7)
	v_fma_mixlo_f16 v96, v99, v193, 0 op_sel_hi:[0,1,0]
	ds_write_b16 v131, v96 offset:26960
	ds_read_u16 v186, v131 offset:256
	ds_read_u16 v187, v131 offset:288
	ds_read_u16 v188, v131 offset:784
	ds_read_u16 v189, v131 offset:816
	ds_read_u16 v190, v131 offset:1312
	ds_read_u16 v191, v131 offset:1344
	ds_read_u16 v192, v131 offset:1840
	ds_read_u16 v193, v131 offset:1872
	s_waitcnt lgkmcnt(7)
	v_fma_mixlo_f16 v92, v92, v186, 0 op_sel_hi:[0,1,0]
	ds_write_b16 v131, v92 offset:256
	s_waitcnt lgkmcnt(7)
	v_fma_mixlo_f16 v88, v88, v187, 0 op_sel_hi:[0,1,0]
	ds_write_b16 v131, v88 offset:288
	s_waitcnt lgkmcnt(7)
	v_fma_mixlo_f16 v92, v93, v188, 0 op_sel_hi:[0,1,0]
	ds_write_b16 v131, v92 offset:784
	s_waitcnt lgkmcnt(7)
	v_fma_mixlo_f16 v88, v89, v189, 0 op_sel_hi:[0,1,0]
	ds_write_b16 v131, v88 offset:816
	s_waitcnt lgkmcnt(7)
; #define FOR_R _Pragma("unroll") for (int r = 0; r < 4; ++r)
; #define FOR_AI _Pragma("unroll") for (int ai = 0; ai < 2; ++ai)
; #define FOR_BJ _Pragma("unroll") for (int bj = 0; bj < 2; ++bj)
; #define FOR_M4 _Pragma("unroll") for (int m = 0; m < 4; ++m)
; #define FOR_NN _Pragma("unroll") for (int n = 0; n < 2; ++n)
; __device__ void job_merged_g(const P& p, int g, int job, const HALF* GTbuf, HALF* sm) {
;     ...
;     FOR_AI FOR_BJ {
;       FOR_M4 FOR_NN {
;         const int row0 = ai * 128 + wr * 64 + m * 16 + fq * 4, col = bj * 128 + wc * 32 + n * 16 + fr;
;         FOR_R {
;           HALF* sp = sm + (row0 + r) * SST2 + col;
;           *sp = (HALF)(acc[ai][bj][m][n][r] * (float)(*sp));
;         }
;       }
;       __builtin_amdgcn_sched_barrier(0);
;     }
	v_fma_mixlo_f16 v92, v94, v190, 0 op_sel_hi:[0,1,0]
	ds_write_b16 v131, v92 offset:1312
	s_waitcnt lgkmcnt(7)
	v_fma_mixlo_f16 v88, v90, v191, 0 op_sel_hi:[0,1,0]
	ds_write_b16 v131, v88 offset:1344
	s_waitcnt lgkmcnt(7)
	v_fma_mixlo_f16 v92, v95, v192, 0 op_sel_hi:[0,1,0]
	ds_write_b16 v131, v92 offset:1840
	s_waitcnt lgkmcnt(7)
	v_fma_mixlo_f16 v88, v91, v193, 0 op_sel_hi:[0,1,0]
	ds_write_b16 v131, v88 offset:1872
	ds_read_u16 v186, v131 offset:8704
	ds_read_u16 v187, v131 offset:9232
	ds_read_u16 v188, v131 offset:9760
	ds_read_u16 v189, v131 offset:10288
	ds_read_u16 v190, v131 offset:8736
	ds_read_u16 v191, v131 offset:9264
	ds_read_u16 v192, v131 offset:9792
	ds_read_u16 v193, v131 offset:10320
	s_waitcnt lgkmcnt(7)
	v_fma_mixlo_f16 v84, v84, v186, 0 op_sel_hi:[0,1,0]
	ds_write_b16 v131, v84 offset:8704
	s_waitcnt lgkmcnt(7)
	v_fma_mixlo_f16 v84, v85, v187, 0 op_sel_hi:[0,1,0]
	ds_write_b16 v131, v84 offset:9232
	s_waitcnt lgkmcnt(7)
	v_fma_mixlo_f16 v84, v86, v188, 0 op_sel_hi:[0,1,0]
	ds_write_b16 v131, v84 offset:9760
	s_waitcnt lgkmcnt(7)
	v_fma_mixlo_f16 v84, v87, v189, 0 op_sel_hi:[0,1,0]
	ds_write_b16 v131, v84 offset:10288
	s_waitcnt lgkmcnt(7)
	v_fma_mixlo_f16 v80, v80, v190, 0 op_sel_hi:[0,1,0]
	ds_write_b16 v131, v80 offset:8736
	s_waitcnt lgkmcnt(7)
	v_fma_mixlo_f16 v80, v81, v191, 0 op_sel_hi:[0,1,0]
	ds_write_b16 v131, v80 offset:9264
	s_waitcnt lgkmcnt(7)
	v_fma_mixlo_f16 v80, v82, v192, 0 op_sel_hi:[0,1,0]
	ds_write_b16 v131, v80 offset:9792
	s_waitcnt lgkmcnt(7)
	v_fma_mixlo_f16 v80, v83, v193, 0 op_sel_hi:[0,1,0]
	ds_write_b16 v131, v80 offset:10320
	ds_read_u16 v186, v131 offset:17152
	ds_read_u16 v187, v131 offset:17680
	ds_read_u16 v188, v131 offset:18208
	ds_read_u16 v189, v131 offset:18736
	ds_read_u16 v190, v131 offset:17184
	ds_read_u16 v191, v131 offset:17712
	ds_read_u16 v192, v131 offset:18240
	ds_read_u16 v193, v131 offset:18768
	s_waitcnt lgkmcnt(7)
	v_fma_mixlo_f16 v76, v76, v186, 0 op_sel_hi:[0,1,0]
	ds_write_b16 v131, v76 offset:17152
	s_waitcnt lgkmcnt(7)
	v_fma_mixlo_f16 v76, v77, v187, 0 op_sel_hi:[0,1,0]
	ds_write_b16 v131, v76 offset:17680
	s_waitcnt lgkmcnt(7)
	v_fma_mixlo_f16 v76, v78, v188, 0 op_sel_hi:[0,1,0]
	ds_write_b16 v131, v76 offset:18208
	s_waitcnt lgkmcnt(7)
	v_fma_mixlo_f16 v76, v79, v189, 0 op_sel_hi:[0,1,0]
	ds_write_b16 v131, v76 offset:18736
	s_waitcnt lgkmcnt(7)
	v_fma_mixlo_f16 v72, v72, v190, 0 op_sel_hi:[0,1,0]
	ds_write_b16 v131, v72 offset:17184
	s_waitcnt lgkmcnt(7)
	v_fma_mixlo_f16 v72, v73, v191, 0 op_sel_hi:[0,1,0]
	ds_write_b16 v131, v72 offset:17712
	s_waitcnt lgkmcnt(7)
	v_fma_mixlo_f16 v72, v74, v192, 0 op_sel_hi:[0,1,0]
	ds_write_b16 v131, v72 offset:18240
	s_waitcnt lgkmcnt(7)
	v_fma_mixlo_f16 v72, v75, v193, 0 op_sel_hi:[0,1,0]
	ds_write_b16 v131, v72 offset:18768
	ds_read_u16 v186, v131 offset:25600
	ds_read_u16 v187, v131 offset:26128
	ds_read_u16 v188, v131 offset:26656
	ds_read_u16 v189, v131 offset:27184
	ds_read_u16 v190, v131 offset:25632
	ds_read_u16 v191, v131 offset:26160
	ds_read_u16 v192, v131 offset:26688
	ds_read_u16 v193, v131 offset:27216
	s_waitcnt lgkmcnt(7)
	v_fma_mixlo_f16 v68, v68, v186, 0 op_sel_hi:[0,1,0]
	ds_write_b16 v131, v68 offset:25600
	s_waitcnt lgkmcnt(7)
	v_fma_mixlo_f16 v68, v69, v187, 0 op_sel_hi:[0,1,0]
	ds_write_b16 v131, v68 offset:26128
	s_waitcnt lgkmcnt(7)
	v_fma_mixlo_f16 v68, v70, v188, 0 op_sel_hi:[0,1,0]
	ds_write_b16 v131, v68 offset:26656
	s_waitcnt lgkmcnt(7)
	v_fma_mixlo_f16 v68, v71, v189, 0 op_sel_hi:[0,1,0]
	ds_write_b16 v131, v68 offset:27184
	s_waitcnt lgkmcnt(7)
	v_fma_mixlo_f16 v64, v64, v190, 0 op_sel_hi:[0,1,0]
	ds_write_b16 v131, v64 offset:25632
	s_waitcnt lgkmcnt(7)
	v_fma_mixlo_f16 v64, v65, v191, 0 op_sel_hi:[0,1,0]
	ds_write_b16 v131, v64 offset:26160
	s_waitcnt lgkmcnt(7)
	v_fma_mixlo_f16 v64, v66, v192, 0 op_sel_hi:[0,1,0]
	ds_write_b16 v131, v64 offset:26688
	s_waitcnt lgkmcnt(7)
	v_fma_mixlo_f16 v64, v67, v193, 0 op_sel_hi:[0,1,0]
	ds_write_b16 v131, v64 offset:27216
	ds_read_u16 v186, v132
	ds_read_u16 v187, v132 offset:32
	ds_read_u16 v188, v132 offset:528
	ds_read_u16 v189, v132 offset:560
	ds_read_u16 v190, v132 offset:1056
	ds_read_u16 v191, v132 offset:1088
	ds_read_u16 v192, v132 offset:1584
	ds_read_u16 v193, v132 offset:1616
	s_waitcnt lgkmcnt(7)
	v_fma_mixlo_f16 v60, v60, v186, 0 op_sel_hi:[0,1,0]
	ds_write_b16 v132, v60
	s_waitcnt lgkmcnt(7)
	v_fma_mixlo_f16 v56, v56, v187, 0 op_sel_hi:[0,1,0]
	ds_write_b16 v132, v56 offset:32
	s_waitcnt lgkmcnt(7)
	v_fma_mixlo_f16 v60, v61, v188, 0 op_sel_hi:[0,1,0]
	ds_write_b16 v132, v60 offset:528
	s_waitcnt lgkmcnt(7)
	v_fma_mixlo_f16 v56, v57, v189, 0 op_sel_hi:[0,1,0]
	ds_write_b16 v132, v56 offset:560
	s_waitcnt lgkmcnt(7)
	v_fma_mixlo_f16 v60, v62, v190, 0 op_sel_hi:[0,1,0]
	ds_write_b16 v132, v60 offset:1056
	s_waitcnt lgkmcnt(7)
	v_fma_mixlo_f16 v56, v58, v191, 0 op_sel_hi:[0,1,0]
	ds_write_b16 v132, v56 offset:1088
	s_waitcnt lgkmcnt(7)
	v_fma_mixlo_f16 v60, v63, v192, 0 op_sel_hi:[0,1,0]
	ds_write_b16 v132, v60 offset:1584
	s_waitcnt lgkmcnt(7)
	v_fma_mixlo_f16 v56, v59, v193, 0 op_sel_hi:[0,1,0]
	ds_write_b16 v132, v56 offset:1616
	ds_read_u16 v186, v132 offset:8448
	ds_read_u16 v187, v132 offset:8976
	ds_read_u16 v188, v132 offset:9504
	ds_read_u16 v189, v132 offset:10032
	ds_read_u16 v190, v132 offset:8480
	ds_read_u16 v191, v132 offset:9008
	ds_read_u16 v192, v132 offset:9536
	ds_read_u16 v193, v132 offset:10064
	s_waitcnt lgkmcnt(7)
	v_fma_mixlo_f16 v52, v52, v186, 0 op_sel_hi:[0,1,0]
	ds_write_b16 v132, v52 offset:8448
	s_waitcnt lgkmcnt(7)
	v_fma_mixlo_f16 v52, v53, v187, 0 op_sel_hi:[0,1,0]
	ds_write_b16 v132, v52 offset:8976
	s_waitcnt lgkmcnt(7)
; #define FOR_R _Pragma("unroll") for (int r = 0; r < 4; ++r)
; #define FOR_AI _Pragma("unroll") for (int ai = 0; ai < 2; ++ai)
; #define FOR_BJ _Pragma("unroll") for (int bj = 0; bj < 2; ++bj)
; #define FOR_M4 _Pragma("unroll") for (int m = 0; m < 4; ++m)
; #define FOR_NN _Pragma("unroll") for (int n = 0; n < 2; ++n)
; __device__ void job_merged_g(const P& p, int g, int job, const HALF* GTbuf, HALF* sm) {
;     ...
;     FOR_AI FOR_BJ {
;       FOR_M4 FOR_NN {
;         const int row0 = ai * 128 + wr * 64 + m * 16 + fq * 4, col = bj * 128 + wc * 32 + n * 16 + fr;
;         FOR_R {
;           HALF* sp = sm + (row0 + r) * SST2 + col;
;           *sp = (HALF)(acc[ai][bj][m][n][r] * (float)(*sp));
;         }
;       }
;       __builtin_amdgcn_sched_barrier(0);
;     }
	v_fma_mixlo_f16 v52, v54, v188, 0 op_sel_hi:[0,1,0]
	ds_write_b16 v132, v52 offset:9504
	s_waitcnt lgkmcnt(7)
	v_fma_mixlo_f16 v52, v55, v189, 0 op_sel_hi:[0,1,0]
	ds_write_b16 v132, v52 offset:10032
	s_waitcnt lgkmcnt(7)
	v_fma_mixlo_f16 v48, v48, v190, 0 op_sel_hi:[0,1,0]
	ds_write_b16 v132, v48 offset:8480
	s_waitcnt lgkmcnt(7)
	v_fma_mixlo_f16 v48, v49, v191, 0 op_sel_hi:[0,1,0]
	ds_write_b16 v132, v48 offset:9008
	s_waitcnt lgkmcnt(7)
	v_fma_mixlo_f16 v48, v50, v192, 0 op_sel_hi:[0,1,0]
	ds_write_b16 v132, v48 offset:9536
	s_waitcnt lgkmcnt(7)
	v_fma_mixlo_f16 v48, v51, v193, 0 op_sel_hi:[0,1,0]
	ds_write_b16 v132, v48 offset:10064
	ds_read_u16 v186, v132 offset:16896
	ds_read_u16 v187, v132 offset:17424
	ds_read_u16 v188, v132 offset:17952
	ds_read_u16 v189, v132 offset:18480
	ds_read_u16 v190, v132 offset:16928
	ds_read_u16 v191, v132 offset:17456
	ds_read_u16 v192, v132 offset:17984
	ds_read_u16 v193, v132 offset:18512
	s_waitcnt lgkmcnt(7)
	v_fma_mixlo_f16 v44, v44, v186, 0 op_sel_hi:[0,1,0]
	ds_write_b16 v132, v44 offset:16896
	s_waitcnt lgkmcnt(7)
	v_fma_mixlo_f16 v44, v45, v187, 0 op_sel_hi:[0,1,0]
	ds_write_b16 v132, v44 offset:17424
	s_waitcnt lgkmcnt(7)
	v_fma_mixlo_f16 v44, v46, v188, 0 op_sel_hi:[0,1,0]
	ds_write_b16 v132, v44 offset:17952
	s_waitcnt lgkmcnt(7)
	v_fma_mixlo_f16 v44, v47, v189, 0 op_sel_hi:[0,1,0]
	ds_write_b16 v132, v44 offset:18480
	s_waitcnt lgkmcnt(7)
	v_fma_mixlo_f16 v40, v40, v190, 0 op_sel_hi:[0,1,0]
	ds_write_b16 v132, v40 offset:16928
	s_waitcnt lgkmcnt(7)
	v_fma_mixlo_f16 v40, v41, v191, 0 op_sel_hi:[0,1,0]
	ds_write_b16 v132, v40 offset:17456
	s_waitcnt lgkmcnt(7)
	v_fma_mixlo_f16 v40, v42, v192, 0 op_sel_hi:[0,1,0]
	ds_write_b16 v132, v40 offset:17984
	s_waitcnt lgkmcnt(7)
	v_fma_mixlo_f16 v40, v43, v193, 0 op_sel_hi:[0,1,0]
	ds_write_b16 v132, v40 offset:18512
	ds_read_u16 v186, v132 offset:25344
	ds_read_u16 v187, v132 offset:25872
	ds_read_u16 v188, v132 offset:26400
	ds_read_u16 v189, v132 offset:26928
	ds_read_u16 v190, v132 offset:25376
	ds_read_u16 v191, v132 offset:25904
	ds_read_u16 v192, v132 offset:26432
	ds_read_u16 v193, v132 offset:26960
	s_waitcnt lgkmcnt(7)
	v_fma_mixlo_f16 v36, v36, v186, 0 op_sel_hi:[0,1,0]
	ds_write_b16 v132, v36 offset:25344
	s_waitcnt lgkmcnt(7)
	v_fma_mixlo_f16 v36, v37, v187, 0 op_sel_hi:[0,1,0]
	ds_write_b16 v132, v36 offset:25872
	s_waitcnt lgkmcnt(7)
	v_fma_mixlo_f16 v36, v38, v188, 0 op_sel_hi:[0,1,0]
	ds_write_b16 v132, v36 offset:26400
	s_waitcnt lgkmcnt(7)
	v_fma_mixlo_f16 v36, v39, v189, 0 op_sel_hi:[0,1,0]
	ds_write_b16 v132, v36 offset:26928
	s_waitcnt lgkmcnt(7)
	v_fma_mixlo_f16 v32, v32, v190, 0 op_sel_hi:[0,1,0]
	ds_write_b16 v132, v32 offset:25376
	s_waitcnt lgkmcnt(7)
	v_fma_mixlo_f16 v32, v33, v191, 0 op_sel_hi:[0,1,0]
	ds_write_b16 v132, v32 offset:25904
	s_waitcnt lgkmcnt(7)
	v_fma_mixlo_f16 v32, v34, v192, 0 op_sel_hi:[0,1,0]
	ds_write_b16 v132, v32 offset:26432
	s_waitcnt lgkmcnt(7)
	v_fma_mixlo_f16 v32, v35, v193, 0 op_sel_hi:[0,1,0]
	ds_write_b16 v132, v32 offset:26960
	ds_read_u16 v186, v132 offset:256
	ds_read_u16 v187, v132 offset:288
	ds_read_u16 v188, v132 offset:784
	ds_read_u16 v189, v132 offset:816
	ds_read_u16 v190, v132 offset:1312
	ds_read_u16 v191, v132 offset:1344
	ds_read_u16 v192, v132 offset:1840
	ds_read_u16 v193, v132 offset:1872
	s_waitcnt lgkmcnt(7)
	v_fma_mixlo_f16 v28, v28, v186, 0 op_sel_hi:[0,1,0]
	ds_write_b16 v132, v28 offset:256
	s_waitcnt lgkmcnt(7)
	v_fma_mixlo_f16 v24, v24, v187, 0 op_sel_hi:[0,1,0]
	ds_write_b16 v132, v24 offset:288
	s_waitcnt lgkmcnt(7)
	v_fma_mixlo_f16 v28, v29, v188, 0 op_sel_hi:[0,1,0]
	ds_write_b16 v132, v28 offset:784
	s_waitcnt lgkmcnt(7)
	v_fma_mixlo_f16 v24, v25, v189, 0 op_sel_hi:[0,1,0]
	ds_write_b16 v132, v24 offset:816
	s_waitcnt lgkmcnt(7)
	v_fma_mixlo_f16 v28, v30, v190, 0 op_sel_hi:[0,1,0]
	ds_write_b16 v132, v28 offset:1312
	s_waitcnt lgkmcnt(7)
	v_fma_mixlo_f16 v24, v26, v191, 0 op_sel_hi:[0,1,0]
	ds_write_b16 v132, v24 offset:1344
	s_waitcnt lgkmcnt(7)
	v_fma_mixlo_f16 v28, v31, v192, 0 op_sel_hi:[0,1,0]
	ds_write_b16 v132, v28 offset:1840
	s_waitcnt lgkmcnt(7)
	v_fma_mixlo_f16 v24, v27, v193, 0 op_sel_hi:[0,1,0]
	ds_write_b16 v132, v24 offset:1872
	ds_read_u16 v186, v132 offset:8704
	ds_read_u16 v187, v132 offset:9232
	ds_read_u16 v188, v132 offset:9760
	ds_read_u16 v189, v132 offset:10288
	ds_read_u16 v190, v132 offset:8736
	ds_read_u16 v191, v132 offset:9264
	ds_read_u16 v192, v132 offset:9792
	ds_read_u16 v193, v132 offset:10320
	s_waitcnt lgkmcnt(7)
	v_fma_mixlo_f16 v20, v20, v186, 0 op_sel_hi:[0,1,0]
	ds_write_b16 v132, v20 offset:8704
	s_waitcnt lgkmcnt(7)
	v_fma_mixlo_f16 v20, v21, v187, 0 op_sel_hi:[0,1,0]
	ds_write_b16 v132, v20 offset:9232
	s_waitcnt lgkmcnt(7)
	v_fma_mixlo_f16 v20, v22, v188, 0 op_sel_hi:[0,1,0]
	ds_write_b16 v132, v20 offset:9760
	s_waitcnt lgkmcnt(7)
	v_fma_mixlo_f16 v20, v23, v189, 0 op_sel_hi:[0,1,0]
	ds_write_b16 v132, v20 offset:10288
	s_waitcnt lgkmcnt(7)
	v_fma_mixlo_f16 v16, v16, v190, 0 op_sel_hi:[0,1,0]
	ds_write_b16 v132, v16 offset:8736
	s_waitcnt lgkmcnt(7)
	v_fma_mixlo_f16 v16, v17, v191, 0 op_sel_hi:[0,1,0]
	ds_write_b16 v132, v16 offset:9264
	s_waitcnt lgkmcnt(7)
	v_fma_mixlo_f16 v16, v18, v192, 0 op_sel_hi:[0,1,0]
	ds_write_b16 v132, v16 offset:9792
	s_waitcnt lgkmcnt(7)
	v_fma_mixlo_f16 v16, v19, v193, 0 op_sel_hi:[0,1,0]
	ds_write_b16 v132, v16 offset:10320
	ds_read_u16 v186, v132 offset:17152
	ds_read_u16 v187, v132 offset:17680
	ds_read_u16 v188, v132 offset:18208
	ds_read_u16 v189, v132 offset:18736
	ds_read_u16 v190, v132 offset:17184
	ds_read_u16 v191, v132 offset:17712
	ds_read_u16 v192, v132 offset:18240
	ds_read_u16 v193, v132 offset:18768
	s_waitcnt lgkmcnt(7)
; #define FOR_R _Pragma("unroll") for (int r = 0; r < 4; ++r)
; #define FOR_AI _Pragma("unroll") for (int ai = 0; ai < 2; ++ai)
; #define FOR_BJ _Pragma("unroll") for (int bj = 0; bj < 2; ++bj)
; #define FOR_M4 _Pragma("unroll") for (int m = 0; m < 4; ++m)
; #define FOR_NN _Pragma("unroll") for (int n = 0; n < 2; ++n)
; __device__ void job_merged_g(const P& p, int g, int job, const HALF* GTbuf, HALF* sm) {
;     ...
;     FOR_AI FOR_BJ {
;       FOR_M4 FOR_NN {
;         const int row0 = ai * 128 + wr * 64 + m * 16 + fq * 4, col = bj * 128 + wc * 32 + n * 16 + fr;
;         FOR_R {
;           HALF* sp = sm + (row0 + r) * SST2 + col;
;           *sp = (HALF)(acc[ai][bj][m][n][r] * (float)(*sp));
;         }
;       }
;       __builtin_amdgcn_sched_barrier(0);
;     }
;     __syncthreads();
	v_fma_mixlo_f16 v12, v12, v186, 0 op_sel_hi:[0,1,0]
	ds_write_b16 v132, v12 offset:17152
	s_waitcnt lgkmcnt(7)
	v_fma_mixlo_f16 v12, v13, v187, 0 op_sel_hi:[0,1,0]
	ds_write_b16 v132, v12 offset:17680
	s_waitcnt lgkmcnt(7)
	v_fma_mixlo_f16 v12, v14, v188, 0 op_sel_hi:[0,1,0]
	ds_write_b16 v132, v12 offset:18208
	s_waitcnt lgkmcnt(7)
	v_fma_mixlo_f16 v12, v15, v189, 0 op_sel_hi:[0,1,0]
	ds_write_b16 v132, v12 offset:18736
	s_waitcnt lgkmcnt(7)
	v_fma_mixlo_f16 v8, v8, v190, 0 op_sel_hi:[0,1,0]
	ds_write_b16 v132, v8 offset:17184
	s_waitcnt lgkmcnt(7)
	v_fma_mixlo_f16 v8, v9, v191, 0 op_sel_hi:[0,1,0]
	ds_write_b16 v132, v8 offset:17712
	s_waitcnt lgkmcnt(7)
	v_fma_mixlo_f16 v8, v10, v192, 0 op_sel_hi:[0,1,0]
	ds_write_b16 v132, v8 offset:18240
	s_waitcnt lgkmcnt(7)
	v_fma_mixlo_f16 v8, v11, v193, 0 op_sel_hi:[0,1,0]
	ds_write_b16 v132, v8 offset:18768
	ds_read_u16 v186, v132 offset:25600
	ds_read_u16 v187, v132 offset:26128
	ds_read_u16 v188, v132 offset:26656
	ds_read_u16 v189, v132 offset:27184
	ds_read_u16 v190, v132 offset:25632
	ds_read_u16 v191, v132 offset:26160
	ds_read_u16 v192, v132 offset:26688
	ds_read_u16 v193, v132 offset:27216
	s_waitcnt lgkmcnt(7)
	v_fma_mixlo_f16 v4, v4, v186, 0 op_sel_hi:[0,1,0]
	ds_write_b16 v132, v4 offset:25600
	s_waitcnt lgkmcnt(7)
	v_fma_mixlo_f16 v4, v5, v187, 0 op_sel_hi:[0,1,0]
	ds_write_b16 v132, v4 offset:26128
	s_waitcnt lgkmcnt(7)
	v_fma_mixlo_f16 v4, v6, v188, 0 op_sel_hi:[0,1,0]
	ds_write_b16 v132, v4 offset:26656
	s_waitcnt lgkmcnt(7)
	v_fma_mixlo_f16 v4, v7, v189, 0 op_sel_hi:[0,1,0]
	ds_write_b16 v132, v4 offset:27184
	s_waitcnt lgkmcnt(7)
	v_fma_mixlo_f16 v0, v0, v190, 0 op_sel_hi:[0,1,0]
	ds_write_b16 v132, v0 offset:25632
	s_waitcnt lgkmcnt(7)
	v_fma_mixlo_f16 v0, v1, v191, 0 op_sel_hi:[0,1,0]
	ds_write_b16 v132, v0 offset:26160
	s_waitcnt lgkmcnt(7)
	v_fma_mixlo_f16 v0, v2, v192, 0 op_sel_hi:[0,1,0]
	ds_write_b16 v132, v0 offset:26688
	s_waitcnt lgkmcnt(7)
	v_fma_mixlo_f16 v0, v3, v193, 0 op_sel_hi:[0,1,0]
	ds_write_b16 v132, v0 offset:27216
	s_waitcnt lgkmcnt(0)
	s_barrier
	s_and_saveexec_b64 s[0:1], s[4:5]
	s_cbranch_execz .LBB0_123
; __device__ void job_merged_g(const P& p, int g, int job, const HALF* GTbuf, HALF* sm) {
;     ...
;     for (int id0 = t5_; id0 < 256 * 32; id0 += 4 * 512) {
;       h8 prev[4];
;       if (fam > 0) {
; #pragma unroll
;         for (int k = 0; k < 4; ++k) {
;           const int id = id0 + 512 * k;
;           prev[k] = *(const h8*)(MR + (size_t)(id >> 5) * 1024 + (id & 31) * 8);
;         }
;       }
; #pragma unroll
;       for (int k = 0; k < 4; ++k) {
;         const int id = id0 + 512 * k;
;         const int row = id >> 5, ch = id & 31;
;         h8 v = *(const h8*)(sm + row * SST2 + ch * 8);
;         if (fam > 0) {
; #pragma unroll
;           for (int e = 0; e < 8; ++e) v[e] = (HALF)((float)v[e] + (float)prev[k][e]);
;         }
;         *(h8*)(MR + (size_t)row * 1024 + ch * 8) = v;
;       }
;     }
	v_ashrrev_i32_e32 v64, 5, v130
	v_lshlrev_b32_e32 v65, 4, v130
	v_and_b32_e32 v65, 0x1f0, v65
	v_lshl_add_u32 v152, v64, 11, v65
	v_lshl_add_u64 v[66:67], s[6:7], 0, v[152:153]
	v_mov_b32_e32 v68, v66
	v_mov_b32_e32 v69, v67
	v_mul_u32_u24_e32 v70, 0x210, v64
	v_add_u32_e32 v70, v70, v65
	v_add_u32_e32 v71, 0x10800, v70
	s_mov_b64 s[2:3], 0x8000
	global_load_dwordx4 v[0:3], v[66:67], off
	v_lshl_add_u64 v[66:67], v[66:67], 0, s[2:3]
	global_load_dwordx4 v[4:7], v[66:67], off
	v_lshl_add_u64 v[66:67], v[66:67], 0, s[2:3]
	global_load_dwordx4 v[8:11], v[66:67], off
	v_lshl_add_u64 v[66:67], v[66:67], 0, s[2:3]
	global_load_dwordx4 v[12:15], v[66:67], off
	v_lshl_add_u64 v[66:67], v[66:67], 0, s[2:3]
	global_load_dwordx4 v[16:19], v[66:67], off
	v_lshl_add_u64 v[66:67], v[66:67], 0, s[2:3]
	global_load_dwordx4 v[20:23], v[66:67], off
	v_lshl_add_u64 v[66:67], v[66:67], 0, s[2:3]
	global_load_dwordx4 v[24:27], v[66:67], off
	v_lshl_add_u64 v[66:67], v[66:67], 0, s[2:3]
	global_load_dwordx4 v[28:31], v[66:67], off
	v_lshl_add_u64 v[66:67], v[66:67], 0, s[2:3]
	global_load_dwordx4 v[32:35], v[66:67], off
	v_lshl_add_u64 v[66:67], v[66:67], 0, s[2:3]
	global_load_dwordx4 v[36:39], v[66:67], off
	v_lshl_add_u64 v[66:67], v[66:67], 0, s[2:3]
	global_load_dwordx4 v[40:43], v[66:67], off
	v_lshl_add_u64 v[66:67], v[66:67], 0, s[2:3]
	global_load_dwordx4 v[44:47], v[66:67], off
	v_lshl_add_u64 v[66:67], v[66:67], 0, s[2:3]
	global_load_dwordx4 v[48:51], v[66:67], off
	v_lshl_add_u64 v[66:67], v[66:67], 0, s[2:3]
	global_load_dwordx4 v[52:55], v[66:67], off
	v_lshl_add_u64 v[66:67], v[66:67], 0, s[2:3]
	global_load_dwordx4 v[56:59], v[66:67], off
	v_lshl_add_u64 v[66:67], v[66:67], 0, s[2:3]
	global_load_dwordx4 v[60:63], v[66:67], off
	ds_read_b128 v[72:75], v70
	ds_read_b128 v[76:79], v70 offset:8448
	ds_read_b128 v[80:83], v70 offset:16896
	ds_read_b128 v[84:87], v70 offset:25344
	s_waitcnt vmcnt(15) lgkmcnt(3)
	v_pk_add_f16 v3, v3, v75
	v_pk_add_f16 v2, v2, v74
	v_pk_add_f16 v1, v1, v73
	v_pk_add_f16 v0, v0, v72
	global_store_dwordx4 v[68:69], v[0:3], off
	v_lshl_add_u64 v[68:69], v[68:69], 0, s[2:3]
	s_waitcnt vmcnt(15) lgkmcnt(2)
	v_pk_add_f16 v7, v7, v79
	v_pk_add_f16 v6, v6, v78
	v_pk_add_f16 v5, v5, v77
	v_pk_add_f16 v4, v4, v76
	global_store_dwordx4 v[68:69], v[4:7], off
	v_lshl_add_u64 v[68:69], v[68:69], 0, s[2:3]
	s_waitcnt vmcnt(15) lgkmcnt(1)
	v_pk_add_f16 v11, v11, v83
	v_pk_add_f16 v10, v10, v82
	v_pk_add_f16 v9, v9, v81
	v_pk_add_f16 v8, v8, v80
	global_store_dwordx4 v[68:69], v[8:11], off
	v_lshl_add_u64 v[68:69], v[68:69], 0, s[2:3]
	s_waitcnt vmcnt(15) lgkmcnt(0)
	v_pk_add_f16 v15, v15, v87
	v_pk_add_f16 v14, v14, v86
	v_pk_add_f16 v13, v13, v85
	v_pk_add_f16 v12, v12, v84
	global_store_dwordx4 v[68:69], v[12:15], off
	v_lshl_add_u64 v[68:69], v[68:69], 0, s[2:3]
	ds_read_b128 v[72:75], v70 offset:33792
	ds_read_b128 v[76:79], v70 offset:42240
	ds_read_b128 v[80:83], v70 offset:50688
	ds_read_b128 v[84:87], v70 offset:59136
	s_waitcnt vmcnt(15) lgkmcnt(3)
	v_pk_add_f16 v19, v19, v75
	v_pk_add_f16 v18, v18, v74
	v_pk_add_f16 v17, v17, v73
	v_pk_add_f16 v16, v16, v72
	global_store_dwordx4 v[68:69], v[16:19], off
	v_lshl_add_u64 v[68:69], v[68:69], 0, s[2:3]
	s_waitcnt vmcnt(15) lgkmcnt(2)
	v_pk_add_f16 v23, v23, v79
	v_pk_add_f16 v22, v22, v78
	v_pk_add_f16 v21, v21, v77
	v_pk_add_f16 v20, v20, v76
	global_store_dwordx4 v[68:69], v[20:23], off
	v_lshl_add_u64 v[68:69], v[68:69], 0, s[2:3]
	s_waitcnt vmcnt(15) lgkmcnt(1)
	v_pk_add_f16 v27, v27, v83
	v_pk_add_f16 v26, v26, v82
	v_pk_add_f16 v25, v25, v81
	v_pk_add_f16 v24, v24, v80
	global_store_dwordx4 v[68:69], v[24:27], off
	v_lshl_add_u64 v[68:69], v[68:69], 0, s[2:3]
	s_waitcnt vmcnt(15) lgkmcnt(0)
	v_pk_add_f16 v31, v31, v87
	v_pk_add_f16 v30, v30, v86
	v_pk_add_f16 v29, v29, v85
	v_pk_add_f16 v28, v28, v84
	global_store_dwordx4 v[68:69], v[28:31], off
	v_lshl_add_u64 v[68:69], v[68:69], 0, s[2:3]
	ds_read_b128 v[72:75], v71
	ds_read_b128 v[76:79], v71 offset:8448
	ds_read_b128 v[80:83], v71 offset:16896
	ds_read_b128 v[84:87], v71 offset:25344
	s_waitcnt vmcnt(15) lgkmcnt(3)
	v_pk_add_f16 v35, v35, v75
	v_pk_add_f16 v34, v34, v74
	v_pk_add_f16 v33, v33, v73
	v_pk_add_f16 v32, v32, v72
	global_store_dwordx4 v[68:69], v[32:35], off
	v_lshl_add_u64 v[68:69], v[68:69], 0, s[2:3]
	s_waitcnt vmcnt(15) lgkmcnt(2)
	v_pk_add_f16 v39, v39, v79
	v_pk_add_f16 v38, v38, v78
	v_pk_add_f16 v37, v37, v77
	v_pk_add_f16 v36, v36, v76
	global_store_dwordx4 v[68:69], v[36:39], off
	v_lshl_add_u64 v[68:69], v[68:69], 0, s[2:3]
	s_waitcnt vmcnt(15) lgkmcnt(1)
	v_pk_add_f16 v43, v43, v83
	v_pk_add_f16 v42, v42, v82
	v_pk_add_f16 v41, v41, v81
	v_pk_add_f16 v40, v40, v80
	global_store_dwordx4 v[68:69], v[40:43], off
	v_lshl_add_u64 v[68:69], v[68:69], 0, s[2:3]
	s_waitcnt vmcnt(15) lgkmcnt(0)
	v_pk_add_f16 v47, v47, v87
	v_pk_add_f16 v46, v46, v86
	v_pk_add_f16 v45, v45, v85
	v_pk_add_f16 v44, v44, v84
	global_store_dwordx4 v[68:69], v[44:47], off
	v_lshl_add_u64 v[68:69], v[68:69], 0, s[2:3]
	ds_read_b128 v[72:75], v71 offset:33792
	ds_read_b128 v[76:79], v71 offset:42240
	ds_read_b128 v[80:83], v71 offset:50688
	ds_read_b128 v[84:87], v71 offset:59136
	s_waitcnt vmcnt(15) lgkmcnt(3)
	v_pk_add_f16 v51, v51, v75
	v_pk_add_f16 v50, v50, v74
	v_pk_add_f16 v49, v49, v73
	v_pk_add_f16 v48, v48, v72
	global_store_dwordx4 v[68:69], v[48:51], off
	v_lshl_add_u64 v[68:69], v[68:69], 0, s[2:3]
	s_waitcnt vmcnt(15) lgkmcnt(2)
	v_pk_add_f16 v55, v55, v79
	v_pk_add_f16 v54, v54, v78
	v_pk_add_f16 v53, v53, v77
	v_pk_add_f16 v52, v52, v76
	global_store_dwordx4 v[68:69], v[52:55], off
	v_lshl_add_u64 v[68:69], v[68:69], 0, s[2:3]
	s_waitcnt vmcnt(15) lgkmcnt(1)
	v_pk_add_f16 v59, v59, v83
	v_pk_add_f16 v58, v58, v82
	v_pk_add_f16 v57, v57, v81
	v_pk_add_f16 v56, v56, v80
	global_store_dwordx4 v[68:69], v[56:59], off
	v_lshl_add_u64 v[68:69], v[68:69], 0, s[2:3]
	s_waitcnt vmcnt(15) lgkmcnt(0)
	v_pk_add_f16 v63, v63, v87
	v_pk_add_f16 v62, v62, v86
	v_pk_add_f16 v61, v61, v85
	v_pk_add_f16 v60, v60, v84
	global_store_dwordx4 v[68:69], v[60:63], off
	s_branch .LBB0_123

; #define FOR_R _Pragma("unroll") for (int r = 0; r < 4; ++r)
; #define FOR_AI _Pragma("unroll") for (int ai = 0; ai < 2; ++ai)
; #define FOR_BJ _Pragma("unroll") for (int bj = 0; bj < 2; ++bj)
; #define FOR_M4 _Pragma("unroll") for (int m = 0; m < 4; ++m)
; template <bool ISK>
; __device__ void job_qk_g(const P& p, int l, int g, int ct2, int rt, HALF* sm) {
;     ...
;   FOR_AI FOR_BJ {
;     FOR_M4 {
;       const int row0 = ai * 128 + wr * 64 + m * 16 + fq * 4;
;       const int lc = bj * 128 + wc * 32 + fr;
;       const int j = (bj * 4 + wc) * 16 + fr;
;       f4 o1, o2;
;       FOR_R {
;         const int sp = (rt * 256 + row0 + r) & (S - 1);
;         const float2 cs = rope[sp * 128 + j];
;         const float a = acc[ai][bj][m][0][r], b = acc[ai][bj][m][1][r];
;         o1[r] = a * cs.x - b * cs.y;
;         o2[r] = a * cs.y + b * cs.x;
;       }
;       acc[ai][bj][m][0] = o1;
;       acc[ai][bj][m][1] = o2;
;       stage2_rm(sm, row0, lc, to_h4(o1));
;       stage2_rm(sm, row0, lc + 16, to_h4(o2));
;       __builtin_amdgcn_sched_barrier(0);
;     }
;   }
.LBB0_196:
	s_or_b64 exec, exec, s[2:3]
	v_lshrrev_b32_e32 v129, 2, v130
	v_ashrrev_i32_e32 v128, 2, v130
	v_and_b32_e32 v129, 12, v129
	s_movk_i32 s6, 0xffc0
	v_and_or_b32 v142, v128, s6, v129
	v_add_u32_e32 v128, s21, v142
	v_bfe_u32 v140, v130, 6, 2
	v_and_b32_e32 v141, 15, v130
	v_and_b32_e32 v130, s22, v128
	v_lshl_or_b32 v129, v140, 4, v141
	v_lshlrev_b32_e32 v143, 7, v130
	v_bitop3_b32 v132, v128, s22, 1 bitop3:0xc8
	s_add_u32 s2, s0, 0x3680000
	v_or_b32_e32 v130, v143, v129
	v_lshlrev_b32_e32 v144, 7, v132
	s_addc_u32 s3, s1, 0
	v_lshlrev_b32_e32 v152, 3, v130
	v_or_b32_e32 v132, v144, v129
	v_lshl_add_u64 v[130:131], s[2:3], 0, v[152:153]
	v_lshlrev_b32_e32 v152, 3, v132
	v_lshl_add_u64 v[132:133], s[2:3], 0, v[152:153]
	s_waitcnt vmcnt(0)
	s_barrier
	v_lshrrev_b32_e32 v226, 8, v155
	v_lshlrev_b32_e32 v226, 6, v226
	v_bfe_u32 v227, v155, 4, 2
	v_lshl_or_b32 v226, v227, 2, v226
	v_add_u32_e32 v226, s21, v226
	v_and_b32_e32 v226, s22, v226
	v_bfe_u32 v227, v155, 6, 2
	v_lshlrev_b32_e32 v227, 4, v227
	v_and_or_b32 v227, v155, 15, v227
	v_lshl_or_b32 v226, v226, 7, v227
	v_lshlrev_b32_e32 v226, 3, v226
	v_mov_b32_e32 v227, v226
	global_load_dwordx2 v[194:195], v227, s[2:3]
	global_load_dwordx2 v[196:197], v227, s[2:3] offset:1024
	global_load_dwordx2 v[198:199], v227, s[2:3] offset:2048
	global_load_dwordx2 v[200:201], v227, s[2:3] offset:3072
	v_add_u32_e32 v227, 0x4000, v226
	global_load_dwordx2 v[202:203], v227, s[2:3]
	global_load_dwordx2 v[204:205], v227, s[2:3] offset:1024
	global_load_dwordx2 v[206:207], v227, s[2:3] offset:2048
	global_load_dwordx2 v[208:209], v227, s[2:3] offset:3072
	v_add_u32_e32 v227, 0x8000, v226
	global_load_dwordx2 v[210:211], v227, s[2:3]
	global_load_dwordx2 v[212:213], v227, s[2:3] offset:1024
	global_load_dwordx2 v[214:215], v227, s[2:3] offset:2048
	global_load_dwordx2 v[216:217], v227, s[2:3] offset:3072
	v_add_u32_e32 v227, 0xc000, v226
	global_load_dwordx2 v[218:219], v227, s[2:3]
	global_load_dwordx2 v[220:221], v227, s[2:3] offset:1024
	global_load_dwordx2 v[222:223], v227, s[2:3] offset:2048
	global_load_dwordx2 v[224:225], v227, s[2:3] offset:3072
	s_waitcnt vmcnt(15)
	v_mov_b32_e32 v134, v194
	v_mov_b32_e32 v135, v195
	s_nop 0
	s_waitcnt vmcnt(14)
	v_mov_b32_e32 v132, v196
	v_mov_b32_e32 v133, v197
	v_bitop3_b32 v130, v128, s22, 2 bitop3:0xc8
	v_lshlrev_b32_e32 v145, 7, v130
	v_or_b32_e32 v130, v145, v129
	v_lshlrev_b32_e32 v152, 3, v130
	v_lshl_add_u64 v[130:131], s[2:3], 0, v[152:153]
	s_waitcnt vmcnt(13)
	v_mov_b32_e32 v136, v198
	v_mov_b32_e32 v137, v199
	v_bitop3_b32 v130, v128, s22, 3 bitop3:0xc8
	v_lshlrev_b32_e32 v146, 7, v130
	v_or_b32_e32 v130, v146, v129
	v_lshlrev_b32_e32 v152, 3, v130
	v_lshl_add_u64 v[130:131], s[2:3], 0, v[152:153]
	s_waitcnt vmcnt(12)
	v_mov_b32_e32 v138, v200
	v_mov_b32_e32 v139, v201
	v_lshlrev_b32_e32 v130, 1, v141
	v_lshl_or_b32 v130, v140, 6, v130
	v_mul_lo_u32 v131, v142, s64
	v_add_u32_e32 v140, 48, v128
	v_add3_u32 v130, 0, v131, v130
	v_and_b32_e32 v131, s22, v140
	v_lshlrev_b32_e32 v131, 7, v131
	s_waitcnt lgkmcnt(0)
	v_mul_f32_e32 v140, v124, v135
	v_mul_f32_e32 v135, v120, v135
	v_mul_f32_e32 v141, v125, v133
	v_mul_f32_e32 v133, v121, v133
	v_fma_mixlo_f16 v120, v120, v134, -v140
	v_fma_mixlo_f16 v124, v124, v134, v135
	v_fma_mixlo_f16 v121, v121, v132, -v141
	v_mul_f32_e32 v134, v126, v137
	v_mul_f32_e32 v135, v122, v137
	ds_write_b16 v130, v120
	v_fma_mixlo_f16 v120, v125, v132, v133
	ds_write_b16 v130, v124 offset:32
	v_fma_mixlo_f16 v122, v122, v136, -v134
	v_mul_f32_e32 v124, v127, v139
	v_mul_f32_e32 v125, v123, v139
	ds_write_b16 v130, v121 offset:528
	v_fma_mixlo_f16 v121, v126, v136, v135
	ds_write_b16 v130, v120 offset:560
	v_fma_mixlo_f16 v120, v123, v138, -v124
	ds_write_b16 v130, v122 offset:1056
	v_fma_mixlo_f16 v122, v127, v138, v125
	ds_write_b16 v130, v121 offset:1088
	ds_write_b16 v130, v120 offset:1584
	ds_write_b16 v130, v122 offset:1616
	v_add_u32_e32 v120, 16, v128
	v_and_b32_e32 v120, s22, v120
	v_add_u32_e32 v122, 17, v128
	v_lshlrev_b32_e32 v132, 7, v120
	v_and_b32_e32 v122, s22, v122
	v_add_u32_e32 v124, 18, v128
	v_or_b32_e32 v120, v132, v129
	v_lshlrev_b32_e32 v133, 7, v122
	v_and_b32_e32 v124, s22, v124
	v_add_u32_e32 v126, 19, v128
	v_lshlrev_b32_e32 v152, 3, v120
	v_or_b32_e32 v122, v133, v129
	v_lshlrev_b32_e32 v134, 7, v124
	v_and_b32_e32 v126, s22, v126
	v_lshl_add_u64 v[120:121], s[2:3], 0, v[152:153]
	v_lshlrev_b32_e32 v152, 3, v122
	v_or_b32_e32 v124, v134, v129
	v_lshlrev_b32_e32 v135, 7, v126
	v_lshl_add_u64 v[122:123], s[2:3], 0, v[152:153]
	v_lshlrev_b32_e32 v152, 3, v124
	v_or_b32_e32 v126, v135, v129
	s_waitcnt vmcnt(11)
	v_mov_b32_e32 v120, v202
	v_mov_b32_e32 v121, v203
	s_nop 0
	s_waitcnt vmcnt(10)
	v_mov_b32_e32 v122, v204
	v_mov_b32_e32 v123, v205
	v_lshl_add_u64 v[124:125], s[2:3], 0, v[152:153]
	v_lshlrev_b32_e32 v152, 3, v126
	s_waitcnt vmcnt(9)
	v_mov_b32_e32 v124, v206
	v_mov_b32_e32 v125, v207
	v_lshl_add_u64 v[126:127], s[2:3], 0, v[152:153]
	s_waitcnt vmcnt(8)
	v_mov_b32_e32 v126, v208
	v_mov_b32_e32 v127, v209
	s_waitcnt lgkmcnt(0)
; #define FOR_R _Pragma("unroll") for (int r = 0; r < 4; ++r)
; #define FOR_AI _Pragma("unroll") for (int ai = 0; ai < 2; ++ai)
; #define FOR_BJ _Pragma("unroll") for (int bj = 0; bj < 2; ++bj)
; #define FOR_M4 _Pragma("unroll") for (int m = 0; m < 4; ++m)
; template <bool ISK>
; __device__ void job_qk_g(const P& p, int l, int g, int ct2, int rt, HALF* sm) {
;     ...
;   FOR_AI FOR_BJ {
;     FOR_M4 {
;       const int row0 = ai * 128 + wr * 64 + m * 16 + fq * 4;
;       const int lc = bj * 128 + wc * 32 + fr;
;       const int j = (bj * 4 + wc) * 16 + fr;
;       f4 o1, o2;
;       FOR_R {
;         const int sp = (rt * 256 + row0 + r) & (S - 1);
;         const float2 cs = rope[sp * 128 + j];
;         const float a = acc[ai][bj][m][0][r], b = acc[ai][bj][m][1][r];
;         o1[r] = a * cs.x - b * cs.y;
;         o2[r] = a * cs.y + b * cs.x;
;       }
;       acc[ai][bj][m][0] = o1;
;       acc[ai][bj][m][1] = o2;
;       stage2_rm(sm, row0, lc, to_h4(o1));
;       stage2_rm(sm, row0, lc + 16, to_h4(o2));
;       __builtin_amdgcn_sched_barrier(0);
;     }
;   }
	v_mul_f32_e32 v136, v116, v121
	v_mul_f32_e32 v121, v112, v121
	v_mul_f32_e32 v137, v117, v123
	v_mul_f32_e32 v123, v113, v123
	v_fma_mixlo_f16 v112, v112, v120, -v136
	v_fma_mixlo_f16 v116, v116, v120, v121
	v_mul_f32_e32 v120, v118, v125
	v_mul_f32_e32 v121, v114, v125
	v_fma_mixlo_f16 v113, v113, v122, -v137
	ds_write_b16 v130, v112 offset:8448
	v_fma_mixlo_f16 v112, v117, v122, v123
	ds_write_b16 v130, v116 offset:8480
	v_mul_f32_e32 v116, v119, v127
	v_mul_f32_e32 v117, v115, v127
	v_fma_mixlo_f16 v114, v114, v124, -v120
	ds_write_b16 v130, v113 offset:8976
	v_fma_mixlo_f16 v113, v118, v124, v121
	ds_write_b16 v130, v112 offset:9008
	v_fma_mixlo_f16 v112, v115, v126, -v116
	ds_write_b16 v130, v114 offset:9504
	v_fma_mixlo_f16 v114, v119, v126, v117
	ds_write_b16 v130, v113 offset:9536
	ds_write_b16 v130, v112 offset:10032
	ds_write_b16 v130, v114 offset:10064
	v_add_u32_e32 v112, 32, v128
	v_and_b32_e32 v112, s22, v112
	v_add_u32_e32 v114, 33, v128
	v_lshlrev_b32_e32 v120, 7, v112
	v_and_b32_e32 v114, s22, v114
	v_add_u32_e32 v116, 34, v128
	v_or_b32_e32 v112, v120, v129
	v_lshlrev_b32_e32 v121, 7, v114
	v_and_b32_e32 v116, s22, v116
	v_add_u32_e32 v118, 35, v128
	v_lshlrev_b32_e32 v152, 3, v112
	v_or_b32_e32 v114, v121, v129
	v_lshlrev_b32_e32 v122, 7, v116
	v_and_b32_e32 v118, s22, v118
	v_lshl_add_u64 v[112:113], s[2:3], 0, v[152:153]
	v_lshlrev_b32_e32 v152, 3, v114
	v_or_b32_e32 v116, v122, v129
	v_lshlrev_b32_e32 v123, 7, v118
	v_lshl_add_u64 v[114:115], s[2:3], 0, v[152:153]
	v_lshlrev_b32_e32 v152, 3, v116
	v_or_b32_e32 v118, v123, v129
	v_add_u32_e32 v227, 0x200, v226
	global_load_dwordx2 v[194:195], v227, s[2:3]
	global_load_dwordx2 v[196:197], v227, s[2:3] offset:1024
	global_load_dwordx2 v[198:199], v227, s[2:3] offset:2048
	global_load_dwordx2 v[200:201], v227, s[2:3] offset:3072
	v_add_u32_e32 v227, 0x4200, v226
	global_load_dwordx2 v[202:203], v227, s[2:3]
	global_load_dwordx2 v[204:205], v227, s[2:3] offset:1024
	global_load_dwordx2 v[206:207], v227, s[2:3] offset:2048
	global_load_dwordx2 v[208:209], v227, s[2:3] offset:3072
	s_waitcnt vmcnt(15)
	v_mov_b32_e32 v112, v210
	v_mov_b32_e32 v113, v211
	s_nop 0
	s_waitcnt vmcnt(14)
	v_mov_b32_e32 v114, v212
	v_mov_b32_e32 v115, v213
	v_lshl_add_u64 v[116:117], s[2:3], 0, v[152:153]
	v_lshlrev_b32_e32 v152, 3, v118
	s_waitcnt vmcnt(13)
	v_mov_b32_e32 v116, v214
	v_mov_b32_e32 v117, v215
	v_lshl_add_u64 v[118:119], s[2:3], 0, v[152:153]
	s_waitcnt vmcnt(12)
	v_mov_b32_e32 v118, v216
	v_mov_b32_e32 v119, v217
	s_waitcnt lgkmcnt(0)
	v_mul_f32_e32 v124, v108, v113
	v_mul_f32_e32 v113, v104, v113
	v_mul_f32_e32 v125, v109, v115
	v_mul_f32_e32 v115, v105, v115
	v_fma_mixlo_f16 v104, v104, v112, -v124
	v_fma_mixlo_f16 v108, v108, v112, v113
	v_mul_f32_e32 v112, v110, v117
	v_mul_f32_e32 v113, v106, v117
	v_fma_mixlo_f16 v105, v105, v114, -v125
	ds_write_b16 v130, v104 offset:16896
	v_fma_mixlo_f16 v104, v109, v114, v115
	ds_write_b16 v130, v108 offset:16928
	v_mul_f32_e32 v108, v111, v119
	v_mul_f32_e32 v109, v107, v119
	v_fma_mixlo_f16 v106, v106, v116, -v112
	ds_write_b16 v130, v105 offset:17424
	v_fma_mixlo_f16 v105, v110, v116, v113
	ds_write_b16 v130, v104 offset:17456
	v_fma_mixlo_f16 v104, v107, v118, -v108
	ds_write_b16 v130, v106 offset:17952
	v_fma_mixlo_f16 v106, v111, v118, v109
	ds_write_b16 v130, v105 offset:17984
	ds_write_b16 v130, v104 offset:18480
	ds_write_b16 v130, v106 offset:18512
	v_add_u32_e32 v106, 49, v128
	v_or_b32_e32 v104, v131, v129
	v_and_b32_e32 v106, s22, v106
	v_add_u32_e32 v108, 50, v128
	v_lshlrev_b32_e32 v152, 3, v104
	v_lshlrev_b32_e32 v112, 7, v106
	v_and_b32_e32 v108, s22, v108
	v_add_u32_e32 v110, 51, v128
	v_lshl_add_u64 v[104:105], s[2:3], 0, v[152:153]
	v_or_b32_e32 v106, v112, v129
	v_lshlrev_b32_e32 v113, 7, v108
	v_and_b32_e32 v110, s22, v110
	s_waitcnt vmcnt(11)
	v_mov_b32_e32 v104, v218
	v_mov_b32_e32 v105, v219
	v_lshlrev_b32_e32 v152, 3, v106
	v_or_b32_e32 v108, v113, v129
	v_lshlrev_b32_e32 v114, 7, v110
	v_lshl_add_u64 v[106:107], s[2:3], 0, v[152:153]
	v_lshlrev_b32_e32 v152, 3, v108
	v_or_b32_e32 v110, v114, v129
	v_lshl_add_u64 v[108:109], s[2:3], 0, v[152:153]
	v_lshlrev_b32_e32 v152, 3, v110
	s_waitcnt vmcnt(10)
	v_mov_b32_e32 v106, v220
	v_mov_b32_e32 v107, v221
	s_nop 0
	s_waitcnt vmcnt(9)
	v_mov_b32_e32 v108, v222
	v_mov_b32_e32 v109, v223
	v_lshl_add_u64 v[110:111], s[2:3], 0, v[152:153]
	s_waitcnt vmcnt(8)
	v_mov_b32_e32 v110, v224
	v_mov_b32_e32 v111, v225
	s_waitcnt lgkmcnt(0)
	v_mul_f32_e32 v115, v100, v105
	v_mul_f32_e32 v105, v96, v105
	v_fma_mixlo_f16 v96, v96, v104, -v115
	v_fma_mixlo_f16 v100, v100, v104, v105
	ds_write_b16 v130, v96 offset:25344
	ds_write_b16 v130, v100 offset:25376
	v_mul_f32_e32 v96, v101, v107
	v_mul_f32_e32 v100, v97, v107
	v_mul_f32_e32 v104, v102, v109
	v_mul_f32_e32 v105, v98, v109
	v_fma_mixlo_f16 v96, v97, v106, -v96
	v_fma_mixlo_f16 v97, v101, v106, v100
	v_mul_f32_e32 v100, v103, v111
	v_mul_f32_e32 v101, v99, v111
	v_fma_mixlo_f16 v98, v98, v108, -v104
	ds_write_b16 v130, v96 offset:25872
	v_fma_mixlo_f16 v96, v102, v108, v105
	ds_write_b16 v130, v97 offset:25904
	v_fma_mixlo_f16 v97, v99, v110, -v100
	ds_write_b16 v130, v98 offset:26400
	v_fma_mixlo_f16 v98, v103, v110, v101
	ds_write_b16 v130, v96 offset:26432
	ds_write_b16 v130, v97 offset:26928
	ds_write_b16 v130, v98 offset:26960
	v_or_b32_e32 v96, 64, v129
	v_or_b32_e32 v97, v143, v96
	v_lshlrev_b32_e32 v152, 3, v97
	v_or_b32_e32 v97, v144, v96
	v_lshl_add_u64 v[98:99], s[2:3], 0, v[152:153]
	v_lshlrev_b32_e32 v152, 3, v97
	v_or_b32_e32 v97, v145, v96
	v_lshl_add_u64 v[100:101], s[2:3], 0, v[152:153]
	v_lshlrev_b32_e32 v152, 3, v97
	v_or_b32_e32 v97, v146, v96
	v_add_u32_e32 v227, 0x8200, v226
	global_load_dwordx2 v[210:211], v227, s[2:3]
	global_load_dwordx2 v[212:213], v227, s[2:3] offset:1024
	global_load_dwordx2 v[214:215], v227, s[2:3] offset:2048
	global_load_dwordx2 v[216:217], v227, s[2:3] offset:3072
	v_add_u32_e32 v227, 0xc200, v226
	global_load_dwordx2 v[218:219], v227, s[2:3]
	global_load_dwordx2 v[220:221], v227, s[2:3] offset:1024
	global_load_dwordx2 v[222:223], v227, s[2:3] offset:2048
	global_load_dwordx2 v[224:225], v227, s[2:3] offset:3072
	s_waitcnt vmcnt(15)
; #define FOR_R _Pragma("unroll") for (int r = 0; r < 4; ++r)
; #define FOR_AI _Pragma("unroll") for (int ai = 0; ai < 2; ++ai)
; #define FOR_BJ _Pragma("unroll") for (int bj = 0; bj < 2; ++bj)
; #define FOR_M4 _Pragma("unroll") for (int m = 0; m < 4; ++m)
; template <bool ISK>
; __device__ void job_qk_g(const P& p, int l, int g, int ct2, int rt, HALF* sm) {
;     ...
;   FOR_AI FOR_BJ {
;     FOR_M4 {
;       const int row0 = ai * 128 + wr * 64 + m * 16 + fq * 4;
;       const int lc = bj * 128 + wc * 32 + fr;
;       const int j = (bj * 4 + wc) * 16 + fr;
;       f4 o1, o2;
;       FOR_R {
;         const int sp = (rt * 256 + row0 + r) & (S - 1);
;         const float2 cs = rope[sp * 128 + j];
;         const float a = acc[ai][bj][m][0][r], b = acc[ai][bj][m][1][r];
;         o1[r] = a * cs.x - b * cs.y;
;         o2[r] = a * cs.y + b * cs.x;
;       }
;       acc[ai][bj][m][0] = o1;
;       acc[ai][bj][m][1] = o2;
;       stage2_rm(sm, row0, lc, to_h4(o1));
;       stage2_rm(sm, row0, lc + 16, to_h4(o2));
;       __builtin_amdgcn_sched_barrier(0);
;     }
;   }
	v_mov_b32_e32 v98, v194
	v_mov_b32_e32 v99, v195
	v_lshl_add_u64 v[102:103], s[2:3], 0, v[152:153]
	s_waitcnt vmcnt(14)
	v_mov_b32_e32 v100, v196
	v_mov_b32_e32 v101, v197
	v_lshlrev_b32_e32 v152, 3, v97
	s_waitcnt vmcnt(13)
	v_mov_b32_e32 v102, v198
	v_mov_b32_e32 v103, v199
	v_lshl_add_u64 v[104:105], s[2:3], 0, v[152:153]
	s_waitcnt vmcnt(12)
	v_mov_b32_e32 v104, v200
	v_mov_b32_e32 v105, v201
	s_waitcnt lgkmcnt(0)
	v_mul_f32_e32 v97, v92, v99
	v_mul_f32_e32 v99, v88, v99
	v_mul_f32_e32 v106, v93, v101
	v_mul_f32_e32 v101, v89, v101
	v_fma_mixlo_f16 v88, v88, v98, -v97
	v_fma_mixlo_f16 v92, v92, v98, v99
	v_mul_f32_e32 v97, v94, v103
	v_mul_f32_e32 v98, v90, v103
	v_fma_mixlo_f16 v89, v89, v100, -v106
	ds_write_b16 v130, v88 offset:256
	v_fma_mixlo_f16 v88, v93, v100, v101
	ds_write_b16 v130, v92 offset:288
	v_mul_f32_e32 v92, v95, v105
	v_mul_f32_e32 v93, v91, v105
	v_fma_mixlo_f16 v90, v90, v102, -v97
	ds_write_b16 v130, v89 offset:784
	v_fma_mixlo_f16 v89, v94, v102, v98
	ds_write_b16 v130, v88 offset:816
	v_fma_mixlo_f16 v88, v91, v104, -v92
	ds_write_b16 v130, v90 offset:1312
	v_fma_mixlo_f16 v90, v95, v104, v93
	ds_write_b16 v130, v89 offset:1344
	ds_write_b16 v130, v88 offset:1840
	ds_write_b16 v130, v90 offset:1872
	v_or_b32_e32 v88, v132, v96
	v_lshlrev_b32_e32 v152, 3, v88
	v_or_b32_e32 v90, v133, v96
	v_lshl_add_u64 v[88:89], s[2:3], 0, v[152:153]
	v_lshlrev_b32_e32 v152, 3, v90
	v_or_b32_e32 v92, v134, v96
	v_lshl_add_u64 v[90:91], s[2:3], 0, v[152:153]
	v_lshlrev_b32_e32 v152, 3, v92
	v_or_b32_e32 v94, v135, v96
	s_waitcnt vmcnt(11)
	v_mov_b32_e32 v88, v202
	v_mov_b32_e32 v89, v203
	v_lshl_add_u64 v[92:93], s[2:3], 0, v[152:153]
	s_waitcnt vmcnt(10)
	v_mov_b32_e32 v90, v204
	v_mov_b32_e32 v91, v205
	v_lshlrev_b32_e32 v152, 3, v94
	s_waitcnt vmcnt(9)
	v_mov_b32_e32 v92, v206
	v_mov_b32_e32 v93, v207
	v_lshl_add_u64 v[94:95], s[2:3], 0, v[152:153]
	s_waitcnt vmcnt(8)
	v_mov_b32_e32 v94, v208
	v_mov_b32_e32 v95, v209
	s_waitcnt lgkmcnt(0)
	v_mul_f32_e32 v97, v84, v89
	v_mul_f32_e32 v89, v80, v89
	v_mul_f32_e32 v98, v85, v91
	v_mul_f32_e32 v91, v81, v91
	v_fma_mixlo_f16 v80, v80, v88, -v97
	v_fma_mixlo_f16 v84, v84, v88, v89
	v_mul_f32_e32 v88, v86, v93
	v_mul_f32_e32 v89, v82, v93
	v_fma_mixlo_f16 v81, v81, v90, -v98
	ds_write_b16 v130, v80 offset:8704
	v_fma_mixlo_f16 v80, v85, v90, v91
	ds_write_b16 v130, v84 offset:8736
	v_mul_f32_e32 v84, v87, v95
	v_mul_f32_e32 v85, v83, v95
	v_fma_mixlo_f16 v82, v82, v92, -v88
	ds_write_b16 v130, v81 offset:9232
	v_fma_mixlo_f16 v81, v86, v92, v89
	ds_write_b16 v130, v80 offset:9264
	v_fma_mixlo_f16 v80, v83, v94, -v84
	ds_write_b16 v130, v82 offset:9760
	v_fma_mixlo_f16 v82, v87, v94, v85
	ds_write_b16 v130, v81 offset:9792
	ds_write_b16 v130, v80 offset:10288
	ds_write_b16 v130, v82 offset:10320
	v_or_b32_e32 v80, v120, v96
	v_lshlrev_b32_e32 v152, 3, v80
	v_or_b32_e32 v82, v121, v96
	v_lshl_add_u64 v[80:81], s[2:3], 0, v[152:153]
	v_lshlrev_b32_e32 v152, 3, v82
	v_or_b32_e32 v84, v122, v96
	v_lshl_add_u64 v[82:83], s[2:3], 0, v[152:153]
	v_lshlrev_b32_e32 v152, 3, v84
	v_or_b32_e32 v86, v123, v96
	v_add_u32_e32 v227, 0x20000, v226
	global_load_dwordx2 v[194:195], v227, s[2:3]
	global_load_dwordx2 v[196:197], v227, s[2:3] offset:1024
	global_load_dwordx2 v[198:199], v227, s[2:3] offset:2048
	global_load_dwordx2 v[200:201], v227, s[2:3] offset:3072
	v_add_u32_e32 v227, 0x24000, v226
	global_load_dwordx2 v[202:203], v227, s[2:3]
	global_load_dwordx2 v[204:205], v227, s[2:3] offset:1024
	global_load_dwordx2 v[206:207], v227, s[2:3] offset:2048
	global_load_dwordx2 v[208:209], v227, s[2:3] offset:3072
	s_waitcnt vmcnt(15)
	v_mov_b32_e32 v80, v210
	v_mov_b32_e32 v81, v211
	v_lshl_add_u64 v[84:85], s[2:3], 0, v[152:153]
	s_waitcnt vmcnt(14)
	v_mov_b32_e32 v82, v212
	v_mov_b32_e32 v83, v213
	v_lshlrev_b32_e32 v152, 3, v86
	s_waitcnt vmcnt(13)
	v_mov_b32_e32 v84, v214
	v_mov_b32_e32 v85, v215
	v_lshl_add_u64 v[86:87], s[2:3], 0, v[152:153]
	s_waitcnt vmcnt(12)
	v_mov_b32_e32 v86, v216
	v_mov_b32_e32 v87, v217
	s_waitcnt lgkmcnt(0)
	v_mul_f32_e32 v88, v76, v81
	v_mul_f32_e32 v81, v72, v81
	v_mul_f32_e32 v89, v77, v83
	v_mul_f32_e32 v83, v73, v83
	v_fma_mixlo_f16 v72, v72, v80, -v88
	v_fma_mixlo_f16 v76, v76, v80, v81
	v_mul_f32_e32 v80, v78, v85
	v_mul_f32_e32 v81, v74, v85
	v_fma_mixlo_f16 v73, v73, v82, -v89
	ds_write_b16 v130, v72 offset:17152
	v_fma_mixlo_f16 v72, v77, v82, v83
	ds_write_b16 v130, v76 offset:17184
	v_mul_f32_e32 v76, v79, v87
	v_mul_f32_e32 v77, v75, v87
	v_fma_mixlo_f16 v74, v74, v84, -v80
	ds_write_b16 v130, v73 offset:17680
	v_fma_mixlo_f16 v73, v78, v84, v81
	ds_write_b16 v130, v72 offset:17712
	v_fma_mixlo_f16 v72, v75, v86, -v76
	ds_write_b16 v130, v74 offset:18208
	v_fma_mixlo_f16 v74, v79, v86, v77
	ds_write_b16 v130, v73 offset:18240
	ds_write_b16 v130, v72 offset:18736
	ds_write_b16 v130, v74 offset:18768
	v_or_b32_e32 v72, v131, v96
	v_lshlrev_b32_e32 v152, 3, v72
	v_or_b32_e32 v74, v112, v96
	v_lshl_add_u64 v[72:73], s[2:3], 0, v[152:153]
	v_lshlrev_b32_e32 v152, 3, v74
	v_or_b32_e32 v76, v113, v96
	v_lshl_add_u64 v[74:75], s[2:3], 0, v[152:153]
	v_lshlrev_b32_e32 v152, 3, v76
	v_or_b32_e32 v78, v114, v96
	s_waitcnt vmcnt(11)
	v_mov_b32_e32 v72, v218
	v_mov_b32_e32 v73, v219
	v_lshl_add_u64 v[76:77], s[2:3], 0, v[152:153]
	s_waitcnt vmcnt(10)
	v_mov_b32_e32 v74, v220
	v_mov_b32_e32 v75, v221
	v_lshlrev_b32_e32 v152, 3, v78
	s_waitcnt vmcnt(9)
	v_mov_b32_e32 v76, v222
	v_mov_b32_e32 v77, v223
	v_lshl_add_u64 v[78:79], s[2:3], 0, v[152:153]
	s_waitcnt vmcnt(8)
	v_mov_b32_e32 v78, v224
	v_mov_b32_e32 v79, v225
	s_waitcnt lgkmcnt(0)
; #define FOR_R _Pragma("unroll") for (int r = 0; r < 4; ++r)
; #define FOR_AI _Pragma("unroll") for (int ai = 0; ai < 2; ++ai)
; #define FOR_BJ _Pragma("unroll") for (int bj = 0; bj < 2; ++bj)
; #define FOR_M4 _Pragma("unroll") for (int m = 0; m < 4; ++m)
; template <bool ISK>
; __device__ void job_qk_g(const P& p, int l, int g, int ct2, int rt, HALF* sm) {
;     ...
;   FOR_AI FOR_BJ {
;     FOR_M4 {
;       const int row0 = ai * 128 + wr * 64 + m * 16 + fq * 4;
;       const int lc = bj * 128 + wc * 32 + fr;
;       const int j = (bj * 4 + wc) * 16 + fr;
;       f4 o1, o2;
;       FOR_R {
;         const int sp = (rt * 256 + row0 + r) & (S - 1);
;         const float2 cs = rope[sp * 128 + j];
;         const float a = acc[ai][bj][m][0][r], b = acc[ai][bj][m][1][r];
;         o1[r] = a * cs.x - b * cs.y;
;         o2[r] = a * cs.y + b * cs.x;
;       }
;       acc[ai][bj][m][0] = o1;
;       acc[ai][bj][m][1] = o2;
;       stage2_rm(sm, row0, lc, to_h4(o1));
;       stage2_rm(sm, row0, lc + 16, to_h4(o2));
;       __builtin_amdgcn_sched_barrier(0);
;     }
;   }
	v_mul_f32_e32 v80, v68, v73
	v_mul_f32_e32 v73, v64, v73
	v_mul_f32_e32 v81, v69, v75
	v_mul_f32_e32 v75, v65, v75
	v_fma_mixlo_f16 v64, v64, v72, -v80
	v_fma_mixlo_f16 v68, v68, v72, v73
	v_mul_f32_e32 v72, v70, v77
	v_mul_f32_e32 v73, v66, v77
	v_fma_mixlo_f16 v65, v65, v74, -v81
	ds_write_b16 v130, v64 offset:25600
	v_fma_mixlo_f16 v64, v69, v74, v75
	ds_write_b16 v130, v68 offset:25632
	v_mul_f32_e32 v68, v71, v79
	v_mul_f32_e32 v69, v67, v79
	v_fma_mixlo_f16 v66, v66, v76, -v72
	ds_write_b16 v130, v65 offset:26128
	v_fma_mixlo_f16 v65, v70, v76, v73
	ds_write_b16 v130, v64 offset:26160
	v_fma_mixlo_f16 v64, v67, v78, -v68
	ds_write_b16 v130, v66 offset:26656
	v_fma_mixlo_f16 v66, v71, v78, v69
	ds_write_b16 v130, v65 offset:26688
	ds_write_b16 v130, v64 offset:27184
	ds_write_b16 v130, v66 offset:27216
	v_add_u32_e32 v64, 0x80, v128
	v_and_b32_e32 v64, s22, v64
	v_add_u32_e32 v66, 0x81, v128
	v_lshlrev_b32_e32 v74, 7, v64
	v_and_b32_e32 v66, s22, v66
	v_or_b32_e32 v64, v74, v129
	v_lshlrev_b32_e32 v75, 7, v66
	v_lshlrev_b32_e32 v152, 3, v64
	v_or_b32_e32 v66, v75, v129
	v_lshl_add_u64 v[64:65], s[2:3], 0, v[152:153]
	v_lshlrev_b32_e32 v152, 3, v66
	v_lshl_add_u64 v[66:67], s[2:3], 0, v[152:153]
	v_add_u32_e32 v227, 0x28000, v226
	global_load_dwordx2 v[210:211], v227, s[2:3]
	global_load_dwordx2 v[212:213], v227, s[2:3] offset:1024
	global_load_dwordx2 v[214:215], v227, s[2:3] offset:2048
	global_load_dwordx2 v[216:217], v227, s[2:3] offset:3072
	v_add_u32_e32 v227, 0x2c000, v226
	global_load_dwordx2 v[218:219], v227, s[2:3]
	global_load_dwordx2 v[220:221], v227, s[2:3] offset:1024
	global_load_dwordx2 v[222:223], v227, s[2:3] offset:2048
	global_load_dwordx2 v[224:225], v227, s[2:3] offset:3072
	s_waitcnt vmcnt(15)
	v_mov_b32_e32 v68, v194
	v_mov_b32_e32 v69, v195
	s_nop 0
	s_waitcnt vmcnt(14)
	v_mov_b32_e32 v66, v196
	v_mov_b32_e32 v67, v197
	v_add_u32_e32 v64, 0x82, v128
	v_and_b32_e32 v64, s22, v64
	v_lshlrev_b32_e32 v76, 7, v64
	v_or_b32_e32 v64, v76, v129
	v_lshlrev_b32_e32 v152, 3, v64
	v_lshl_add_u64 v[64:65], s[2:3], 0, v[152:153]
	s_waitcnt vmcnt(13)
	v_mov_b32_e32 v70, v198
	v_mov_b32_e32 v71, v199
	v_add_u32_e32 v64, 0x83, v128
	v_and_b32_e32 v64, s22, v64
	v_lshlrev_b32_e32 v77, 7, v64
	v_or_b32_e32 v64, v77, v129
	v_lshlrev_b32_e32 v152, 3, v64
	v_lshl_add_u64 v[64:65], s[2:3], 0, v[152:153]
	s_waitcnt vmcnt(12)
	v_mov_b32_e32 v72, v200
	v_mov_b32_e32 v73, v201
	v_add_u32_e32 v65, 0xb0, v128
	v_add_u32_e32 v64, 0x10800, v130
	v_and_b32_e32 v65, s22, v65
	v_lshlrev_b32_e32 v65, 7, v65
	s_waitcnt lgkmcnt(0)
	v_mul_f32_e32 v78, v60, v69
	v_mul_f32_e32 v69, v56, v69
	v_mul_f32_e32 v79, v61, v67
	v_mul_f32_e32 v67, v57, v67
	v_fma_mixlo_f16 v56, v56, v68, -v78
	v_fma_mixlo_f16 v60, v60, v68, v69
	v_fma_mixlo_f16 v57, v57, v66, -v79
	ds_write_b16 v64, v56
	v_mul_f32_e32 v68, v62, v71
	v_mul_f32_e32 v69, v58, v71
	v_fma_mixlo_f16 v56, v61, v66, v67
	ds_write_b16 v64, v60 offset:32
	v_fma_mixlo_f16 v58, v58, v70, -v68
	ds_write_b16 v64, v57 offset:528
	v_fma_mixlo_f16 v57, v62, v70, v69
	v_mul_f32_e32 v60, v63, v73
	v_mul_f32_e32 v61, v59, v73
	ds_write_b16 v64, v56 offset:560
	v_fma_mixlo_f16 v56, v59, v72, -v60
	ds_write_b16 v64, v58 offset:1056
	v_fma_mixlo_f16 v58, v63, v72, v61
	ds_write_b16 v64, v57 offset:1088
	ds_write_b16 v64, v56 offset:1584
	ds_write_b16 v64, v58 offset:1616
	v_add_u32_e32 v56, 0x90, v128
	v_and_b32_e32 v56, s22, v56
	v_add_u32_e32 v58, 0x91, v128
	v_lshlrev_b32_e32 v66, 7, v56
	v_and_b32_e32 v58, s22, v58
	v_add_u32_e32 v60, 0x92, v128
	v_or_b32_e32 v56, v66, v129
	v_lshlrev_b32_e32 v67, 7, v58
	v_and_b32_e32 v60, s22, v60
	v_add_u32_e32 v62, 0x93, v128
	v_lshlrev_b32_e32 v152, 3, v56
	v_or_b32_e32 v58, v67, v129
	v_lshlrev_b32_e32 v68, 7, v60
	v_and_b32_e32 v62, s22, v62
	v_lshl_add_u64 v[56:57], s[2:3], 0, v[152:153]
	v_lshlrev_b32_e32 v152, 3, v58
	v_or_b32_e32 v60, v68, v129
	v_lshlrev_b32_e32 v69, 7, v62
	v_lshl_add_u64 v[58:59], s[2:3], 0, v[152:153]
	v_lshlrev_b32_e32 v152, 3, v60
	v_or_b32_e32 v62, v69, v129
	s_waitcnt vmcnt(11)
	v_mov_b32_e32 v56, v202
	v_mov_b32_e32 v57, v203
	s_nop 0
	s_waitcnt vmcnt(10)
	v_mov_b32_e32 v58, v204
	v_mov_b32_e32 v59, v205
	v_lshl_add_u64 v[60:61], s[2:3], 0, v[152:153]
	v_lshlrev_b32_e32 v152, 3, v62
	s_waitcnt vmcnt(9)
	v_mov_b32_e32 v60, v206
	v_mov_b32_e32 v61, v207
	v_lshl_add_u64 v[62:63], s[2:3], 0, v[152:153]
	s_waitcnt vmcnt(8)
	v_mov_b32_e32 v62, v208
	v_mov_b32_e32 v63, v209
	s_waitcnt lgkmcnt(0)
	v_mul_f32_e32 v70, v52, v57
	v_mul_f32_e32 v57, v48, v57
	v_mul_f32_e32 v71, v53, v59
	v_mul_f32_e32 v59, v49, v59
	v_fma_mixlo_f16 v48, v48, v56, -v70
	v_fma_mixlo_f16 v52, v52, v56, v57
	v_mul_f32_e32 v56, v54, v61
	v_mul_f32_e32 v57, v50, v61
	v_fma_mixlo_f16 v49, v49, v58, -v71
	ds_write_b16 v64, v48 offset:8448
	v_fma_mixlo_f16 v48, v53, v58, v59
	ds_write_b16 v64, v52 offset:8480
	v_mul_f32_e32 v52, v55, v63
	v_mul_f32_e32 v53, v51, v63
	v_fma_mixlo_f16 v50, v50, v60, -v56
	ds_write_b16 v64, v49 offset:8976
	v_fma_mixlo_f16 v49, v54, v60, v57
	ds_write_b16 v64, v48 offset:9008
	v_fma_mixlo_f16 v48, v51, v62, -v52
	ds_write_b16 v64, v50 offset:9504
	v_fma_mixlo_f16 v50, v55, v62, v53
	ds_write_b16 v64, v49 offset:9536
	ds_write_b16 v64, v48 offset:10032
	ds_write_b16 v64, v50 offset:10064
	v_add_u32_e32 v48, 0xa0, v128
	v_and_b32_e32 v48, s22, v48
	v_add_u32_e32 v50, 0xa1, v128
	v_lshlrev_b32_e32 v56, 7, v48
	v_and_b32_e32 v50, s22, v50
	v_add_u32_e32 v52, 0xa2, v128
	v_or_b32_e32 v48, v56, v129
	v_lshlrev_b32_e32 v57, 7, v50
	v_and_b32_e32 v52, s22, v52
	v_add_u32_e32 v54, 0xa3, v128
	v_lshlrev_b32_e32 v152, 3, v48
	v_or_b32_e32 v50, v57, v129
	v_lshlrev_b32_e32 v58, 7, v52
	v_and_b32_e32 v54, s22, v54
	v_lshl_add_u64 v[48:49], s[2:3], 0, v[152:153]
	v_lshlrev_b32_e32 v152, 3, v50
	v_or_b32_e32 v52, v58, v129
	v_lshlrev_b32_e32 v59, 7, v54
	v_lshl_add_u64 v[50:51], s[2:3], 0, v[152:153]
	v_lshlrev_b32_e32 v152, 3, v52
	v_or_b32_e32 v54, v59, v129
	v_add_u32_e32 v227, 0x20200, v226
	global_load_dwordx2 v[194:195], v227, s[2:3]
	global_load_dwordx2 v[196:197], v227, s[2:3] offset:1024
	global_load_dwordx2 v[198:199], v227, s[2:3] offset:2048
	global_load_dwordx2 v[200:201], v227, s[2:3] offset:3072
	v_add_u32_e32 v227, 0x24200, v226
	global_load_dwordx2 v[202:203], v227, s[2:3]
	global_load_dwordx2 v[204:205], v227, s[2:3] offset:1024
	global_load_dwordx2 v[206:207], v227, s[2:3] offset:2048
	global_load_dwordx2 v[208:209], v227, s[2:3] offset:3072
	s_waitcnt vmcnt(15)
; #define FOR_R _Pragma("unroll") for (int r = 0; r < 4; ++r)
; #define FOR_AI _Pragma("unroll") for (int ai = 0; ai < 2; ++ai)
; #define FOR_BJ _Pragma("unroll") for (int bj = 0; bj < 2; ++bj)
; #define FOR_M4 _Pragma("unroll") for (int m = 0; m < 4; ++m)
; template <bool ISK>
; __device__ void job_qk_g(const P& p, int l, int g, int ct2, int rt, HALF* sm) {
;     ...
;   FOR_AI FOR_BJ {
;     FOR_M4 {
;       const int row0 = ai * 128 + wr * 64 + m * 16 + fq * 4;
;       const int lc = bj * 128 + wc * 32 + fr;
;       const int j = (bj * 4 + wc) * 16 + fr;
;       f4 o1, o2;
;       FOR_R {
;         const int sp = (rt * 256 + row0 + r) & (S - 1);
;         const float2 cs = rope[sp * 128 + j];
;         const float a = acc[ai][bj][m][0][r], b = acc[ai][bj][m][1][r];
;         o1[r] = a * cs.x - b * cs.y;
;         o2[r] = a * cs.y + b * cs.x;
;       }
;       acc[ai][bj][m][0] = o1;
;       acc[ai][bj][m][1] = o2;
;       stage2_rm(sm, row0, lc, to_h4(o1));
;       stage2_rm(sm, row0, lc + 16, to_h4(o2));
;       __builtin_amdgcn_sched_barrier(0);
;     }
;   }
	v_mov_b32_e32 v48, v210
	v_mov_b32_e32 v49, v211
	s_nop 0
	s_waitcnt vmcnt(14)
	v_mov_b32_e32 v50, v212
	v_mov_b32_e32 v51, v213
	v_lshl_add_u64 v[52:53], s[2:3], 0, v[152:153]
	v_lshlrev_b32_e32 v152, 3, v54
	s_waitcnt vmcnt(13)
	v_mov_b32_e32 v52, v214
	v_mov_b32_e32 v53, v215
	v_lshl_add_u64 v[54:55], s[2:3], 0, v[152:153]
	s_waitcnt vmcnt(12)
	v_mov_b32_e32 v54, v216
	v_mov_b32_e32 v55, v217
	s_waitcnt lgkmcnt(0)
	v_mul_f32_e32 v60, v44, v49
	v_mul_f32_e32 v49, v40, v49
	v_mul_f32_e32 v61, v45, v51
	v_mul_f32_e32 v51, v41, v51
	v_fma_mixlo_f16 v40, v40, v48, -v60
	v_fma_mixlo_f16 v44, v44, v48, v49
	v_mul_f32_e32 v48, v46, v53
	v_mul_f32_e32 v49, v42, v53
	v_fma_mixlo_f16 v41, v41, v50, -v61
	ds_write_b16 v64, v40 offset:16896
	v_fma_mixlo_f16 v40, v45, v50, v51
	ds_write_b16 v64, v44 offset:16928
	v_mul_f32_e32 v44, v47, v55
	v_mul_f32_e32 v45, v43, v55
	v_fma_mixlo_f16 v42, v42, v52, -v48
	ds_write_b16 v64, v41 offset:17424
	v_fma_mixlo_f16 v41, v46, v52, v49
	ds_write_b16 v64, v40 offset:17456
	v_fma_mixlo_f16 v40, v43, v54, -v44
	ds_write_b16 v64, v42 offset:17952
	v_fma_mixlo_f16 v42, v47, v54, v45
	ds_write_b16 v64, v41 offset:17984
	ds_write_b16 v64, v40 offset:18480
	ds_write_b16 v64, v42 offset:18512
	v_add_u32_e32 v42, 0xb1, v128
	v_or_b32_e32 v40, v65, v129
	v_and_b32_e32 v42, s22, v42
	v_add_u32_e32 v44, 0xb2, v128
	v_lshlrev_b32_e32 v152, 3, v40
	v_lshlrev_b32_e32 v48, 7, v42
	v_and_b32_e32 v44, s22, v44
	v_add_u32_e32 v46, 0xb3, v128
	v_lshl_add_u64 v[40:41], s[2:3], 0, v[152:153]
	v_or_b32_e32 v42, v48, v129
	v_lshlrev_b32_e32 v49, 7, v44
	v_and_b32_e32 v46, s22, v46
	s_waitcnt vmcnt(11)
	v_mov_b32_e32 v40, v218
	v_mov_b32_e32 v41, v219
	v_lshlrev_b32_e32 v152, 3, v42
	v_or_b32_e32 v44, v49, v129
	v_lshlrev_b32_e32 v50, 7, v46
	v_lshl_add_u64 v[42:43], s[2:3], 0, v[152:153]
	v_lshlrev_b32_e32 v152, 3, v44
	v_or_b32_e32 v46, v50, v129
	v_lshl_add_u64 v[44:45], s[2:3], 0, v[152:153]
	v_lshlrev_b32_e32 v152, 3, v46
	s_waitcnt vmcnt(10)
	v_mov_b32_e32 v42, v220
	v_mov_b32_e32 v43, v221
	s_nop 0
	s_waitcnt vmcnt(9)
	v_mov_b32_e32 v44, v222
	v_mov_b32_e32 v45, v223
	v_lshl_add_u64 v[46:47], s[2:3], 0, v[152:153]
	s_waitcnt vmcnt(8)
	v_mov_b32_e32 v46, v224
	v_mov_b32_e32 v47, v225
	s_waitcnt lgkmcnt(0)
	v_mul_f32_e32 v51, v36, v41
	v_mul_f32_e32 v41, v32, v41
	v_fma_mixlo_f16 v32, v32, v40, -v51
	v_fma_mixlo_f16 v36, v36, v40, v41
	ds_write_b16 v64, v32 offset:25344
	ds_write_b16 v64, v36 offset:25376
	v_mul_f32_e32 v32, v37, v43
	v_mul_f32_e32 v36, v33, v43
	v_mul_f32_e32 v40, v38, v45
	v_mul_f32_e32 v41, v34, v45
	v_fma_mixlo_f16 v32, v33, v42, -v32
	v_fma_mixlo_f16 v33, v37, v42, v36
	v_mul_f32_e32 v36, v39, v47
	v_mul_f32_e32 v37, v35, v47
	v_fma_mixlo_f16 v34, v34, v44, -v40
	ds_write_b16 v64, v32 offset:25872
	v_fma_mixlo_f16 v32, v38, v44, v41
	ds_write_b16 v64, v33 offset:25904
	v_fma_mixlo_f16 v33, v35, v46, -v36
	ds_write_b16 v64, v34 offset:26400
	v_fma_mixlo_f16 v34, v39, v46, v37
	ds_write_b16 v64, v32 offset:26432
	ds_write_b16 v64, v33 offset:26928
	ds_write_b16 v64, v34 offset:26960
	v_or_b32_e32 v32, v74, v96
	v_lshlrev_b32_e32 v152, 3, v32
	v_or_b32_e32 v34, v75, v96
	v_lshl_add_u64 v[32:33], s[2:3], 0, v[152:153]
	v_lshlrev_b32_e32 v152, 3, v34
	v_or_b32_e32 v36, v76, v96
	v_lshl_add_u64 v[34:35], s[2:3], 0, v[152:153]
	v_lshlrev_b32_e32 v152, 3, v36
	v_or_b32_e32 v38, v77, v96
	v_add_u32_e32 v227, 0x28200, v226
	global_load_dwordx2 v[210:211], v227, s[2:3]
	global_load_dwordx2 v[212:213], v227, s[2:3] offset:1024
	global_load_dwordx2 v[214:215], v227, s[2:3] offset:2048
	global_load_dwordx2 v[216:217], v227, s[2:3] offset:3072
	v_add_u32_e32 v227, 0x2c200, v226
	global_load_dwordx2 v[218:219], v227, s[2:3]
	global_load_dwordx2 v[220:221], v227, s[2:3] offset:1024
	global_load_dwordx2 v[222:223], v227, s[2:3] offset:2048
	global_load_dwordx2 v[224:225], v227, s[2:3] offset:3072
	s_waitcnt vmcnt(15)
	v_mov_b32_e32 v32, v194
	v_mov_b32_e32 v33, v195
	v_lshl_add_u64 v[36:37], s[2:3], 0, v[152:153]
	s_waitcnt vmcnt(14)
	v_mov_b32_e32 v34, v196
	v_mov_b32_e32 v35, v197
	v_lshlrev_b32_e32 v152, 3, v38
	s_waitcnt vmcnt(13)
	v_mov_b32_e32 v36, v198
	v_mov_b32_e32 v37, v199
	v_lshl_add_u64 v[38:39], s[2:3], 0, v[152:153]
	s_waitcnt vmcnt(12)
	v_mov_b32_e32 v38, v200
	v_mov_b32_e32 v39, v201
	s_waitcnt lgkmcnt(0)
	v_mul_f32_e32 v40, v28, v33
	v_mul_f32_e32 v33, v24, v33
	v_mul_f32_e32 v41, v29, v35
	v_mul_f32_e32 v35, v25, v35
	v_fma_mixlo_f16 v24, v24, v32, -v40
	v_fma_mixlo_f16 v28, v28, v32, v33
	v_mul_f32_e32 v32, v30, v37
	v_mul_f32_e32 v33, v26, v37
	v_fma_mixlo_f16 v25, v25, v34, -v41
	ds_write_b16 v64, v24 offset:256
	v_fma_mixlo_f16 v24, v29, v34, v35
	ds_write_b16 v64, v28 offset:288
	v_mul_f32_e32 v28, v31, v39
	v_mul_f32_e32 v29, v27, v39
	v_fma_mixlo_f16 v26, v26, v36, -v32
	ds_write_b16 v64, v25 offset:784
	v_fma_mixlo_f16 v25, v30, v36, v33
	ds_write_b16 v64, v24 offset:816
	v_fma_mixlo_f16 v24, v27, v38, -v28
	ds_write_b16 v64, v26 offset:1312
	v_fma_mixlo_f16 v26, v31, v38, v29
	ds_write_b16 v64, v25 offset:1344
	ds_write_b16 v64, v24 offset:1840
	ds_write_b16 v64, v26 offset:1872
	v_or_b32_e32 v24, v66, v96
	v_lshlrev_b32_e32 v152, 3, v24
	v_or_b32_e32 v26, v67, v96
	v_lshl_add_u64 v[24:25], s[2:3], 0, v[152:153]
	v_lshlrev_b32_e32 v152, 3, v26
	v_or_b32_e32 v28, v68, v96
	v_lshl_add_u64 v[26:27], s[2:3], 0, v[152:153]
	v_lshlrev_b32_e32 v152, 3, v28
	v_or_b32_e32 v30, v69, v96
	s_waitcnt vmcnt(11)
; #define FOR_R _Pragma("unroll") for (int r = 0; r < 4; ++r)
; #define FOR_AI _Pragma("unroll") for (int ai = 0; ai < 2; ++ai)
; #define FOR_BJ _Pragma("unroll") for (int bj = 0; bj < 2; ++bj)
; #define FOR_M4 _Pragma("unroll") for (int m = 0; m < 4; ++m)
; template <bool ISK>
; __device__ void job_qk_g(const P& p, int l, int g, int ct2, int rt, HALF* sm) {
;     ...
;   FOR_AI FOR_BJ {
;     FOR_M4 {
;       const int row0 = ai * 128 + wr * 64 + m * 16 + fq * 4;
;       const int lc = bj * 128 + wc * 32 + fr;
;       const int j = (bj * 4 + wc) * 16 + fr;
;       f4 o1, o2;
;       FOR_R {
;         const int sp = (rt * 256 + row0 + r) & (S - 1);
;         const float2 cs = rope[sp * 128 + j];
;         const float a = acc[ai][bj][m][0][r], b = acc[ai][bj][m][1][r];
;         o1[r] = a * cs.x - b * cs.y;
;         o2[r] = a * cs.y + b * cs.x;
;       }
;       acc[ai][bj][m][0] = o1;
;       acc[ai][bj][m][1] = o2;
;       stage2_rm(sm, row0, lc, to_h4(o1));
;       stage2_rm(sm, row0, lc + 16, to_h4(o2));
;       __builtin_amdgcn_sched_barrier(0);
;     }
;   }
;   __syncthreads();
;   HALF* dst = (HALF*)(ws + (ISK ? G_K : G_Q));
;   flush2<32>(sm, 256, [&](int row, int ch) { return dst + (size_t)(rt * 256 + row) * 1024 + hh * 256 + ch * 8; });
	v_mov_b32_e32 v24, v202
	v_mov_b32_e32 v25, v203
	v_lshl_add_u64 v[28:29], s[2:3], 0, v[152:153]
	s_waitcnt vmcnt(10)
	v_mov_b32_e32 v26, v204
	v_mov_b32_e32 v27, v205
	v_lshlrev_b32_e32 v152, 3, v30
	s_waitcnt vmcnt(9)
	v_mov_b32_e32 v28, v206
	v_mov_b32_e32 v29, v207
	v_lshl_add_u64 v[30:31], s[2:3], 0, v[152:153]
	s_waitcnt vmcnt(8)
	v_mov_b32_e32 v30, v208
	v_mov_b32_e32 v31, v209
	s_waitcnt lgkmcnt(0)
	v_mul_f32_e32 v32, v20, v25
	v_mul_f32_e32 v25, v16, v25
	v_mul_f32_e32 v33, v21, v27
	v_mul_f32_e32 v27, v17, v27
	v_fma_mixlo_f16 v16, v16, v24, -v32
	v_fma_mixlo_f16 v20, v20, v24, v25
	v_mul_f32_e32 v24, v22, v29
	v_mul_f32_e32 v25, v18, v29
	v_fma_mixlo_f16 v17, v17, v26, -v33
	ds_write_b16 v64, v16 offset:8704
	v_fma_mixlo_f16 v16, v21, v26, v27
	ds_write_b16 v64, v20 offset:8736
	v_mul_f32_e32 v20, v23, v31
	v_mul_f32_e32 v21, v19, v31
	v_fma_mixlo_f16 v18, v18, v28, -v24
	ds_write_b16 v64, v17 offset:9232
	v_fma_mixlo_f16 v17, v22, v28, v25
	ds_write_b16 v64, v16 offset:9264
	v_fma_mixlo_f16 v16, v19, v30, -v20
	ds_write_b16 v64, v18 offset:9760
	v_fma_mixlo_f16 v18, v23, v30, v21
	ds_write_b16 v64, v17 offset:9792
	ds_write_b16 v64, v16 offset:10288
	ds_write_b16 v64, v18 offset:10320
	v_or_b32_e32 v16, v56, v96
	v_lshlrev_b32_e32 v152, 3, v16
	v_or_b32_e32 v18, v57, v96
	v_lshl_add_u64 v[16:17], s[2:3], 0, v[152:153]
	v_lshlrev_b32_e32 v152, 3, v18
	v_or_b32_e32 v20, v58, v96
	v_lshl_add_u64 v[18:19], s[2:3], 0, v[152:153]
	v_lshlrev_b32_e32 v152, 3, v20
	v_or_b32_e32 v22, v59, v96
	v_lshl_add_u64 v[20:21], s[2:3], 0, v[152:153]
	v_lshlrev_b32_e32 v152, 3, v22
	s_waitcnt vmcnt(7)
	v_mov_b32_e32 v16, v210
	v_mov_b32_e32 v17, v211
	v_lshl_add_u64 v[22:23], s[2:3], 0, v[152:153]
	s_waitcnt vmcnt(6)
	v_mov_b32_e32 v18, v212
	v_mov_b32_e32 v19, v213
	s_nop 0
	s_waitcnt vmcnt(5)
	v_mov_b32_e32 v20, v214
	v_mov_b32_e32 v21, v215
	s_nop 0
	s_waitcnt vmcnt(4)
	v_mov_b32_e32 v22, v216
	v_mov_b32_e32 v23, v217
	s_waitcnt lgkmcnt(0)
	v_mul_f32_e32 v24, v8, v17
	v_mul_f32_e32 v17, v12, v17
	v_mul_f32_e32 v25, v9, v19
	v_mul_f32_e32 v19, v13, v19
	v_mul_f32_e32 v26, v10, v21
	v_mul_f32_e32 v21, v14, v21
	v_mul_f32_e32 v27, v11, v23
	v_mul_f32_e32 v23, v15, v23
	v_fma_mixlo_f16 v12, v12, v16, -v24
	v_fma_mixlo_f16 v8, v8, v16, v17
	v_fma_mixlo_f16 v13, v13, v18, -v25
	v_fma_mixlo_f16 v14, v14, v20, -v26
	v_fma_mixlo_f16 v15, v15, v22, -v27
	ds_write_b16 v64, v12 offset:17152
	ds_write_b16 v64, v13 offset:17680
	ds_write_b16 v64, v14 offset:18208
	ds_write_b16 v64, v15 offset:18736
	v_fma_mixlo_f16 v9, v9, v18, v19
	v_fma_mixlo_f16 v10, v10, v20, v21
	v_fma_mixlo_f16 v11, v11, v22, v23
	ds_write_b16 v64, v8 offset:17184
	ds_write_b16 v64, v9 offset:17712
	ds_write_b16 v64, v10 offset:18240
	ds_write_b16 v64, v11 offset:18768
	v_or_b32_e32 v8, v65, v96
	v_lshlrev_b32_e32 v152, 3, v8
	v_or_b32_e32 v10, v48, v96
	v_lshl_add_u64 v[8:9], s[2:3], 0, v[152:153]
	v_lshlrev_b32_e32 v152, 3, v10
	v_or_b32_e32 v12, v49, v96
	v_lshl_add_u64 v[10:11], s[2:3], 0, v[152:153]
	v_lshlrev_b32_e32 v152, 3, v12
	v_or_b32_e32 v14, v50, v96
	v_lshl_add_u64 v[12:13], s[2:3], 0, v[152:153]
	v_lshlrev_b32_e32 v152, 3, v14
	s_waitcnt vmcnt(3)
	v_mov_b32_e32 v8, v218
	v_mov_b32_e32 v9, v219
	v_lshl_add_u64 v[14:15], s[2:3], 0, v[152:153]
	s_waitcnt vmcnt(2)
	v_mov_b32_e32 v10, v220
	v_mov_b32_e32 v11, v221
	s_nop 0
	s_waitcnt vmcnt(1)
	v_mov_b32_e32 v12, v222
	v_mov_b32_e32 v13, v223
	s_nop 0
	s_waitcnt vmcnt(0)
	v_mov_b32_e32 v14, v224
	v_mov_b32_e32 v15, v225
	s_waitcnt lgkmcnt(0)
	v_mul_f32_e32 v16, v0, v9
	v_mul_f32_e32 v9, v4, v9
	v_mul_f32_e32 v17, v1, v11
	v_mul_f32_e32 v11, v5, v11
	v_mul_f32_e32 v18, v2, v13
	v_mul_f32_e32 v13, v6, v13
	v_mul_f32_e32 v19, v3, v15
	v_mul_f32_e32 v15, v7, v15
	v_fma_mixlo_f16 v4, v4, v8, -v16
	v_fma_mixlo_f16 v0, v0, v8, v9
	v_fma_mixlo_f16 v5, v5, v10, -v17
	v_fma_mixlo_f16 v6, v6, v12, -v18
	v_fma_mixlo_f16 v7, v7, v14, -v19
	ds_write_b16 v64, v4 offset:25600
	ds_write_b16 v64, v5 offset:26128
	ds_write_b16 v64, v6 offset:26656
	ds_write_b16 v64, v7 offset:27184
	v_fma_mixlo_f16 v1, v1, v10, v11
	v_fma_mixlo_f16 v2, v2, v12, v13
	v_fma_mixlo_f16 v3, v3, v14, v15
	ds_write_b16 v64, v0 offset:25632
	ds_write_b16 v64, v1 offset:26160
	ds_write_b16 v64, v2 offset:26688
	ds_write_b16 v64, v3 offset:27216
	v_mov_b32_e32 v0, v155
	s_movk_i32 s2, 0x2000
	s_waitcnt lgkmcnt(0)
	s_barrier
	s_nop 0
	v_cmp_gt_i32_e32 vcc, s2, v0
	s_and_saveexec_b64 s[2:3], vcc
	s_cbranch_execz .LBB0_204
	s_lshl_b32 s6, s8, 9
	s_and_b32 s6, s6, 0x600
	v_max_i32_e32 v1, 0x1e00, v0
	s_add_u32 s0, s0, s6
	v_sub_u32_e32 v1, v1, v0
	s_addc_u32 s1, s1, 0
	v_add_u32_e32 v1, 0x1ff, v1
	s_add_u32 s0, s0, 0x19eb0000
	v_and_b32_e32 v2, 0x600, v1
	s_movk_i32 s6, 0x600
	s_addc_u32 s1, s1, 0
	v_cmp_ne_u32_e32 vcc, s6, v2
	s_and_saveexec_b64 s[6:7], vcc
	s_cbranch_execz .LBB0_201
	v_lshrrev_b32_e32 v2, 9, v1
	v_add_u32_e32 v2, 1, v2
	v_and_b32_e32 v4, 3, v2
	v_lshl_add_u32 v2, v0, 4, 0
	v_lshlrev_b32_e32 v3, 3, v0
	v_sub_u32_e32 v4, 0, v4
	s_mov_b64 s[12:13], 0

; #define FOR_R _Pragma("unroll") for (int r = 0; r < 4; ++r)
; #define FOR_AI _Pragma("unroll") for (int ai = 0; ai < 2; ++ai)
; #define FOR_BJ _Pragma("unroll") for (int bj = 0; bj < 2; ++bj)
; #define FOR_M4 _Pragma("unroll") for (int m = 0; m < 4; ++m)
; template <bool ISK>
; __device__ void job_qk_g(const P& p, int l, int g, int ct2, int rt, HALF* sm) {
;     ...
;   FOR_AI FOR_BJ {
;     FOR_M4 {
;       const int row0 = ai * 128 + wr * 64 + m * 16 + fq * 4;
;       const int lc = bj * 128 + wc * 32 + fr;
;       const int j = (bj * 4 + wc) * 16 + fr;
;       f4 o1, o2;
;       FOR_R {
;         const int sp = (rt * 256 + row0 + r) & (S - 1);
;         const float2 cs = rope[sp * 128 + j];
;         const float a = acc[ai][bj][m][0][r], b = acc[ai][bj][m][1][r];
;         o1[r] = a * cs.x - b * cs.y;
;         o2[r] = a * cs.y + b * cs.x;
;       }
;       acc[ai][bj][m][0] = o1;
;       acc[ai][bj][m][1] = o2;
;       stage2_rm(sm, row0, lc, to_h4(o1));
;       stage2_rm(sm, row0, lc + 16, to_h4(o2));
;       __builtin_amdgcn_sched_barrier(0);
;     }
;   }
.LBB0_212:
	s_or_b64 exec, exec, s[2:3]
	v_bfe_u32 v128, v130, 6, 2
	v_and_b32_e32 v129, 15, v130
	v_ashrrev_i32_e32 v131, 2, v130
	v_lshrrev_b32_e32 v130, 2, v130
	v_and_b32_e32 v130, 12, v130
	s_movk_i32 s6, 0xffc0
	v_and_or_b32 v133, v131, s6, v130
	v_or_b32_e32 v132, 48, v133
	v_add_u32_e32 v142, s21, v132
	v_add_u32_e32 v139, s21, v133
	v_and_b32_e32 v130, s22, v142
	v_lshl_or_b32 v134, v128, 5, v129
	v_lshl_or_b32 v141, v128, 4, v129
	v_and_b32_e32 v128, s22, v139
	s_and_b32 s44, s8, 3
	v_lshlrev_b32_e32 v135, 7, v130
	v_lshlrev_b32_e32 v138, 7, v128
	v_bitop3_b32 v130, v139, s22, 1 bitop3:0xc8
	s_add_u32 s2, s0, 0x3680000
	v_or_b32_e32 v128, v138, v141
	v_lshlrev_b32_e32 v140, 7, v130
	s_addc_u32 s3, s1, 0
	v_lshlrev_b32_e32 v152, 3, v128
	v_or_b32_e32 v130, v140, v141
	v_lshl_add_u64 v[128:129], s[2:3], 0, v[152:153]
	v_lshlrev_b32_e32 v152, 3, v130
	s_waitcnt vmcnt(0)
	s_barrier
	v_lshl_add_u64 v[130:131], s[2:3], 0, v[152:153]
	v_lshrrev_b32_e32 v226, 8, v155
	v_lshlrev_b32_e32 v226, 6, v226
	v_bfe_u32 v227, v155, 4, 2
	v_lshl_or_b32 v226, v227, 2, v226
	v_add_u32_e32 v226, s21, v226
	v_and_b32_e32 v226, s22, v226
	v_bfe_u32 v227, v155, 6, 2
	v_lshlrev_b32_e32 v227, 4, v227
	v_and_or_b32 v227, v155, 15, v227
	v_lshl_or_b32 v226, v226, 7, v227
	v_lshlrev_b32_e32 v226, 3, v226
	v_mov_b32_e32 v227, v226
	global_load_dwordx2 v[194:195], v227, s[2:3]
	global_load_dwordx2 v[196:197], v227, s[2:3] offset:1024
	global_load_dwordx2 v[198:199], v227, s[2:3] offset:2048
	global_load_dwordx2 v[200:201], v227, s[2:3] offset:3072
	v_add_u32_e32 v227, 0x4000, v226
	global_load_dwordx2 v[202:203], v227, s[2:3]
	global_load_dwordx2 v[204:205], v227, s[2:3] offset:1024
	global_load_dwordx2 v[206:207], v227, s[2:3] offset:2048
	global_load_dwordx2 v[208:209], v227, s[2:3] offset:3072
	v_add_u32_e32 v227, 0x8000, v226
	global_load_dwordx2 v[210:211], v227, s[2:3]
	global_load_dwordx2 v[212:213], v227, s[2:3] offset:1024
	global_load_dwordx2 v[214:215], v227, s[2:3] offset:2048
	global_load_dwordx2 v[216:217], v227, s[2:3] offset:3072
	v_add_u32_e32 v227, 0xc000, v226
	global_load_dwordx2 v[218:219], v227, s[2:3]
	global_load_dwordx2 v[220:221], v227, s[2:3] offset:1024
	global_load_dwordx2 v[222:223], v227, s[2:3] offset:2048
	global_load_dwordx2 v[224:225], v227, s[2:3] offset:3072
	s_waitcnt vmcnt(15)
	v_mov_b32_e32 v136, v194
	v_mov_b32_e32 v137, v195
	s_nop 0
	s_waitcnt vmcnt(14)
	v_mov_b32_e32 v128, v196
	v_mov_b32_e32 v129, v197
	s_waitcnt lgkmcnt(0)
	v_mov_b32_e32 v130, v137
	v_mov_b32_e32 v131, v129
	v_pk_mul_f32 v[144:145], v[120:121], v[130:131]
	v_mov_b32_e32 v137, v128
	v_pk_fma_f32 v[128:129], v[124:125], v[136:137], v[144:145]
	v_pk_mul_f32 v[124:125], v[124:125], v[130:131]
	v_bitop3_b32 v130, v139, s22, 3 bitop3:0xc8
	v_pk_fma_f32 v[120:121], v[120:121], v[136:137], v[124:125] neg_lo:[0,0,1] neg_hi:[0,0,1]
	v_bitop3_b32 v124, v139, s22, 2 bitop3:0xc8
	v_lshlrev_b32_e32 v143, 7, v124
	v_or_b32_e32 v124, v143, v141
	v_lshlrev_b32_e32 v144, 7, v130
	v_lshlrev_b32_e32 v152, 3, v124
	v_or_b32_e32 v130, v144, v141
	v_lshl_add_u64 v[124:125], s[2:3], 0, v[152:153]
	v_lshlrev_b32_e32 v152, 3, v130
	v_lshl_add_u64 v[130:131], s[2:3], 0, v[152:153]
	s_waitcnt vmcnt(13)
	v_mov_b32_e32 v136, v198
	v_mov_b32_e32 v137, v199
	s_nop 0
	s_waitcnt vmcnt(12)
	v_mov_b32_e32 v124, v200
	v_mov_b32_e32 v125, v201
	s_waitcnt lgkmcnt(0)
	v_mov_b32_e32 v130, v137
	v_mov_b32_e32 v131, v125
	v_pk_mul_f32 v[146:147], v[122:123], v[130:131]
	v_mov_b32_e32 v137, v124
	v_pk_fma_f32 v[124:125], v[126:127], v[136:137], v[146:147]
	v_pk_mul_f32 v[126:127], v[126:127], v[130:131]
	s_nop 0
	v_pk_fma_f32 v[126:127], v[122:123], v[136:137], v[126:127] neg_lo:[0,0,1] neg_hi:[0,0,1]
	v_cvt_f16_f32_e32 v122, v120
	v_cvt_f16_f32_e32 v123, v121
	v_cvt_f16_f32_e32 v130, v126
	v_mul_lo_u32 v136, v133, s64
	v_lshlrev_b32_e32 v137, 1, v134
	v_cvt_f16_f32_e32 v131, v127
	v_add3_u32 v139, 0, v136, v137
	ds_write_b16 v139, v122
	ds_write_b16 v139, v123 offset:528
	ds_write_b16 v139, v130 offset:1056
	ds_write_b16 v139, v131 offset:1584
	v_cvt_f16_f32_e32 v122, v128
	v_cvt_f16_f32_e32 v123, v129
	v_cvt_f16_f32_e32 v130, v124
	v_cvt_f16_f32_e32 v131, v125
	ds_write_b16 v139, v122 offset:32
	ds_write_b16 v139, v123 offset:560
	ds_write_b16 v139, v130 offset:1088
	ds_write_b16 v139, v131 offset:1616
	v_or_b32_e32 v137, 16, v133
	v_add_u32_e32 v136, s21, v137
	v_and_b32_e32 v122, s22, v136
	v_lshlrev_b32_e32 v145, 7, v122
	v_bitop3_b32 v130, v136, s22, 1 bitop3:0xc8
	v_or_b32_e32 v122, v145, v141
	v_lshlrev_b32_e32 v146, 7, v130
	v_lshlrev_b32_e32 v152, 3, v122
	v_or_b32_e32 v130, v146, v141
	v_lshl_add_u64 v[122:123], s[2:3], 0, v[152:153]
	v_lshlrev_b32_e32 v152, 3, v130
	v_lshl_add_u64 v[130:131], s[2:3], 0, v[152:153]
	s_waitcnt vmcnt(11)
	v_mov_b32_e32 v148, v202
	v_mov_b32_e32 v149, v203
	s_nop 0
	s_waitcnt vmcnt(10)
	v_mov_b32_e32 v122, v204
	v_mov_b32_e32 v123, v205
	s_waitcnt lgkmcnt(0)
	v_mov_b32_e32 v130, v149
	v_mov_b32_e32 v131, v123
	v_pk_mul_f32 v[150:151], v[112:113], v[130:131]
	v_mov_b32_e32 v149, v122
	v_pk_fma_f32 v[122:123], v[116:117], v[148:149], v[150:151]
	v_pk_mul_f32 v[116:117], v[116:117], v[130:131]
	v_bitop3_b32 v130, v136, s22, 3 bitop3:0xc8
	v_pk_fma_f32 v[116:117], v[112:113], v[148:149], v[116:117] neg_lo:[0,0,1] neg_hi:[0,0,1]
	v_bitop3_b32 v112, v136, s22, 2 bitop3:0xc8
	v_lshlrev_b32_e32 v147, 7, v112
	v_or_b32_e32 v112, v147, v141
	v_lshlrev_b32_e32 v148, 7, v130
	v_lshlrev_b32_e32 v152, 3, v112
	v_or_b32_e32 v130, v148, v141
	v_lshl_add_u64 v[112:113], s[2:3], 0, v[152:153]
	v_lshlrev_b32_e32 v152, 3, v130
	v_lshl_add_u64 v[130:131], s[2:3], 0, v[152:153]
	s_waitcnt vmcnt(9)
; #define FOR_R _Pragma("unroll") for (int r = 0; r < 4; ++r)
; #define FOR_AI _Pragma("unroll") for (int ai = 0; ai < 2; ++ai)
; #define FOR_BJ _Pragma("unroll") for (int bj = 0; bj < 2; ++bj)
; #define FOR_M4 _Pragma("unroll") for (int m = 0; m < 4; ++m)
; template <bool ISK>
; __device__ void job_qk_g(const P& p, int l, int g, int ct2, int rt, HALF* sm) {
;     ...
;   FOR_AI FOR_BJ {
;     FOR_M4 {
;       const int row0 = ai * 128 + wr * 64 + m * 16 + fq * 4;
;       const int lc = bj * 128 + wc * 32 + fr;
;       const int j = (bj * 4 + wc) * 16 + fr;
;       f4 o1, o2;
;       FOR_R {
;         const int sp = (rt * 256 + row0 + r) & (S - 1);
;         const float2 cs = rope[sp * 128 + j];
;         const float a = acc[ai][bj][m][0][r], b = acc[ai][bj][m][1][r];
;         o1[r] = a * cs.x - b * cs.y;
;         o2[r] = a * cs.y + b * cs.x;
;       }
;       acc[ai][bj][m][0] = o1;
;       acc[ai][bj][m][1] = o2;
;       stage2_rm(sm, row0, lc, to_h4(o1));
;       stage2_rm(sm, row0, lc + 16, to_h4(o2));
;       __builtin_amdgcn_sched_barrier(0);
;     }
;   }
	v_mov_b32_e32 v112, v206
	v_mov_b32_e32 v113, v207
	s_nop 0
	s_waitcnt vmcnt(8)
	v_mov_b32_e32 v130, v208
	v_mov_b32_e32 v131, v209
	s_waitcnt lgkmcnt(0)
	v_mov_b32_e32 v150, v113
	v_mov_b32_e32 v151, v131
	v_pk_mul_f32 v[158:159], v[114:115], v[150:151]
	v_mov_b32_e32 v113, v130
	v_pk_fma_f32 v[130:131], v[118:119], v[112:113], v[158:159]
	v_pk_mul_f32 v[118:119], v[118:119], v[150:151]
	s_nop 0
	v_pk_fma_f32 v[118:119], v[114:115], v[112:113], v[118:119] neg_lo:[0,0,1] neg_hi:[0,0,1]
	v_cvt_f16_f32_e32 v112, v116
	v_cvt_f16_f32_e32 v113, v117
	v_cvt_f16_f32_e32 v114, v118
	v_cvt_f16_f32_e32 v115, v119
	ds_write_b16 v139, v112 offset:8448
	ds_write_b16 v139, v113 offset:8976
	ds_write_b16 v139, v114 offset:9504
	ds_write_b16 v139, v115 offset:10032
	v_cvt_f16_f32_e32 v112, v122
	v_cvt_f16_f32_e32 v113, v123
	v_cvt_f16_f32_e32 v114, v130
	v_cvt_f16_f32_e32 v115, v131
	ds_write_b16 v139, v112 offset:8480
	ds_write_b16 v139, v113 offset:9008
	ds_write_b16 v139, v114 offset:9536
	ds_write_b16 v139, v115 offset:10064
	v_or_b32_e32 v136, 32, v133
	v_add_u32_e32 v157, s21, v136
	v_and_b32_e32 v112, s22, v157
	v_lshlrev_b32_e32 v149, 7, v112
	v_bitop3_b32 v114, v157, s22, 1 bitop3:0xc8
	v_or_b32_e32 v112, v149, v141
	v_lshlrev_b32_e32 v150, 7, v114
	v_lshlrev_b32_e32 v152, 3, v112
	v_or_b32_e32 v114, v150, v141
	v_lshl_add_u64 v[112:113], s[2:3], 0, v[152:153]
	v_lshlrev_b32_e32 v152, 3, v114
	v_lshl_add_u64 v[114:115], s[2:3], 0, v[152:153]
	v_add_u32_e32 v227, 0x200, v226
	global_load_dwordx2 v[194:195], v227, s[2:3]
	global_load_dwordx2 v[196:197], v227, s[2:3] offset:1024
	global_load_dwordx2 v[198:199], v227, s[2:3] offset:2048
	global_load_dwordx2 v[200:201], v227, s[2:3] offset:3072
	v_add_u32_e32 v227, 0x4200, v226
	global_load_dwordx2 v[202:203], v227, s[2:3]
	global_load_dwordx2 v[204:205], v227, s[2:3] offset:1024
	global_load_dwordx2 v[206:207], v227, s[2:3] offset:2048
	global_load_dwordx2 v[208:209], v227, s[2:3] offset:3072
	s_waitcnt vmcnt(15)
	v_mov_b32_e32 v158, v210
	v_mov_b32_e32 v159, v211
	s_nop 0
	s_waitcnt vmcnt(14)
	v_mov_b32_e32 v112, v212
	v_mov_b32_e32 v113, v213
	s_waitcnt lgkmcnt(0)
	v_mov_b32_e32 v114, v159
	v_mov_b32_e32 v115, v113
	v_pk_mul_f32 v[160:161], v[104:105], v[114:115]
	v_mov_b32_e32 v159, v112
	v_pk_fma_f32 v[112:113], v[108:109], v[158:159], v[160:161]
	v_pk_mul_f32 v[108:109], v[108:109], v[114:115]
	v_bitop3_b32 v114, v157, s22, 3 bitop3:0xc8
	v_pk_fma_f32 v[108:109], v[104:105], v[158:159], v[108:109] neg_lo:[0,0,1] neg_hi:[0,0,1]
	v_bitop3_b32 v104, v157, s22, 2 bitop3:0xc8
	v_lshlrev_b32_e32 v151, 7, v104
	v_or_b32_e32 v104, v151, v141
	v_lshlrev_b32_e32 v157, 7, v114
	v_lshlrev_b32_e32 v152, 3, v104
	v_or_b32_e32 v114, v157, v141
	v_lshl_add_u64 v[104:105], s[2:3], 0, v[152:153]
	v_lshlrev_b32_e32 v152, 3, v114
	v_lshl_add_u64 v[114:115], s[2:3], 0, v[152:153]
	s_waitcnt vmcnt(13)
	v_mov_b32_e32 v104, v214
	v_mov_b32_e32 v105, v215
	s_nop 0
	s_waitcnt vmcnt(12)
	v_mov_b32_e32 v114, v216
	v_mov_b32_e32 v115, v217
	s_waitcnt lgkmcnt(0)
	v_mov_b32_e32 v158, v105
	v_mov_b32_e32 v159, v115
	v_pk_mul_f32 v[160:161], v[106:107], v[158:159]
	v_mov_b32_e32 v105, v114
	v_pk_fma_f32 v[114:115], v[110:111], v[104:105], v[160:161]
	v_pk_mul_f32 v[110:111], v[110:111], v[158:159]
	s_nop 0
	v_pk_fma_f32 v[106:107], v[106:107], v[104:105], v[110:111] neg_lo:[0,0,1] neg_hi:[0,0,1]
	v_cvt_f16_f32_e32 v104, v108
	v_cvt_f16_f32_e32 v105, v109
	v_cvt_f16_f32_e32 v110, v106
	v_cvt_f16_f32_e32 v111, v107
	ds_write_b16 v139, v104 offset:16896
	ds_write_b16 v139, v105 offset:17424
	ds_write_b16 v139, v110 offset:17952
	ds_write_b16 v139, v111 offset:18480
	v_cvt_f16_f32_e32 v104, v112
	v_cvt_f16_f32_e32 v105, v113
	v_cvt_f16_f32_e32 v110, v114
	v_cvt_f16_f32_e32 v111, v115
	ds_write_b16 v139, v104 offset:16928
	ds_write_b16 v139, v105 offset:17456
	ds_write_b16 v139, v110 offset:17984
	ds_write_b16 v139, v111 offset:18512
	v_bitop3_b32 v110, v142, s22, 1 bitop3:0xc8
	v_or_b32_e32 v104, v135, v141
	v_lshlrev_b32_e32 v158, 7, v110
	v_lshlrev_b32_e32 v152, 3, v104
	v_or_b32_e32 v110, v158, v141
	v_lshl_add_u64 v[104:105], s[2:3], 0, v[152:153]
	v_lshlrev_b32_e32 v152, 3, v110
	v_lshl_add_u64 v[110:111], s[2:3], 0, v[152:153]
	s_waitcnt vmcnt(11)
	v_mov_b32_e32 v160, v218
	v_mov_b32_e32 v161, v219
	s_nop 0
	s_waitcnt vmcnt(10)
	v_mov_b32_e32 v104, v220
	v_mov_b32_e32 v105, v221
	s_waitcnt lgkmcnt(0)
	v_mov_b32_e32 v110, v161
	v_mov_b32_e32 v111, v105
	v_pk_mul_f32 v[162:163], v[96:97], v[110:111]
	v_mov_b32_e32 v161, v104
	v_pk_fma_f32 v[104:105], v[100:101], v[160:161], v[162:163]
	v_pk_mul_f32 v[100:101], v[100:101], v[110:111]
	v_bitop3_b32 v110, v142, s22, 3 bitop3:0xc8
	v_pk_fma_f32 v[96:97], v[96:97], v[160:161], v[100:101] neg_lo:[0,0,1] neg_hi:[0,0,1]
	v_bitop3_b32 v100, v142, s22, 2 bitop3:0xc8
	v_lshlrev_b32_e32 v159, 7, v100
	v_or_b32_e32 v100, v159, v141
	v_lshlrev_b32_e32 v160, 7, v110
	v_lshlrev_b32_e32 v152, 3, v100
	v_or_b32_e32 v110, v160, v141
	v_lshl_add_u64 v[100:101], s[2:3], 0, v[152:153]
	v_lshlrev_b32_e32 v152, 3, v110
	v_lshl_add_u64 v[110:111], s[2:3], 0, v[152:153]
	s_waitcnt vmcnt(9)
	v_mov_b32_e32 v162, v222
	v_mov_b32_e32 v163, v223
	s_nop 0
	s_waitcnt vmcnt(8)
	v_mov_b32_e32 v100, v224
	v_mov_b32_e32 v101, v225
	s_waitcnt lgkmcnt(0)
; #define FOR_R _Pragma("unroll") for (int r = 0; r < 4; ++r)
; #define FOR_AI _Pragma("unroll") for (int ai = 0; ai < 2; ++ai)
; #define FOR_BJ _Pragma("unroll") for (int bj = 0; bj < 2; ++bj)
; #define FOR_M4 _Pragma("unroll") for (int m = 0; m < 4; ++m)
; template <bool ISK>
; __device__ void job_qk_g(const P& p, int l, int g, int ct2, int rt, HALF* sm) {
;     ...
;   FOR_AI FOR_BJ {
;     FOR_M4 {
;       const int row0 = ai * 128 + wr * 64 + m * 16 + fq * 4;
;       const int lc = bj * 128 + wc * 32 + fr;
;       const int j = (bj * 4 + wc) * 16 + fr;
;       f4 o1, o2;
;       FOR_R {
;         const int sp = (rt * 256 + row0 + r) & (S - 1);
;         const float2 cs = rope[sp * 128 + j];
;         const float a = acc[ai][bj][m][0][r], b = acc[ai][bj][m][1][r];
;         o1[r] = a * cs.x - b * cs.y;
;         o2[r] = a * cs.y + b * cs.x;
;       }
;       acc[ai][bj][m][0] = o1;
;       acc[ai][bj][m][1] = o2;
;       stage2_rm(sm, row0, lc, to_h4(o1));
;       stage2_rm(sm, row0, lc + 16, to_h4(o2));
;       __builtin_amdgcn_sched_barrier(0);
;     }
;   }
	v_mov_b32_e32 v110, v163
	v_mov_b32_e32 v111, v101
	v_pk_mul_f32 v[164:165], v[98:99], v[110:111]
	v_mov_b32_e32 v163, v100
	v_pk_fma_f32 v[100:101], v[102:103], v[162:163], v[164:165]
	v_pk_mul_f32 v[102:103], v[102:103], v[110:111]
	s_nop 0
	v_pk_fma_f32 v[98:99], v[98:99], v[162:163], v[102:103] neg_lo:[0,0,1] neg_hi:[0,0,1]
	v_cvt_f16_f32_e32 v102, v96
	v_cvt_f16_f32_e32 v103, v97
	v_cvt_f16_f32_e32 v110, v98
	v_cvt_f16_f32_e32 v111, v99
	ds_write_b16 v139, v102 offset:25344
	ds_write_b16 v139, v103 offset:25872
	ds_write_b16 v139, v110 offset:26400
	ds_write_b16 v139, v111 offset:26928
	v_cvt_f16_f32_e32 v102, v104
	v_cvt_f16_f32_e32 v103, v105
	v_cvt_f16_f32_e32 v110, v100
	v_cvt_f16_f32_e32 v111, v101
	ds_write_b16 v139, v102 offset:25376
	ds_write_b16 v139, v103 offset:25904
	ds_write_b16 v139, v110 offset:26432
	ds_write_b16 v139, v111 offset:26960
	v_or_b32_e32 v142, 64, v141
	v_or_b32_e32 v102, v138, v142
	v_lshlrev_b32_e32 v152, 3, v102
	v_or_b32_e32 v110, v140, v142
	v_lshl_add_u64 v[102:103], s[2:3], 0, v[152:153]
	v_lshlrev_b32_e32 v152, 3, v110
	v_lshl_add_u64 v[110:111], s[2:3], 0, v[152:153]
	v_add_u32_e32 v227, 0x8200, v226
	global_load_dwordx2 v[210:211], v227, s[2:3]
	global_load_dwordx2 v[212:213], v227, s[2:3] offset:1024
	global_load_dwordx2 v[214:215], v227, s[2:3] offset:2048
	global_load_dwordx2 v[216:217], v227, s[2:3] offset:3072
	v_add_u32_e32 v227, 0xc200, v226
	global_load_dwordx2 v[218:219], v227, s[2:3]
	global_load_dwordx2 v[220:221], v227, s[2:3] offset:1024
	global_load_dwordx2 v[222:223], v227, s[2:3] offset:2048
	global_load_dwordx2 v[224:225], v227, s[2:3] offset:3072
	s_waitcnt vmcnt(15)
	v_mov_b32_e32 v162, v194
	v_mov_b32_e32 v163, v195
	s_nop 0
	s_waitcnt vmcnt(14)
	v_mov_b32_e32 v102, v196
	v_mov_b32_e32 v103, v197
	s_waitcnt lgkmcnt(0)
	v_mov_b32_e32 v110, v163
	v_mov_b32_e32 v111, v103
	v_pk_mul_f32 v[164:165], v[88:89], v[110:111]
	v_mov_b32_e32 v163, v102
	v_pk_fma_f32 v[102:103], v[92:93], v[162:163], v[164:165]
	v_pk_mul_f32 v[92:93], v[92:93], v[110:111]
	v_or_b32_e32 v110, v144, v142
	v_pk_fma_f32 v[92:93], v[88:89], v[162:163], v[92:93] neg_lo:[0,0,1] neg_hi:[0,0,1]
	v_or_b32_e32 v88, v143, v142
	v_lshlrev_b32_e32 v152, 3, v88
	v_lshl_add_u64 v[88:89], s[2:3], 0, v[152:153]
	v_lshlrev_b32_e32 v152, 3, v110
	v_lshl_add_u64 v[110:111], s[2:3], 0, v[152:153]
	s_waitcnt vmcnt(13)
	v_mov_b32_e32 v88, v198
	v_mov_b32_e32 v89, v199
	s_nop 0
	s_waitcnt vmcnt(12)
	v_mov_b32_e32 v110, v200
	v_mov_b32_e32 v111, v201
	s_waitcnt lgkmcnt(0)
	v_mov_b32_e32 v162, v89
	v_mov_b32_e32 v163, v111
	v_pk_mul_f32 v[164:165], v[90:91], v[162:163]
	v_mov_b32_e32 v89, v110
	v_pk_fma_f32 v[110:111], v[94:95], v[88:89], v[164:165]
	v_pk_mul_f32 v[94:95], v[94:95], v[162:163]
	s_nop 0
	v_pk_fma_f32 v[94:95], v[90:91], v[88:89], v[94:95] neg_lo:[0,0,1] neg_hi:[0,0,1]
	v_cvt_f16_f32_e32 v88, v92
	v_cvt_f16_f32_e32 v89, v93
	v_cvt_f16_f32_e32 v90, v94
	v_cvt_f16_f32_e32 v91, v95
	ds_write_b16 v139, v88 offset:256
	ds_write_b16 v139, v89 offset:784
	ds_write_b16 v139, v90 offset:1312
	ds_write_b16 v139, v91 offset:1840
	v_cvt_f16_f32_e32 v88, v102
	v_cvt_f16_f32_e32 v89, v103
	v_cvt_f16_f32_e32 v90, v110
	v_cvt_f16_f32_e32 v91, v111
	ds_write_b16 v139, v88 offset:288
	ds_write_b16 v139, v89 offset:816
	ds_write_b16 v139, v90 offset:1344
	ds_write_b16 v139, v91 offset:1872
	v_or_b32_e32 v88, v145, v142
	v_lshlrev_b32_e32 v152, 3, v88
	v_or_b32_e32 v90, v146, v142
	v_lshl_add_u64 v[88:89], s[2:3], 0, v[152:153]
	v_lshlrev_b32_e32 v152, 3, v90
	v_lshl_add_u64 v[90:91], s[2:3], 0, v[152:153]
	s_waitcnt vmcnt(11)
	v_mov_b32_e32 v144, v202
	v_mov_b32_e32 v145, v203
	s_nop 0
	s_waitcnt vmcnt(10)
	v_mov_b32_e32 v88, v204
	v_mov_b32_e32 v89, v205
	s_waitcnt lgkmcnt(0)
	v_mov_b32_e32 v90, v145
	v_mov_b32_e32 v91, v89
	v_pk_mul_f32 v[162:163], v[80:81], v[90:91]
	v_mov_b32_e32 v145, v88
	v_pk_fma_f32 v[88:89], v[84:85], v[144:145], v[162:163]
	v_pk_mul_f32 v[84:85], v[84:85], v[90:91]
	v_or_b32_e32 v90, v148, v142
	v_pk_fma_f32 v[84:85], v[80:81], v[144:145], v[84:85] neg_lo:[0,0,1] neg_hi:[0,0,1]
	v_or_b32_e32 v80, v147, v142
	v_lshlrev_b32_e32 v152, 3, v80
	v_lshl_add_u64 v[80:81], s[2:3], 0, v[152:153]
	v_lshlrev_b32_e32 v152, 3, v90
	v_lshl_add_u64 v[90:91], s[2:3], 0, v[152:153]
	s_waitcnt vmcnt(9)
	v_mov_b32_e32 v80, v206
	v_mov_b32_e32 v81, v207
	s_nop 0
	s_waitcnt vmcnt(8)
	v_mov_b32_e32 v90, v208
	v_mov_b32_e32 v91, v209
	s_waitcnt lgkmcnt(0)
	v_mov_b32_e32 v144, v81
	v_mov_b32_e32 v145, v91
	v_pk_mul_f32 v[146:147], v[82:83], v[144:145]
	v_mov_b32_e32 v81, v90
	v_pk_fma_f32 v[90:91], v[86:87], v[80:81], v[146:147]
	v_pk_mul_f32 v[86:87], v[86:87], v[144:145]
	s_nop 0
	v_pk_fma_f32 v[86:87], v[82:83], v[80:81], v[86:87] neg_lo:[0,0,1] neg_hi:[0,0,1]
	v_cvt_f16_f32_e32 v80, v84
	v_cvt_f16_f32_e32 v81, v85
	v_cvt_f16_f32_e32 v82, v86
	v_cvt_f16_f32_e32 v83, v87
	ds_write_b16 v139, v80 offset:8704
	ds_write_b16 v139, v81 offset:9232
	ds_write_b16 v139, v82 offset:9760
	ds_write_b16 v139, v83 offset:10288
	v_cvt_f16_f32_e32 v80, v88
	v_cvt_f16_f32_e32 v81, v89
	v_cvt_f16_f32_e32 v82, v90
	v_cvt_f16_f32_e32 v83, v91
	ds_write_b16 v139, v80 offset:8736
	ds_write_b16 v139, v81 offset:9264
	ds_write_b16 v139, v82 offset:9792
	ds_write_b16 v139, v83 offset:10320
	v_or_b32_e32 v80, v149, v142
	v_lshlrev_b32_e32 v152, 3, v80
	v_or_b32_e32 v82, v150, v142
	v_lshl_add_u64 v[80:81], s[2:3], 0, v[152:153]
	v_lshlrev_b32_e32 v152, 3, v82
	v_lshl_add_u64 v[82:83], s[2:3], 0, v[152:153]
	v_add_u32_e32 v227, 0x20000, v226
	global_load_dwordx2 v[194:195], v227, s[2:3]
	global_load_dwordx2 v[196:197], v227, s[2:3] offset:1024
	global_load_dwordx2 v[198:199], v227, s[2:3] offset:2048
	global_load_dwordx2 v[200:201], v227, s[2:3] offset:3072
	v_add_u32_e32 v227, 0x24000, v226
	global_load_dwordx2 v[202:203], v227, s[2:3]
	global_load_dwordx2 v[204:205], v227, s[2:3] offset:1024
	global_load_dwordx2 v[206:207], v227, s[2:3] offset:2048
	global_load_dwordx2 v[208:209], v227, s[2:3] offset:3072
	s_waitcnt vmcnt(15)
; #define FOR_R _Pragma("unroll") for (int r = 0; r < 4; ++r)
; #define FOR_AI _Pragma("unroll") for (int ai = 0; ai < 2; ++ai)
; #define FOR_BJ _Pragma("unroll") for (int bj = 0; bj < 2; ++bj)
; #define FOR_M4 _Pragma("unroll") for (int m = 0; m < 4; ++m)
; template <bool ISK>
; __device__ void job_qk_g(const P& p, int l, int g, int ct2, int rt, HALF* sm) {
;     ...
;   FOR_AI FOR_BJ {
;     FOR_M4 {
;       const int row0 = ai * 128 + wr * 64 + m * 16 + fq * 4;
;       const int lc = bj * 128 + wc * 32 + fr;
;       const int j = (bj * 4 + wc) * 16 + fr;
;       f4 o1, o2;
;       FOR_R {
;         const int sp = (rt * 256 + row0 + r) & (S - 1);
;         const float2 cs = rope[sp * 128 + j];
;         const float a = acc[ai][bj][m][0][r], b = acc[ai][bj][m][1][r];
;         o1[r] = a * cs.x - b * cs.y;
;         o2[r] = a * cs.y + b * cs.x;
;       }
;       acc[ai][bj][m][0] = o1;
;       acc[ai][bj][m][1] = o2;
;       stage2_rm(sm, row0, lc, to_h4(o1));
;       stage2_rm(sm, row0, lc + 16, to_h4(o2));
;       __builtin_amdgcn_sched_barrier(0);
;     }
;   }
	v_mov_b32_e32 v144, v210
	v_mov_b32_e32 v145, v211
	s_nop 0
	s_waitcnt vmcnt(14)
	v_mov_b32_e32 v80, v212
	v_mov_b32_e32 v81, v213
	s_waitcnt lgkmcnt(0)
	v_mov_b32_e32 v82, v145
	v_mov_b32_e32 v83, v81
	v_pk_mul_f32 v[146:147], v[72:73], v[82:83]
	v_mov_b32_e32 v145, v80
	v_pk_fma_f32 v[80:81], v[76:77], v[144:145], v[146:147]
	v_pk_mul_f32 v[76:77], v[76:77], v[82:83]
	v_or_b32_e32 v82, v157, v142
	v_pk_fma_f32 v[76:77], v[72:73], v[144:145], v[76:77] neg_lo:[0,0,1] neg_hi:[0,0,1]
	v_or_b32_e32 v72, v151, v142
	v_lshlrev_b32_e32 v152, 3, v72
	v_lshl_add_u64 v[72:73], s[2:3], 0, v[152:153]
	v_lshlrev_b32_e32 v152, 3, v82
	v_lshl_add_u64 v[82:83], s[2:3], 0, v[152:153]
	s_waitcnt vmcnt(13)
	v_mov_b32_e32 v72, v214
	v_mov_b32_e32 v73, v215
	s_nop 0
	s_waitcnt vmcnt(12)
	v_mov_b32_e32 v82, v216
	v_mov_b32_e32 v83, v217
	s_waitcnt lgkmcnt(0)
	v_mov_b32_e32 v144, v73
	v_mov_b32_e32 v145, v83
	v_pk_mul_f32 v[146:147], v[74:75], v[144:145]
	v_mov_b32_e32 v73, v82
	v_pk_fma_f32 v[82:83], v[78:79], v[72:73], v[146:147]
	v_pk_mul_f32 v[78:79], v[78:79], v[144:145]
	s_nop 0
	v_pk_fma_f32 v[78:79], v[74:75], v[72:73], v[78:79] neg_lo:[0,0,1] neg_hi:[0,0,1]
	v_cvt_f16_f32_e32 v72, v76
	v_cvt_f16_f32_e32 v73, v77
	v_cvt_f16_f32_e32 v74, v78
	v_cvt_f16_f32_e32 v75, v79
	ds_write_b16 v139, v72 offset:17152
	ds_write_b16 v139, v73 offset:17680
	ds_write_b16 v139, v74 offset:18208
	ds_write_b16 v139, v75 offset:18736
	v_cvt_f16_f32_e32 v72, v80
	v_cvt_f16_f32_e32 v73, v81
	v_cvt_f16_f32_e32 v74, v82
	v_cvt_f16_f32_e32 v75, v83
	ds_write_b16 v139, v72 offset:17184
	ds_write_b16 v139, v73 offset:17712
	ds_write_b16 v139, v74 offset:18240
	ds_write_b16 v139, v75 offset:18768
	v_or_b32_e32 v72, v135, v142
	v_lshlrev_b32_e32 v152, 3, v72
	v_or_b32_e32 v74, v158, v142
	v_lshl_add_u64 v[72:73], s[2:3], 0, v[152:153]
	v_lshlrev_b32_e32 v152, 3, v74
	v_lshl_add_u64 v[74:75], s[2:3], 0, v[152:153]
	s_waitcnt vmcnt(11)
	v_mov_b32_e32 v144, v218
	v_mov_b32_e32 v145, v219
	s_nop 0
	s_waitcnt vmcnt(10)
	v_mov_b32_e32 v72, v220
	v_mov_b32_e32 v73, v221
	s_waitcnt lgkmcnt(0)
	v_mov_b32_e32 v74, v145
	v_mov_b32_e32 v75, v73
	v_pk_mul_f32 v[146:147], v[64:65], v[74:75]
	v_mov_b32_e32 v145, v72
	v_pk_fma_f32 v[72:73], v[68:69], v[144:145], v[146:147]
	v_pk_mul_f32 v[68:69], v[68:69], v[74:75]
	v_or_b32_e32 v74, v160, v142
	v_pk_fma_f32 v[68:69], v[64:65], v[144:145], v[68:69] neg_lo:[0,0,1] neg_hi:[0,0,1]
	v_or_b32_e32 v64, v159, v142
	v_lshlrev_b32_e32 v152, 3, v64
	v_lshl_add_u64 v[64:65], s[2:3], 0, v[152:153]
	v_lshlrev_b32_e32 v152, 3, v74
	v_lshl_add_u64 v[74:75], s[2:3], 0, v[152:153]
	s_waitcnt vmcnt(9)
	v_mov_b32_e32 v64, v222
	v_mov_b32_e32 v65, v223
	s_nop 0
	s_waitcnt vmcnt(8)
	v_mov_b32_e32 v74, v224
	v_mov_b32_e32 v75, v225
	s_waitcnt lgkmcnt(0)
	v_mov_b32_e32 v144, v65
	v_mov_b32_e32 v145, v75
	v_pk_mul_f32 v[146:147], v[66:67], v[144:145]
	v_mov_b32_e32 v65, v74
	v_pk_fma_f32 v[74:75], v[70:71], v[64:65], v[146:147]
	v_pk_mul_f32 v[70:71], v[70:71], v[144:145]
	s_nop 0
	v_pk_fma_f32 v[70:71], v[66:67], v[64:65], v[70:71] neg_lo:[0,0,1] neg_hi:[0,0,1]
	v_cvt_f16_f32_e32 v64, v68
	v_cvt_f16_f32_e32 v65, v69
	v_cvt_f16_f32_e32 v66, v70
	v_cvt_f16_f32_e32 v67, v71
	ds_write_b16 v139, v64 offset:25600
	ds_write_b16 v139, v65 offset:26128
	ds_write_b16 v139, v66 offset:26656
	ds_write_b16 v139, v67 offset:27184
	v_cvt_f16_f32_e32 v64, v72
	v_cvt_f16_f32_e32 v65, v73
	v_cvt_f16_f32_e32 v66, v74
	v_cvt_f16_f32_e32 v67, v75
	ds_write_b16 v139, v64 offset:25632
	ds_write_b16 v139, v65 offset:26160
	ds_write_b16 v139, v66 offset:26688
	ds_write_b16 v139, v67 offset:27216
	v_add_u32_e32 v135, 0xb0, v133
	v_add_u32_e32 v138, 0x80, v133
	v_add_u32_e32 v164, s21, v135
	v_and_b32_e32 v64, s22, v164
	v_add_u32_e32 v140, s21, v138
	v_lshlrev_b32_e32 v144, 7, v64
	v_and_b32_e32 v64, s22, v140
	v_lshlrev_b32_e32 v145, 7, v64
	v_bitop3_b32 v66, v140, s22, 1 bitop3:0xc8
	v_or_b32_e32 v64, v145, v141
	v_lshlrev_b32_e32 v146, 7, v66
	v_lshlrev_b32_e32 v152, 3, v64
	v_or_b32_e32 v66, v146, v141
	v_lshl_add_u64 v[64:65], s[2:3], 0, v[152:153]
	v_lshlrev_b32_e32 v152, 3, v66
	v_lshl_add_u64 v[66:67], s[2:3], 0, v[152:153]
	v_add_u32_e32 v227, 0x28000, v226
	global_load_dwordx2 v[210:211], v227, s[2:3]
	global_load_dwordx2 v[212:213], v227, s[2:3] offset:1024
	global_load_dwordx2 v[214:215], v227, s[2:3] offset:2048
	global_load_dwordx2 v[216:217], v227, s[2:3] offset:3072
	v_add_u32_e32 v227, 0x2c000, v226
	global_load_dwordx2 v[218:219], v227, s[2:3]
	global_load_dwordx2 v[220:221], v227, s[2:3] offset:1024
	global_load_dwordx2 v[222:223], v227, s[2:3] offset:2048
	global_load_dwordx2 v[224:225], v227, s[2:3] offset:3072
	s_waitcnt vmcnt(15)
	v_mov_b32_e32 v148, v194
	v_mov_b32_e32 v149, v195
	s_nop 0
	s_waitcnt vmcnt(14)
	v_mov_b32_e32 v64, v196
	v_mov_b32_e32 v65, v197
	v_add_u32_e32 v143, 0x10800, v139
	s_waitcnt lgkmcnt(0)
	v_mov_b32_e32 v66, v149
	v_mov_b32_e32 v67, v65
	v_pk_mul_f32 v[150:151], v[56:57], v[66:67]
	v_mov_b32_e32 v149, v64
	v_pk_fma_f32 v[64:65], v[60:61], v[148:149], v[150:151]
	v_pk_mul_f32 v[60:61], v[60:61], v[66:67]
	v_bitop3_b32 v66, v140, s22, 3 bitop3:0xc8
	v_pk_fma_f32 v[56:57], v[56:57], v[148:149], v[60:61] neg_lo:[0,0,1] neg_hi:[0,0,1]
	v_bitop3_b32 v60, v140, s22, 2 bitop3:0xc8
	v_lshlrev_b32_e32 v147, 7, v60
	v_or_b32_e32 v60, v147, v141
	v_lshlrev_b32_e32 v148, 7, v66
	v_lshlrev_b32_e32 v152, 3, v60
	v_or_b32_e32 v66, v148, v141
	v_lshl_add_u64 v[60:61], s[2:3], 0, v[152:153]
	v_lshlrev_b32_e32 v152, 3, v66
	v_lshl_add_u64 v[66:67], s[2:3], 0, v[152:153]
	s_waitcnt vmcnt(13)
	v_mov_b32_e32 v150, v198
	v_mov_b32_e32 v151, v199
	s_nop 0
	s_waitcnt vmcnt(12)
; #define FOR_R _Pragma("unroll") for (int r = 0; r < 4; ++r)
; #define FOR_AI _Pragma("unroll") for (int ai = 0; ai < 2; ++ai)
; #define FOR_BJ _Pragma("unroll") for (int bj = 0; bj < 2; ++bj)
; #define FOR_M4 _Pragma("unroll") for (int m = 0; m < 4; ++m)
; template <bool ISK>
; __device__ void job_qk_g(const P& p, int l, int g, int ct2, int rt, HALF* sm) {
;     ...
;   FOR_AI FOR_BJ {
;     FOR_M4 {
;       const int row0 = ai * 128 + wr * 64 + m * 16 + fq * 4;
;       const int lc = bj * 128 + wc * 32 + fr;
;       const int j = (bj * 4 + wc) * 16 + fr;
;       f4 o1, o2;
;       FOR_R {
;         const int sp = (rt * 256 + row0 + r) & (S - 1);
;         const float2 cs = rope[sp * 128 + j];
;         const float a = acc[ai][bj][m][0][r], b = acc[ai][bj][m][1][r];
;         o1[r] = a * cs.x - b * cs.y;
;         o2[r] = a * cs.y + b * cs.x;
;       }
;       acc[ai][bj][m][0] = o1;
;       acc[ai][bj][m][1] = o2;
;       stage2_rm(sm, row0, lc, to_h4(o1));
;       stage2_rm(sm, row0, lc + 16, to_h4(o2));
;       __builtin_amdgcn_sched_barrier(0);
;     }
;   }
	v_mov_b32_e32 v60, v200
	v_mov_b32_e32 v61, v201
	s_waitcnt lgkmcnt(0)
	v_mov_b32_e32 v66, v151
	v_mov_b32_e32 v67, v61
	v_pk_mul_f32 v[158:159], v[58:59], v[66:67]
	v_mov_b32_e32 v151, v60
	v_pk_fma_f32 v[60:61], v[62:63], v[150:151], v[158:159]
	v_pk_mul_f32 v[62:63], v[62:63], v[66:67]
	s_nop 0
	v_pk_fma_f32 v[62:63], v[58:59], v[150:151], v[62:63] neg_lo:[0,0,1] neg_hi:[0,0,1]
	v_cvt_f16_f32_e32 v58, v56
	v_cvt_f16_f32_e32 v59, v57
	v_cvt_f16_f32_e32 v66, v62
	v_cvt_f16_f32_e32 v67, v63
	ds_write_b16 v143, v58
	ds_write_b16 v143, v59 offset:528
	ds_write_b16 v143, v66 offset:1056
	ds_write_b16 v143, v67 offset:1584
	v_cvt_f16_f32_e32 v58, v64
	v_cvt_f16_f32_e32 v59, v65
	v_cvt_f16_f32_e32 v66, v60
	v_cvt_f16_f32_e32 v67, v61
	ds_write_b16 v143, v58 offset:32
	ds_write_b16 v143, v59 offset:560
	ds_write_b16 v143, v66 offset:1088
	ds_write_b16 v143, v67 offset:1616
	v_add_u32_e32 v140, 0x90, v133
	v_add_u32_e32 v139, s21, v140
	v_and_b32_e32 v58, s22, v139
	v_lshlrev_b32_e32 v149, 7, v58
	v_bitop3_b32 v66, v139, s22, 1 bitop3:0xc8
	v_or_b32_e32 v58, v149, v141
	v_lshlrev_b32_e32 v150, 7, v66
	v_lshlrev_b32_e32 v152, 3, v58
	v_or_b32_e32 v66, v150, v141
	v_lshl_add_u64 v[58:59], s[2:3], 0, v[152:153]
	v_lshlrev_b32_e32 v152, 3, v66
	v_lshl_add_u64 v[66:67], s[2:3], 0, v[152:153]
	s_waitcnt vmcnt(11)
	v_mov_b32_e32 v158, v202
	v_mov_b32_e32 v159, v203
	s_nop 0
	s_waitcnt vmcnt(10)
	v_mov_b32_e32 v58, v204
	v_mov_b32_e32 v59, v205
	s_waitcnt lgkmcnt(0)
	v_mov_b32_e32 v66, v159
	v_mov_b32_e32 v67, v59
	v_pk_mul_f32 v[160:161], v[48:49], v[66:67]
	v_mov_b32_e32 v159, v58
	v_pk_fma_f32 v[58:59], v[52:53], v[158:159], v[160:161]
	v_pk_mul_f32 v[52:53], v[52:53], v[66:67]
	v_bitop3_b32 v66, v139, s22, 3 bitop3:0xc8
	v_pk_fma_f32 v[52:53], v[48:49], v[158:159], v[52:53] neg_lo:[0,0,1] neg_hi:[0,0,1]
	v_bitop3_b32 v48, v139, s22, 2 bitop3:0xc8
	v_lshlrev_b32_e32 v151, 7, v48
	v_or_b32_e32 v48, v151, v141
	v_lshlrev_b32_e32 v157, 7, v66
	v_lshlrev_b32_e32 v152, 3, v48
	v_or_b32_e32 v66, v157, v141
	v_lshl_add_u64 v[48:49], s[2:3], 0, v[152:153]
	v_lshlrev_b32_e32 v152, 3, v66
	v_lshl_add_u64 v[66:67], s[2:3], 0, v[152:153]
	s_waitcnt vmcnt(9)
	v_mov_b32_e32 v48, v206
	v_mov_b32_e32 v49, v207
	s_nop 0
	s_waitcnt vmcnt(8)
	v_mov_b32_e32 v66, v208
	v_mov_b32_e32 v67, v209
	s_waitcnt lgkmcnt(0)
	v_mov_b32_e32 v158, v49
	v_mov_b32_e32 v159, v67
	v_pk_mul_f32 v[160:161], v[50:51], v[158:159]
	v_mov_b32_e32 v49, v66
	v_pk_fma_f32 v[66:67], v[54:55], v[48:49], v[160:161]
	v_pk_mul_f32 v[54:55], v[54:55], v[158:159]
	s_nop 0
	v_pk_fma_f32 v[54:55], v[50:51], v[48:49], v[54:55] neg_lo:[0,0,1] neg_hi:[0,0,1]
	v_cvt_f16_f32_e32 v48, v52
	v_cvt_f16_f32_e32 v49, v53
	v_cvt_f16_f32_e32 v50, v54
	v_cvt_f16_f32_e32 v51, v55
	ds_write_b16 v143, v48 offset:8448
	ds_write_b16 v143, v49 offset:8976
	ds_write_b16 v143, v50 offset:9504
	ds_write_b16 v143, v51 offset:10032
	v_cvt_f16_f32_e32 v48, v58
	v_cvt_f16_f32_e32 v49, v59
	v_cvt_f16_f32_e32 v50, v66
	v_cvt_f16_f32_e32 v51, v67
	ds_write_b16 v143, v48 offset:8480
	ds_write_b16 v143, v49 offset:9008
	ds_write_b16 v143, v50 offset:9536
	ds_write_b16 v143, v51 offset:10064
	v_add_u32_e32 v139, 0xa0, v133
	v_add_u32_e32 v165, s21, v139
	v_and_b32_e32 v48, s22, v165
	v_lshlrev_b32_e32 v158, 7, v48
	v_bitop3_b32 v50, v165, s22, 1 bitop3:0xc8
	v_or_b32_e32 v48, v158, v141
	v_lshlrev_b32_e32 v159, 7, v50
	v_lshlrev_b32_e32 v152, 3, v48
	v_or_b32_e32 v50, v159, v141
	v_lshl_add_u64 v[48:49], s[2:3], 0, v[152:153]
	v_lshlrev_b32_e32 v152, 3, v50
	v_lshl_add_u64 v[50:51], s[2:3], 0, v[152:153]
	v_add_u32_e32 v227, 0x20200, v226
	global_load_dwordx2 v[194:195], v227, s[2:3]
	global_load_dwordx2 v[196:197], v227, s[2:3] offset:1024
	global_load_dwordx2 v[198:199], v227, s[2:3] offset:2048
	global_load_dwordx2 v[200:201], v227, s[2:3] offset:3072
	v_add_u32_e32 v227, 0x24200, v226
	global_load_dwordx2 v[202:203], v227, s[2:3]
	global_load_dwordx2 v[204:205], v227, s[2:3] offset:1024
	global_load_dwordx2 v[206:207], v227, s[2:3] offset:2048
	global_load_dwordx2 v[208:209], v227, s[2:3] offset:3072
	s_waitcnt vmcnt(15)
	v_mov_b32_e32 v160, v210
	v_mov_b32_e32 v161, v211
	s_nop 0
	s_waitcnt vmcnt(14)
	v_mov_b32_e32 v48, v212
	v_mov_b32_e32 v49, v213
	s_waitcnt lgkmcnt(0)
	v_mov_b32_e32 v50, v161
	v_mov_b32_e32 v51, v49
	v_pk_mul_f32 v[162:163], v[40:41], v[50:51]
	v_mov_b32_e32 v161, v48
	v_pk_fma_f32 v[48:49], v[44:45], v[160:161], v[162:163]
	v_pk_mul_f32 v[44:45], v[44:45], v[50:51]
	v_bitop3_b32 v50, v165, s22, 3 bitop3:0xc8
	v_pk_fma_f32 v[44:45], v[40:41], v[160:161], v[44:45] neg_lo:[0,0,1] neg_hi:[0,0,1]
	v_bitop3_b32 v40, v165, s22, 2 bitop3:0xc8
	v_lshlrev_b32_e32 v160, 7, v40
	v_or_b32_e32 v40, v160, v141
	v_lshlrev_b32_e32 v161, 7, v50
	v_lshlrev_b32_e32 v152, 3, v40
	v_or_b32_e32 v50, v161, v141
	v_lshl_add_u64 v[40:41], s[2:3], 0, v[152:153]
	v_lshlrev_b32_e32 v152, 3, v50
	v_lshl_add_u64 v[50:51], s[2:3], 0, v[152:153]
	s_waitcnt vmcnt(13)
	v_mov_b32_e32 v40, v214
	v_mov_b32_e32 v41, v215
	s_nop 0
	s_waitcnt vmcnt(12)
	v_mov_b32_e32 v50, v216
	v_mov_b32_e32 v51, v217
	s_waitcnt lgkmcnt(0)
; #define FOR_R _Pragma("unroll") for (int r = 0; r < 4; ++r)
; #define FOR_AI _Pragma("unroll") for (int ai = 0; ai < 2; ++ai)
; #define FOR_BJ _Pragma("unroll") for (int bj = 0; bj < 2; ++bj)
; #define FOR_M4 _Pragma("unroll") for (int m = 0; m < 4; ++m)
; template <bool ISK>
; __device__ void job_qk_g(const P& p, int l, int g, int ct2, int rt, HALF* sm) {
;     ...
;   FOR_AI FOR_BJ {
;     FOR_M4 {
;       const int row0 = ai * 128 + wr * 64 + m * 16 + fq * 4;
;       const int lc = bj * 128 + wc * 32 + fr;
;       const int j = (bj * 4 + wc) * 16 + fr;
;       f4 o1, o2;
;       FOR_R {
;         const int sp = (rt * 256 + row0 + r) & (S - 1);
;         const float2 cs = rope[sp * 128 + j];
;         const float a = acc[ai][bj][m][0][r], b = acc[ai][bj][m][1][r];
;         o1[r] = a * cs.x - b * cs.y;
;         o2[r] = a * cs.y + b * cs.x;
;       }
;       acc[ai][bj][m][0] = o1;
;       acc[ai][bj][m][1] = o2;
;       stage2_rm(sm, row0, lc, to_h4(o1));
;       stage2_rm(sm, row0, lc + 16, to_h4(o2));
;       __builtin_amdgcn_sched_barrier(0);
;     }
;   }
	v_mov_b32_e32 v162, v41
	v_mov_b32_e32 v163, v51
	v_pk_mul_f32 v[166:167], v[42:43], v[162:163]
	v_mov_b32_e32 v41, v50
	v_pk_fma_f32 v[50:51], v[46:47], v[40:41], v[166:167]
	v_pk_mul_f32 v[46:47], v[46:47], v[162:163]
	s_nop 0
	v_pk_fma_f32 v[42:43], v[42:43], v[40:41], v[46:47] neg_lo:[0,0,1] neg_hi:[0,0,1]
	v_cvt_f16_f32_e32 v40, v44
	v_cvt_f16_f32_e32 v41, v45
	v_cvt_f16_f32_e32 v46, v42
	v_cvt_f16_f32_e32 v47, v43
	ds_write_b16 v143, v40 offset:16896
	ds_write_b16 v143, v41 offset:17424
	ds_write_b16 v143, v46 offset:17952
	ds_write_b16 v143, v47 offset:18480
	v_cvt_f16_f32_e32 v40, v48
	v_cvt_f16_f32_e32 v41, v49
	v_cvt_f16_f32_e32 v46, v50
	v_cvt_f16_f32_e32 v47, v51
	ds_write_b16 v143, v40 offset:16928
	ds_write_b16 v143, v41 offset:17456
	ds_write_b16 v143, v46 offset:17984
	ds_write_b16 v143, v47 offset:18512
	v_bitop3_b32 v46, v164, s22, 1 bitop3:0xc8
	v_or_b32_e32 v40, v144, v141
	v_lshlrev_b32_e32 v162, 7, v46
	v_lshlrev_b32_e32 v152, 3, v40
	v_or_b32_e32 v46, v162, v141
	v_lshl_add_u64 v[40:41], s[2:3], 0, v[152:153]
	v_lshlrev_b32_e32 v152, 3, v46
	v_lshl_add_u64 v[46:47], s[2:3], 0, v[152:153]
	s_waitcnt vmcnt(11)
	v_mov_b32_e32 v166, v218
	v_mov_b32_e32 v167, v219
	s_nop 0
	s_waitcnt vmcnt(10)
	v_mov_b32_e32 v40, v220
	v_mov_b32_e32 v41, v221
	s_waitcnt lgkmcnt(0)
	v_mov_b32_e32 v46, v167
	v_mov_b32_e32 v47, v41
	v_pk_mul_f32 v[168:169], v[32:33], v[46:47]
	v_mov_b32_e32 v167, v40
	v_pk_fma_f32 v[40:41], v[36:37], v[166:167], v[168:169]
	v_pk_mul_f32 v[36:37], v[36:37], v[46:47]
	v_bitop3_b32 v46, v164, s22, 3 bitop3:0xc8
	v_pk_fma_f32 v[32:33], v[32:33], v[166:167], v[36:37] neg_lo:[0,0,1] neg_hi:[0,0,1]
	v_bitop3_b32 v36, v164, s22, 2 bitop3:0xc8
	v_lshlrev_b32_e32 v163, 7, v36
	v_or_b32_e32 v36, v163, v141
	v_lshlrev_b32_e32 v164, 7, v46
	v_lshlrev_b32_e32 v152, 3, v36
	v_or_b32_e32 v46, v164, v141
	v_lshl_add_u64 v[36:37], s[2:3], 0, v[152:153]
	v_lshlrev_b32_e32 v152, 3, v46
	v_lshl_add_u64 v[46:47], s[2:3], 0, v[152:153]
	s_waitcnt vmcnt(9)
	v_mov_b32_e32 v166, v222
	v_mov_b32_e32 v167, v223
	s_nop 0
	s_waitcnt vmcnt(8)
	v_mov_b32_e32 v36, v224
	v_mov_b32_e32 v37, v225
	s_waitcnt lgkmcnt(0)
	v_mov_b32_e32 v46, v167
	v_mov_b32_e32 v47, v37
	v_pk_mul_f32 v[168:169], v[34:35], v[46:47]
	v_mov_b32_e32 v167, v36
	v_pk_fma_f32 v[36:37], v[38:39], v[166:167], v[168:169]
	v_pk_mul_f32 v[38:39], v[38:39], v[46:47]
	s_nop 0
	v_pk_fma_f32 v[34:35], v[34:35], v[166:167], v[38:39] neg_lo:[0,0,1] neg_hi:[0,0,1]
	v_cvt_f16_f32_e32 v38, v32
	v_cvt_f16_f32_e32 v39, v33
	v_cvt_f16_f32_e32 v46, v34
	v_cvt_f16_f32_e32 v47, v35
	ds_write_b16 v143, v38 offset:25344
	ds_write_b16 v143, v39 offset:25872
	ds_write_b16 v143, v46 offset:26400
	ds_write_b16 v143, v47 offset:26928
	v_cvt_f16_f32_e32 v38, v40
	v_cvt_f16_f32_e32 v39, v41
	v_cvt_f16_f32_e32 v46, v36
	v_cvt_f16_f32_e32 v47, v37
	ds_write_b16 v143, v38 offset:25376
	ds_write_b16 v143, v39 offset:25904
	ds_write_b16 v143, v46 offset:26432
	ds_write_b16 v143, v47 offset:26960
	v_or_b32_e32 v38, v145, v142
	v_lshlrev_b32_e32 v152, 3, v38
	v_or_b32_e32 v46, v146, v142
	v_lshl_add_u64 v[38:39], s[2:3], 0, v[152:153]
	v_lshlrev_b32_e32 v152, 3, v46
	v_lshl_add_u64 v[46:47], s[2:3], 0, v[152:153]
	v_add_u32_e32 v227, 0x28200, v226
	global_load_dwordx2 v[210:211], v227, s[2:3]
	global_load_dwordx2 v[212:213], v227, s[2:3] offset:1024
	global_load_dwordx2 v[214:215], v227, s[2:3] offset:2048
	global_load_dwordx2 v[216:217], v227, s[2:3] offset:3072
	v_add_u32_e32 v227, 0x2c200, v226
	global_load_dwordx2 v[218:219], v227, s[2:3]
	global_load_dwordx2 v[220:221], v227, s[2:3] offset:1024
	global_load_dwordx2 v[222:223], v227, s[2:3] offset:2048
	global_load_dwordx2 v[224:225], v227, s[2:3] offset:3072
	s_waitcnt vmcnt(15)
	v_mov_b32_e32 v166, v194
	v_mov_b32_e32 v167, v195
	s_nop 0
	s_waitcnt vmcnt(14)
	v_mov_b32_e32 v38, v196
	v_mov_b32_e32 v39, v197
	s_waitcnt lgkmcnt(0)
	v_mov_b32_e32 v46, v167
	v_mov_b32_e32 v47, v39
	v_pk_mul_f32 v[168:169], v[24:25], v[46:47]
	v_mov_b32_e32 v167, v38
	v_pk_fma_f32 v[38:39], v[28:29], v[166:167], v[168:169]
	v_pk_mul_f32 v[28:29], v[28:29], v[46:47]
	v_or_b32_e32 v46, v148, v142
	v_pk_fma_f32 v[28:29], v[24:25], v[166:167], v[28:29] neg_lo:[0,0,1] neg_hi:[0,0,1]
	v_or_b32_e32 v24, v147, v142
	v_lshlrev_b32_e32 v152, 3, v24
	v_lshl_add_u64 v[24:25], s[2:3], 0, v[152:153]
	v_lshlrev_b32_e32 v152, 3, v46
	v_lshl_add_u64 v[46:47], s[2:3], 0, v[152:153]
	s_waitcnt vmcnt(13)
	v_mov_b32_e32 v24, v198
	v_mov_b32_e32 v25, v199
	s_nop 0
	s_waitcnt vmcnt(12)
	v_mov_b32_e32 v46, v200
	v_mov_b32_e32 v47, v201
	s_waitcnt lgkmcnt(0)
	v_mov_b32_e32 v146, v25
	v_mov_b32_e32 v147, v47
	v_pk_mul_f32 v[166:167], v[26:27], v[146:147]
	v_mov_b32_e32 v25, v46
	v_pk_fma_f32 v[46:47], v[30:31], v[24:25], v[166:167]
	v_pk_mul_f32 v[30:31], v[30:31], v[146:147]
	s_nop 0
	v_pk_fma_f32 v[30:31], v[26:27], v[24:25], v[30:31] neg_lo:[0,0,1] neg_hi:[0,0,1]
	v_cvt_f16_f32_e32 v24, v28
	v_cvt_f16_f32_e32 v25, v29
	v_cvt_f16_f32_e32 v26, v30
	v_cvt_f16_f32_e32 v27, v31
	ds_write_b16 v143, v24 offset:256
	ds_write_b16 v143, v25 offset:784
	ds_write_b16 v143, v26 offset:1312
	ds_write_b16 v143, v27 offset:1840
	v_cvt_f16_f32_e32 v24, v38
	v_cvt_f16_f32_e32 v25, v39
	v_cvt_f16_f32_e32 v26, v46
	v_cvt_f16_f32_e32 v27, v47
	ds_write_b16 v143, v24 offset:288
	ds_write_b16 v143, v25 offset:816
	ds_write_b16 v143, v26 offset:1344
	ds_write_b16 v143, v27 offset:1872
	v_or_b32_e32 v24, v149, v142
	v_lshlrev_b32_e32 v152, 3, v24
	v_or_b32_e32 v26, v150, v142
	v_lshl_add_u64 v[24:25], s[2:3], 0, v[152:153]
	v_lshlrev_b32_e32 v152, 3, v26
	v_lshl_add_u64 v[26:27], s[2:3], 0, v[152:153]
	s_waitcnt vmcnt(11)
; #define FOR_R _Pragma("unroll") for (int r = 0; r < 4; ++r)
; #define FOR_AI _Pragma("unroll") for (int ai = 0; ai < 2; ++ai)
; #define FOR_BJ _Pragma("unroll") for (int bj = 0; bj < 2; ++bj)
; #define FOR_M4 _Pragma("unroll") for (int m = 0; m < 4; ++m)
; template <bool ISK>
; __device__ void job_qk_g(const P& p, int l, int g, int ct2, int rt, HALF* sm) {
;     ...
;   FOR_AI FOR_BJ {
;     FOR_M4 {
;       const int row0 = ai * 128 + wr * 64 + m * 16 + fq * 4;
;       const int lc = bj * 128 + wc * 32 + fr;
;       const int j = (bj * 4 + wc) * 16 + fr;
;       f4 o1, o2;
;       FOR_R {
;         const int sp = (rt * 256 + row0 + r) & (S - 1);
;         const float2 cs = rope[sp * 128 + j];
;         const float a = acc[ai][bj][m][0][r], b = acc[ai][bj][m][1][r];
;         o1[r] = a * cs.x - b * cs.y;
;         o2[r] = a * cs.y + b * cs.x;
;       }
;       acc[ai][bj][m][0] = o1;
;       acc[ai][bj][m][1] = o2;
;       stage2_rm(sm, row0, lc, to_h4(o1));
;       stage2_rm(sm, row0, lc + 16, to_h4(o2));
;       __builtin_amdgcn_sched_barrier(0);
;     }
;   }
;   __syncthreads();
;   HALF* dst = (HALF*)(ws + (ISK ? G_K : G_Q));
;   flush2<32>(sm, 256, [&](int row, int ch) { return dst + (size_t)(rt * 256 + row) * 1024 + hh * 256 + ch * 8; });
	v_mov_b32_e32 v146, v202
	v_mov_b32_e32 v147, v203
	s_nop 0
	s_waitcnt vmcnt(10)
	v_mov_b32_e32 v24, v204
	v_mov_b32_e32 v25, v205
	s_waitcnt lgkmcnt(0)
	v_mov_b32_e32 v26, v147
	v_mov_b32_e32 v27, v25
	v_pk_mul_f32 v[148:149], v[16:17], v[26:27]
	v_mov_b32_e32 v147, v24
	v_pk_fma_f32 v[24:25], v[20:21], v[146:147], v[148:149]
	v_pk_mul_f32 v[20:21], v[20:21], v[26:27]
	v_or_b32_e32 v26, v157, v142
	v_pk_fma_f32 v[20:21], v[16:17], v[146:147], v[20:21] neg_lo:[0,0,1] neg_hi:[0,0,1]
	v_or_b32_e32 v16, v151, v142
	v_lshlrev_b32_e32 v152, 3, v16
	v_lshl_add_u64 v[16:17], s[2:3], 0, v[152:153]
	v_lshlrev_b32_e32 v152, 3, v26
	v_lshl_add_u64 v[26:27], s[2:3], 0, v[152:153]
	s_waitcnt vmcnt(9)
	v_mov_b32_e32 v16, v206
	v_mov_b32_e32 v17, v207
	s_nop 0
	s_waitcnt vmcnt(8)
	v_mov_b32_e32 v26, v208
	v_mov_b32_e32 v27, v209
	s_waitcnt lgkmcnt(0)
	v_mov_b32_e32 v146, v17
	v_mov_b32_e32 v147, v27
	v_pk_mul_f32 v[148:149], v[18:19], v[146:147]
	v_mov_b32_e32 v17, v26
	v_pk_fma_f32 v[26:27], v[22:23], v[16:17], v[148:149]
	v_pk_mul_f32 v[22:23], v[22:23], v[146:147]
	s_nop 0
	v_pk_fma_f32 v[22:23], v[18:19], v[16:17], v[22:23] neg_lo:[0,0,1] neg_hi:[0,0,1]
	v_cvt_f16_f32_e32 v16, v20
	v_cvt_f16_f32_e32 v17, v21
	v_cvt_f16_f32_e32 v18, v22
	v_cvt_f16_f32_e32 v19, v23
	ds_write_b16 v143, v16 offset:8704
	ds_write_b16 v143, v17 offset:9232
	ds_write_b16 v143, v18 offset:9760
	ds_write_b16 v143, v19 offset:10288
	v_cvt_f16_f32_e32 v16, v24
	v_cvt_f16_f32_e32 v17, v25
	v_cvt_f16_f32_e32 v18, v26
	v_cvt_f16_f32_e32 v19, v27
	ds_write_b16 v143, v16 offset:8736
	ds_write_b16 v143, v17 offset:9264
	ds_write_b16 v143, v18 offset:9792
	ds_write_b16 v143, v19 offset:10320
	v_or_b32_e32 v16, v158, v142
	v_lshlrev_b32_e32 v152, 3, v16
	v_or_b32_e32 v18, v159, v142
	v_lshl_add_u64 v[16:17], s[2:3], 0, v[152:153]
	v_lshlrev_b32_e32 v152, 3, v18
	v_lshl_add_u64 v[18:19], s[2:3], 0, v[152:153]
	s_waitcnt vmcnt(7)
	v_mov_b32_e32 v146, v210
	v_mov_b32_e32 v147, v211
	s_nop 0
	s_waitcnt vmcnt(6)
	v_mov_b32_e32 v16, v212
	v_mov_b32_e32 v17, v213
	s_waitcnt lgkmcnt(0)
	v_mov_b32_e32 v18, v147
	v_mov_b32_e32 v19, v17
	v_pk_mul_f32 v[148:149], v[8:9], v[18:19]
	v_mov_b32_e32 v147, v16
	v_pk_fma_f32 v[16:17], v[12:13], v[146:147], v[148:149]
	v_pk_mul_f32 v[12:13], v[12:13], v[18:19]
	v_or_b32_e32 v18, v161, v142
	v_pk_fma_f32 v[12:13], v[8:9], v[146:147], v[12:13] neg_lo:[0,0,1] neg_hi:[0,0,1]
	v_or_b32_e32 v8, v160, v142
	v_lshlrev_b32_e32 v152, 3, v8
	v_lshl_add_u64 v[8:9], s[2:3], 0, v[152:153]
	v_lshlrev_b32_e32 v152, 3, v18
	v_lshl_add_u64 v[18:19], s[2:3], 0, v[152:153]
	s_waitcnt vmcnt(5)
	v_mov_b32_e32 v8, v214
	v_mov_b32_e32 v9, v215
	s_nop 0
	s_waitcnt vmcnt(4)
	v_mov_b32_e32 v18, v216
	v_mov_b32_e32 v19, v217
	s_waitcnt lgkmcnt(0)
	v_mov_b32_e32 v146, v9
	v_mov_b32_e32 v147, v19
	v_pk_mul_f32 v[148:149], v[10:11], v[146:147]
	v_mov_b32_e32 v9, v18
	v_pk_fma_f32 v[18:19], v[14:15], v[8:9], v[148:149]
	v_pk_mul_f32 v[14:15], v[14:15], v[146:147]
	s_nop 0
	v_pk_fma_f32 v[10:11], v[10:11], v[8:9], v[14:15] neg_lo:[0,0,1] neg_hi:[0,0,1]
	v_cvt_f16_f32_e32 v8, v12
	v_cvt_f16_f32_e32 v9, v13
	v_cvt_f16_f32_e32 v14, v10
	v_cvt_f16_f32_e32 v15, v11
	ds_write_b16 v143, v8 offset:17152
	ds_write_b16 v143, v9 offset:17680
	ds_write_b16 v143, v14 offset:18208
	ds_write_b16 v143, v15 offset:18736
	v_cvt_f16_f32_e32 v8, v16
	v_cvt_f16_f32_e32 v9, v17
	v_cvt_f16_f32_e32 v14, v18
	v_cvt_f16_f32_e32 v15, v19
	ds_write_b16 v143, v8 offset:17184
	ds_write_b16 v143, v9 offset:17712
	ds_write_b16 v143, v14 offset:18240
	ds_write_b16 v143, v15 offset:18768
	v_or_b32_e32 v8, v144, v142
	v_lshlrev_b32_e32 v152, 3, v8
	v_or_b32_e32 v14, v162, v142
	v_lshl_add_u64 v[8:9], s[2:3], 0, v[152:153]
	v_lshlrev_b32_e32 v152, 3, v14
	v_lshl_add_u64 v[14:15], s[2:3], 0, v[152:153]
	s_waitcnt vmcnt(3)
	v_mov_b32_e32 v144, v218
	v_mov_b32_e32 v145, v219
	s_nop 0
	s_waitcnt vmcnt(2)
	v_mov_b32_e32 v8, v220
	v_mov_b32_e32 v9, v221
	s_waitcnt lgkmcnt(0)
	v_mov_b32_e32 v14, v145
	v_mov_b32_e32 v15, v9
	v_pk_mul_f32 v[146:147], v[0:1], v[14:15]
	v_mov_b32_e32 v145, v8
	v_pk_fma_f32 v[8:9], v[4:5], v[144:145], v[146:147]
	v_pk_mul_f32 v[4:5], v[4:5], v[14:15]
	v_or_b32_e32 v14, v164, v142
	v_pk_fma_f32 v[0:1], v[0:1], v[144:145], v[4:5] neg_lo:[0,0,1] neg_hi:[0,0,1]
	v_or_b32_e32 v4, v163, v142
	v_lshlrev_b32_e32 v152, 3, v4
	v_lshl_add_u64 v[4:5], s[2:3], 0, v[152:153]
	v_lshlrev_b32_e32 v152, 3, v14
	v_lshl_add_u64 v[14:15], s[2:3], 0, v[152:153]
	s_waitcnt vmcnt(1)
	v_mov_b32_e32 v144, v222
	v_mov_b32_e32 v145, v223
	s_nop 0
	s_waitcnt vmcnt(0)
	v_mov_b32_e32 v4, v224
	v_mov_b32_e32 v5, v225
	s_waitcnt lgkmcnt(0)
	v_mov_b32_e32 v14, v145
	v_mov_b32_e32 v15, v5
	v_pk_mul_f32 v[146:147], v[2:3], v[14:15]
	v_mov_b32_e32 v145, v4
	v_pk_fma_f32 v[4:5], v[6:7], v[144:145], v[146:147]
	v_pk_mul_f32 v[6:7], v[6:7], v[14:15]
	s_nop 0
	v_pk_fma_f32 v[2:3], v[2:3], v[144:145], v[6:7] neg_lo:[0,0,1] neg_hi:[0,0,1]
	v_cvt_f16_f32_e32 v6, v0
	v_cvt_f16_f32_e32 v7, v1
	v_cvt_f16_f32_e32 v14, v2
	v_cvt_f16_f32_e32 v15, v3
	ds_write_b16 v143, v6 offset:25600
	ds_write_b16 v143, v7 offset:26128
	ds_write_b16 v143, v14 offset:26656
	ds_write_b16 v143, v15 offset:27184
	v_cvt_f16_f32_e32 v6, v8
	v_cvt_f16_f32_e32 v7, v9
	v_cvt_f16_f32_e32 v14, v4
	v_cvt_f16_f32_e32 v15, v5
	ds_write_b16 v143, v6 offset:25632
	ds_write_b16 v143, v7 offset:26160
	ds_write_b16 v143, v14 offset:26688
	ds_write_b16 v143, v15 offset:27216
	v_mov_b32_e32 v7, v155
	s_movk_i32 s2, 0x1fff
	s_waitcnt lgkmcnt(0)
	s_barrier
	s_nop 0
	v_cmp_lt_i32_e32 vcc, s2, v7
	s_and_saveexec_b64 s[2:3], vcc
	s_xor_b64 s[2:3], exec, s[2:3]
	s_lshl_b32 s6, s44, 8
	s_or_saveexec_b64 s[2:3], s[2:3]
	v_mov_b32_e32 v6, s6
	s_xor_b64 exec, exec, s[2:3]
	s_cbranch_execz .LBB0_223
	s_lshl_b32 s6, s44, 9
	v_max_i32_e32 v6, 0x1e00, v7
	s_add_u32 s6, s0, s6
	v_sub_u32_e32 v6, v6, v7
	s_addc_u32 s7, s1, 0
	v_add_u32_e32 v6, 0x1ff, v6
	s_add_u32 s6, s6, 0x1aeb0000
	v_and_b32_e32 v14, 0x600, v6
	s_movk_i32 s12, 0x600
	s_addc_u32 s7, s7, 0
	v_cmp_ne_u32_e32 vcc, s12, v14
	s_and_saveexec_b64 s[12:13], vcc
	s_cbranch_execz .LBB0_219
	v_lshrrev_b32_e32 v14, 9, v6
	v_add_u32_e32 v14, 1, v14
	v_and_b32_e32 v141, 3, v14
	v_lshl_add_u32 v14, v7, 4, 0
	v_lshlrev_b32_e32 v15, 3, v7
	v_sub_u32_e32 v141, 0, v141
	s_mov_b64 s[14:15], 0

; DEV int opaque_tid() { int t = threadIdx.x & 255; asm volatile("" : "+v"(t)); return t; }
; DEV char* opaque_ptr(char* q) { asm volatile("" : "+s"(q)); return q; }
; template <class AF, class BF>
; DEV void kloop(f4 (&acc)[4][4], AF arow, BF brow, int K, HALF* sm) {
;   const int tid = opaque_tid(), lane = tid & 63, wid = tid >> 6;
;   const int wr = wid >> 1, wc = wid & 1, fr = lane & 15, fq = lane >> 4;
;   const int lrow = tid >> 3, lch = tid & 7;
;   const int gch = (lch ^ ((lrow >> 1) & 7)) * 8;
;   const HALF* pa[4];
;   const HALF* pb[4];
; #pragma unroll
;   for (int i = 0; i < 4; ++i) {
;     pa[i] = arow(lrow + 32 * i) + gch;
;     pb[i] = brow(lrow + 32 * i) + gch;
;   }
;   HALF* As = sm;
;   HALF* Bs = sm + 16384;
;   const int woff = tid * 8;
;   const int nk = K >> 6;
;   const int aoff = (wr * 64 + fr) * 64, boff = (wc * 64 + fr) * 64;
;   const int sw0 = ((fq) ^ (fr >> 1)) * 8, sw1 = ((4 + fq) ^ (fr >> 1)) * 8;
;   __syncthreads();
; #pragma unroll
;   for (int i = 0; i < 4; ++i) {
;     __builtin_amdgcn_global_load_lds((const unsigned*)(pa[i]), (unsigned*)(As + woff + i * 2048), 16, 0, 0);
;     __builtin_amdgcn_global_load_lds((const unsigned*)(pb[i]), (unsigned*)(Bs + woff + i * 2048), 16, 0, 0);
;   }
; __device__ void job_fft2(const P& p, int g, int tile, HALF* sm) {
;   TILE_IDS
;   char* ws = opaque_ptr(p.ws);
;   const int sh = (g < 2) ? 12 : 13;
;   const int N2 = 1 << (sh - 6);
;   const int nseq = (g < 2) ? 2 : 1;
;   const int c0 = (tile & 7) * 128, t1 = (tile >> 3) & 63, seq = tile >> 9;
;   const HALF* GP = (const HALF*)(ws + G_GP);
;   const HALF* D2 = (const HALF*)(ws + ((g < 2) ? OFF_D2TA : OFF_D2TB)) + (size_t)t1 * 128 * (2 * N2);
;   const int K = 2 * N2;
;   f4 acc[4][4];
;   zero_acc(acc);
;   kloop(acc, [&](int r) { return GP + ((size_t)(((c0 + r) * nseq + seq) * 64 + t1)) * K; },
;         [&](int n) { return D2 + (size_t)n * K; }, K, sm);
.LBB0_498:
	s_lshl_b32 s0, s12, 1
	v_readlane_b32 s1, v255, 2
	s_add_i32 s2, s0, s1
	v_mov_b32_e32 v65, v182
	s_mov_b64 s[0:1], s[20:21]
	v_mov_b32_e32 v10, v182
	s_lshl_b32 s3, s2, 7
	s_and_b32 s3, s3, 0x80
	s_lshl_b32 s4, s2, 4
	s_and_b32 s4, s4, 0x300
	s_or_b32 s4, s4, s3
	v_lshrrev_b32_e32 v11, 4, v10
	s_bfe_u32 s5, s2, 0x30001
	s_bfe_u32 s3, s2, 0x30006
	s_lshl_b32 s3, s3, 3
	s_or_b32 s5, s5, s3
	s_ashr_i32 s13, s2, 9
	v_xor_b32_e32 v1, v11, v10
	s_add_u32 s14, s0, s8
	v_ashrrev_i32_e32 v0, 3, v10
	v_lshlrev_b32_e32 v1, 4, v1
	s_addc_u32 s15, s1, 0
	s_lshl_b32 s44, s5, 7
	v_and_b32_e32 v152, 0x70, v1
	v_add_u32_e32 v1, s4, v0
	s_lshl_b64 s[2:3], s[44:45], s9
	v_lshlrev_b32_e32 v1, v185, v1
	s_lshl_b64 s[2:3], s[2:3], 1
	v_add_u32_e32 v1, s13, v1
	s_add_u32 s2, s14, s2
	v_lshl_or_b32 v6, v1, 6, s5
	s_addc_u32 s3, s15, s3
	v_lshl_add_u64 v[2:3], s[0:1], 0, v[152:153]
	s_mov_b64 s[14:15], 0x27eb0000
	v_ashrrev_i32_e32 v7, 31, v6
	v_lshl_add_u64 v[2:3], v[2:3], 0, s[14:15]
	v_lshlrev_b64 v[6:7], s9, v[6:7]
	v_ashrrev_i32_e32 v1, 31, v0
	v_lshl_add_u64 v[4:5], s[2:3], 0, v[152:153]
	v_lshl_add_u64 v[68:69], v[6:7], 1, v[2:3]
	v_lshlrev_b64 v[6:7], s9, v[0:1]
	v_lshl_add_u64 v[70:71], v[6:7], 1, v[4:5]
	v_add_u32_e32 v6, 32, v0
	v_add_u32_e32 v1, s4, v6
	v_ashrrev_i32_e32 v7, 31, v6
	v_lshlrev_b32_e32 v1, v185, v1
	v_lshlrev_b64 v[6:7], s9, v[6:7]
	v_add_u32_e32 v1, s13, v1
	v_lshl_add_u64 v[74:75], v[6:7], 1, v[4:5]
	v_add_u32_e32 v6, 64, v0
	v_lshl_or_b32 v8, v1, 6, s5
	v_add_u32_e32 v1, s4, v6
	v_ashrrev_i32_e32 v9, 31, v8
	v_lshlrev_b32_e32 v1, v185, v1
	v_lshlrev_b64 v[8:9], s9, v[8:9]
	v_add_u32_e32 v1, s13, v1
	v_add_u32_e32 v0, 0x60, v0
	v_lshl_add_u64 v[72:73], v[8:9], 1, v[2:3]
	v_lshl_or_b32 v8, v1, 6, s5
	v_add_u32_e32 v1, s4, v0
	v_ashrrev_i32_e32 v7, 31, v6
	v_lshlrev_b32_e32 v1, v185, v1
	v_lshlrev_b64 v[6:7], s9, v[6:7]
	v_add_u32_e32 v1, s13, v1
	v_lshl_add_u64 v[78:79], v[6:7], 1, v[4:5]
	v_lshl_or_b32 v6, v1, 6, s5
	v_ashrrev_i32_e32 v1, 31, v0
	v_readlane_b32 s3, v255, 34
	v_lshlrev_b64 v[0:1], s9, v[0:1]
	v_lshl_add_u64 v[82:83], v[0:1], 1, v[4:5]
	v_lshl_add_u32 v84, v10, 4, s3
	v_add_u32_e32 v0, 0x8000, v84
	v_readfirstlane_b32 s2, v84
	s_mov_b32 m0, s2
	v_readfirstlane_b32 s2, v0
	v_add_u32_e32 v0, 0x1000, v84
	s_waitcnt lgkmcnt(0)
	s_barrier
	global_load_lds_dwordx4 v[68:69], off
	s_mov_b32 m0, s2
	v_readfirstlane_b32 s2, v0
	v_add_u32_e32 v0, 0x9000, v84
	v_ashrrev_i32_e32 v9, 31, v8
	global_load_lds_dwordx4 v[70:71], off
	s_mov_b32 m0, s2
	v_readfirstlane_b32 s2, v0
	v_add_u32_e32 v0, 0x2000, v84
	v_lshlrev_b64 v[8:9], s9, v[8:9]
	global_load_lds_dwordx4 v[72:73], off
	s_mov_b32 m0, s2
	v_readfirstlane_b32 s2, v0
	v_add_u32_e32 v0, 0xa000, v84
	v_lshl_add_u64 v[76:77], v[8:9], 1, v[2:3]
	v_ashrrev_i32_e32 v7, 31, v6
	global_load_lds_dwordx4 v[74:75], off
	s_mov_b32 m0, s2
	v_readfirstlane_b32 s2, v0
	v_add_u32_e32 v0, 0x3000, v84
	v_lshlrev_b64 v[6:7], s9, v[6:7]
	global_load_lds_dwordx4 v[76:77], off
	s_mov_b32 m0, s2
	v_readfirstlane_b32 s2, v0
	v_add_u32_e32 v0, 0xb000, v84
	v_lshl_add_u64 v[80:81], v[6:7], 1, v[2:3]
	global_load_lds_dwordx4 v[78:79], off
	s_mov_b32 m0, s2
	v_readfirstlane_b32 s2, v0
	global_load_lds_dwordx4 v[80:81], off
	s_mov_b32 m0, s2
	v_and_b32_e32 v1, 15, v10
	global_load_lds_dwordx4 v[82:83], off
	v_lshrrev_b32_e32 v3, 1, v10
	s_mov_b32 s2, 0x1ffffc0
	v_bfe_u32 v0, v10, 4, 2
	v_bfe_u32 v2, v10, 1, 3
	v_and_or_b32 v1, v3, s2, v1
	v_bitop3_b32 v0, v0, v2, 4 bitop3:0x36
	v_bitop3_b32 v2, v11, v2, 3 bitop3:0x6c
	v_lshl_add_u32 v85, v1, 7, s3
	v_lshlrev_b32_e32 v1, 7, v10
	v_lshlrev_b32_e32 v0, 3, v0
	v_lshlrev_b32_e32 v2, 3, v2
	v_and_b32_e32 v1, 0x2780, v1
	v_mov_b32_e32 v16, 0
	s_mov_b32 s44, 64
	v_add_u32_e32 v86, s3, v1
	s_mov_b32 s16, 0
	v_lshlrev_b32_e32 v87, 1, v2
	v_lshlrev_b32_e32 v88, 1, v0
	s_mov_b32 s14, 0
	v_mov_b32_e32 v17, v16
	v_mov_b32_e32 v18, v16
	v_mov_b32_e32 v19, v16
	v_mov_b32_e32 v0, v16
	v_mov_b32_e32 v1, v16
	v_mov_b32_e32 v2, v16
	v_mov_b32_e32 v3, v16
	v_mov_b32_e32 v4, v16
	v_mov_b32_e32 v5, v16
	v_mov_b32_e32 v6, v16
	v_mov_b32_e32 v7, v16
	v_mov_b32_e32 v8, v16
	v_mov_b32_e32 v9, v16
	v_mov_b32_e32 v10, v16
	v_mov_b32_e32 v11, v16
	v_mov_b32_e32 v12, v16
	v_mov_b32_e32 v13, v16
	v_mov_b32_e32 v14, v16
	v_mov_b32_e32 v15, v16
	v_mov_b32_e32 v20, v16
	v_mov_b32_e32 v21, v16
	v_mov_b32_e32 v22, v16
	v_mov_b32_e32 v23, v16
	v_mov_b32_e32 v24, v16
	v_mov_b32_e32 v25, v16
	v_mov_b32_e32 v26, v16
	v_mov_b32_e32 v27, v16
	v_mov_b32_e32 v28, v16
	v_mov_b32_e32 v29, v16
	v_mov_b32_e32 v30, v16
	v_mov_b32_e32 v31, v16
	v_mov_b32_e32 v32, v16
	v_mov_b32_e32 v33, v16
	v_mov_b32_e32 v34, v16
	v_mov_b32_e32 v35, v16
	v_mov_b32_e32 v36, v16
	v_mov_b32_e32 v37, v16
	v_mov_b32_e32 v38, v16
	v_mov_b32_e32 v39, v16
	v_mov_b32_e32 v40, v16
	v_mov_b32_e32 v41, v16
	v_mov_b32_e32 v42, v16
	v_mov_b32_e32 v43, v16
	v_mov_b32_e32 v44, v16
	v_mov_b32_e32 v45, v16
	v_mov_b32_e32 v46, v16
	v_mov_b32_e32 v47, v16
	v_mov_b32_e32 v48, v16
	v_mov_b32_e32 v49, v16
	v_mov_b32_e32 v50, v16
	v_mov_b32_e32 v51, v16
	v_mov_b32_e32 v52, v16
	v_mov_b32_e32 v53, v16
	v_mov_b32_e32 v54, v16
	v_mov_b32_e32 v55, v16
	v_mov_b32_e32 v56, v16
	v_mov_b32_e32 v57, v16
	v_mov_b32_e32 v58, v16
	v_mov_b32_e32 v59, v16
	v_mov_b32_e32 v60, v16
	v_mov_b32_e32 v61, v16
	v_mov_b32_e32 v62, v16
	v_mov_b32_e32 v63, v16
	s_branch .LBB0_500
